# rescale flag (s_cmp_lg_u64+s_cselect) taken off the v_cmp->branch chain at 19 attention row-max sites: common path s_mov 0 after the branch, rare path s_mov -1
# baseline (speedup 1.0000x reference)
; #define WAIT_BAR(N) asm volatile("s_waitcnt vmcnt(" #N ") lgkmcnt(0)\n\ts_barrier":::"memory")
;   #define DMA_K(t,slot) glds16(ksrc+(long)(t)*KVBLK*PQ,(unsigned)__builtin_amdgcn_readfirstlane(kdst+(slot)))
;   #define DMA_V(t,slot) glds16(vsrc+(long)(t)*KVBLK*PQ,(unsigned)__builtin_amdgcn_readfirstlane(vdst+(slot)))
;   #define CMASK(P0,P1,t) do{}while(0)
;   #define START(P0,P1) do{ const float rm=rowmax(P0,P1); resc=false; \
;     { const float dl=rm; mhat=fadd_s(mhat,dl); \
;       _Pragma("unroll") for(int r=0;r<16;++r){P0[r]=fsub_s(P0[r],dl);P1[r]=fsub_s(P1[r],dl);} \
;       _Pragma("unroll") for(int r=0;r<16;++r)negm[r]=-mhat; asm volatile("":"+v"(negm)); } \
;     _Pragma("unroll") for(int r=0;r<16;++r)P0[r]=__builtin_amdgcn_exp2f(P0[r]); }while(0)
;   #define CMASK(P0,P1,t) do{}while(0)
; template<int THRL,int MODE> __device__ __forceinline__ void attn_unit128(const bf16*Qblk,const bf16*__restrict__ Kh,const bf16*__restrict__ Vh,bf16*Oblk,const int NT,char*shm,const bf16*O1blk,bf16*AOblk,const float lam,const float*sln,const float omli){
;   int tid_=threadIdx.x; asm volatile("":"+v"(tid_));
;   const int tid=tid_,lane=tid&63,r32=lane&31,hi=lane>>5; const int wid=__builtin_amdgcn_readfirstlane(tid>>6);
;   const bf16*Qw=Qblk+(long)wid*QBLK*PQ;
;   const unsigned lds0=(unsigned)(uintptr_t)shm;
;   float*wsf=(float*)(shm+LDS_WS8)+wid*64;
;   const unsigned koff=(unsigned)(lane*PQ+wid*8)*2u;
;   const unsigned voff=(unsigned)((16*(wid&3)+(lane>>2))*PQ+(wid>>2)*32+(lane&3)*8)*2u;
;   const unsigned kdst=lds0+LDS_K+wid*1024, vdst=lds0+LDS_V+wid*1024;
;     ...
;   const char*Kbase=shm+LDS_K; bf16x8 kf[8];
;   const lds_cptr shm3=(lds_cptr)shm; const lds_cptr kp0=shm3+LDS_K+hi*1024+r32*16; const lds_cptr vp0=shm3+LDS_V+((lane>>4)&1)*32+(lane&3)*8+(4*hi+((lane&15)>>2))*64;
;   DMA_K(0,0);DMA_V(0,0);DMA_K(1,SLOTB);
;   bf16x8 qr[4];
;   #pragma unroll
;   for(int d0=0;d0<4;++d0)qr[d0]=*reinterpret_cast<const bf16x8*>(&Qw[(long)r32*PQ+d0*16+hi*8]);
;   float mhat=0.f,l_reg=0.f;f32x16 o[4];o[0]=f32x16{};o[1]=f32x16{};o[2]=f32x16{};o[3]=f32x16{};f32x16 negm=f32x16{};asm volatile("":"+v"(negm));
;     ...
;   bool resc=false;
;     ...
;   f32x16 pA0,pA1,pB0,pB1;
;   int sl_prev=0,sl_cur=0,sl_next=SLOTB;
;     ...
;   DMA_K(2,2*SLOTB);
;   WAIT_BAR(4);
;   qkt(pA0,pA1,Kbase,qr,negm,r32,hi);asm volatile("s_nop 15\n\ts_nop 7":"+v"(pA0),"+v"(pA1));CMASK(pA0,pA1,0);
;   START(pA0,pA1);
.LBB0_514:
	s_andn2_b64 vcc, exec, s[0:1]
	s_mov_b64 s[0:1], -1
	s_cbranch_vccnz .LBB0_505
	s_cmpk_gt_i32 s35, 0x1ff
	s_cbranch_scc0 .LBB0_539
	s_add_i32 s0, s35, 0xfffffe00
	s_lshr_b32 s28, s0, 2
	s_and_b32 s36, s35, 3
	s_mul_i32 s1, s28, 0x4920000
	s_mul_hi_u32 s0, s28, 0x4920000
	s_add_u32 s6, s58, s1
	s_addc_u32 s7, s59, s0
	s_lshl_b32 s42, s36, 7
	s_lshl_b32 s0, s36, 8
	s_add_u32 s0, s6, s0
	s_addc_u32 s1, s7, 0
	s_add_u32 s4, s0, 0x800
	s_addc_u32 s5, s1, 0
	v_mov_b32_e32 v44, v220
	s_add_u32 s6, s6, s42
	s_addc_u32 s7, s7, 0
	v_readfirstlane_b32 s8, v44
	s_ashr_i32 s33, s8, 6
	s_mul_i32 s10, s33, 0x24000
	s_mul_hi_i32 s9, s33, 0x24000
	s_add_u32 s16, s6, s10
	s_addc_u32 s17, s7, s9
	s_and_b32 s10, s8, 0x3fffffc0
	s_ashr_i32 s8, s8, 3
	s_lshl_b32 s9, s33, 4
	v_bfe_u32 v2, v44, 2, 4
	s_and_b32 s8, s8, 0x7fffffe0
	v_and_or_b32 v2, s9, 48, v2
	v_mov_b32_e32 v3, s8
	s_movk_i32 s8, 0x900
	v_mad_u32_u24 v2, v2, s8, v3
	v_lshlrev_b32_e32 v215, 3, v44
	s_lshl_b32 s8, s33, 10
	v_and_b32_e32 v212, 63, v44
	v_mov_b32_e32 v0, s9
	v_and_b32_e32 v45, 24, v215
	s_cmp_lg_u32 0, -1
	v_mad_u32_u24 v0, v212, s81, v0
	v_or_b32_e32 v2, v2, v45
	s_cselect_b32 s9, 0, 0
	v_lshlrev_b32_e32 v4, 1, v2
	s_add_i32 s22, s9, s8
	v_lshl_add_u64 v[34:35], s[6:7], 0, v[0:1]
	s_mov_b64 s[8:9], 0x400
	v_lshl_add_u64 v[2:3], v[34:35], 0, s[8:9]
	s_mov_b32 s8, m0
	s_mov_b32 m0, s22
	s_nop 0
	global_load_lds_dwordx4 v[2:3], off
	s_mov_b32 m0, s8
	v_mov_b32_e32 v0, v4
	s_add_i32 s26, s22, 0x6000
	v_lshl_add_u64 v[2:3], s[4:5], 0, v[0:1]
	s_mov_b32 s8, m0
	s_mov_b32 m0, s26
	s_nop 0
	global_load_lds_dwordx4 v[2:3], off
	s_mov_b32 m0, s8
	s_add_u32 s8, s0, 0x880
	s_addc_u32 s9, s1, 0
	v_lshl_add_u64 v[2:3], s[8:9], 0, v[0:1]
	s_add_i32 s11, s22, 0x8000
	s_mov_b32 s18, m0
	s_mov_b32 m0, s11
	s_nop 0
	global_load_lds_dwordx4 v[2:3], off
	s_mov_b32 m0, s18
	s_mov_b64 s[18:19], 0x48400
	v_and_b32_e32 v213, 31, v44
	v_lshl_add_u64 v[2:3], v[34:35], 0, s[18:19]
	s_add_i32 s11, s22, 0x2000
	s_mov_b32 s18, m0
	s_mov_b32 m0, s11
	s_nop 0
	global_load_lds_dwordx4 v[2:3], off
	s_mov_b32 m0, s18
	v_mul_u32_u24_e32 v2, 0x900, v213
	v_bfe_u32 v214, v44, 5, 1
	v_lshlrev_b32_e32 v2, 1, v2
	v_lshl_or_b32 v10, v214, 4, v2
	global_load_dwordx4 v[174:177], v10, s[16:17]
	global_load_dwordx4 v[170:173], v10, s[16:17] offset:32
	global_load_dwordx4 v[166:169], v10, s[16:17] offset:64
	global_load_dwordx4 v[162:165], v10, s[16:17] offset:96
	v_mov_b32_e32 v2, v1
	v_mov_b32_e32 v3, v1
	v_mov_b32_e32 v4, v1
	v_mov_b32_e32 v5, v1
	v_mov_b32_e32 v6, v1
	v_mov_b32_e32 v7, v1
	v_mov_b32_e32 v8, v1
	v_mov_b32_e32 v9, v1
	v_mov_b32_e32 v10, v1
	v_mov_b32_e32 v11, v1
	v_mov_b32_e32 v12, v1
	v_mov_b32_e32 v13, v1
	v_mov_b32_e32 v14, v1
	v_mov_b32_e32 v15, v1
	v_mov_b32_e32 v16, v1
	v_mov_b32_e32 v17, v1
	v_lshlrev_b32_e32 v18, 4, v213
	v_lshl_add_u32 v19, v214, 10, 0
	s_mov_b64 s[16:17], 0x90400
	v_add_u32_e32 v235, v19, v18
	v_lshl_add_u64 v[18:19], v[34:35], 0, s[16:17]
	s_add_i32 s11, s22, 0x4000
	s_mov_b32 s16, m0
	s_mov_b32 m0, s11
	s_nop 0
	global_load_lds_dwordx4 v[18:19], off
	s_mov_b32 m0, s16
	s_waitcnt vmcnt(4) lgkmcnt(0)
	s_barrier
	ds_read_b128 v[36:39], v235
	ds_read_b128 v[40:43], v235 offset:512
	s_lshl_b32 s10, s10, 2
	s_add_i32 s24, s10, 0
	s_mov_b64 s[10:11], 0xd8400
	s_add_i32 s24, s24, 0x12000
	v_cmp_gt_u32_e64 s[40:41], 32, v212
	v_lshl_add_u32 v216, v213, 2, s24
	s_waitcnt vmcnt(3) lgkmcnt(1)
	v_mfma_f32_32x32x16_bf16 v[18:33], v[36:39], v[174:177], v[2:17]
	s_waitcnt lgkmcnt(0)
	v_mfma_f32_32x32x16_bf16 v[2:17], v[40:43], v[174:177], v[2:17]
	ds_read_b128 v[36:39], v235 offset:2048
	ds_read_b128 v[40:43], v235 offset:2560
	s_waitcnt vmcnt(2) lgkmcnt(1)
	v_mfma_f32_32x32x16_bf16 v[18:33], v[36:39], v[170:173], v[18:33]
	s_waitcnt lgkmcnt(0)
	v_mfma_f32_32x32x16_bf16 v[2:17], v[40:43], v[170:173], v[2:17]
	ds_read_b128 v[36:39], v235 offset:4096
	ds_read_b128 v[40:43], v235 offset:4608
	s_waitcnt vmcnt(1) lgkmcnt(1)
	v_mfma_f32_32x32x16_bf16 v[18:33], v[36:39], v[166:169], v[18:33]
	s_waitcnt lgkmcnt(0)
	v_mfma_f32_32x32x16_bf16 v[2:17], v[40:43], v[166:169], v[2:17]
	ds_read_b128 v[36:39], v235 offset:6144
	ds_read_b128 v[40:43], v235 offset:6656
	s_waitcnt vmcnt(0) lgkmcnt(1)
	v_mfma_f32_32x32x16_bf16 v[18:33], v[36:39], v[162:165], v[18:33]
	v_lshlrev_b32_e32 v36, 1, v44
	v_and_b32_e32 v36, 32, v36
	v_lshlrev_b32_e32 v37, 4, v44
	v_add3_u32 v36, 0, v36, v45
	v_lshlrev_b32_e32 v38, 8, v214
	v_and_b32_e32 v37, 0xc0, v37
	v_add3_u32 v233, v36, v38, v37
	s_waitcnt lgkmcnt(0)
	v_mfma_f32_32x32x16_bf16 v[2:17], v[40:43], v[162:165], v[2:17]
	s_nop 15
	s_nop 7
	s_nop 0
	v_max3_f32 v39, v18, v19, v2
	v_max3_f32 v40, v20, v21, v3
	s_nop 0
	v_max3_f32 v39, v39, v4, v5
	v_max3_f32 v40, v40, v24, v25
	s_nop 0
	v_max3_f32 v39, v39, v22, v23
	v_max3_f32 v40, v40, v8, v9
	s_nop 0
	v_max3_f32 v39, v39, v6, v7
	v_max3_f32 v40, v40, v28, v29
	s_nop 0
	v_max3_f32 v39, v39, v26, v27
	v_max3_f32 v40, v40, v12, v13
	s_nop 0
	v_max3_f32 v39, v39, v10, v11
	v_max3_f32 v40, v40, v32, v33
	s_nop 0
	v_max3_f32 v39, v39, v30, v31
	v_max3_f32 v40, v40, v16, v17
	s_nop 0
	v_max3_f32 v39, v39, v14, v15
	s_nop 0
	v_max_f32_e32 v39, v39, v40
	s_nop 0
	v_mov_b32_e32 v40, v39
	s_nop 1
	v_permlane32_swap_b32_e32 v39, v40
	v_max_f32_e32 v39, v39, v40
	s_nop 0
	v_add_f32_e32 v234, v1, v39
	v_sub_f32_e32 v40, v2, v39
	v_sub_f32_e32 v18, v18, v39
	v_sub_f32_e32 v19, v19, v39
	v_sub_f32_e32 v41, v3, v39
	v_sub_f32_e32 v20, v20, v39
	s_nop 0
	v_xor_b32_e32 v2, 0x80000000, v234
	v_sub_f32_e32 v42, v4, v39
	v_sub_f32_e32 v21, v21, v39
	v_sub_f32_e32 v43, v5, v39
	v_sub_f32_e32 v22, v22, v39
	v_sub_f32_e32 v44, v6, v39
	v_sub_f32_e32 v23, v23, v39
	v_sub_f32_e32 v45, v7, v39
	v_sub_f32_e32 v24, v24, v39
	v_sub_f32_e32 v46, v8, v39
	v_sub_f32_e32 v25, v25, v39
	v_sub_f32_e32 v47, v9, v39
	v_sub_f32_e32 v26, v26, v39
	v_sub_f32_e32 v48, v10, v39
	v_sub_f32_e32 v27, v27, v39
	v_sub_f32_e32 v49, v11, v39
	v_sub_f32_e32 v28, v28, v39
	v_sub_f32_e32 v50, v12, v39
	v_sub_f32_e32 v29, v29, v39
	v_sub_f32_e32 v51, v13, v39
	v_sub_f32_e32 v30, v30, v39
	v_sub_f32_e32 v52, v14, v39
	v_sub_f32_e32 v31, v31, v39
	v_sub_f32_e32 v53, v15, v39
	v_sub_f32_e32 v32, v32, v39
	v_sub_f32_e32 v54, v16, v39
	v_sub_f32_e32 v33, v33, v39
	v_sub_f32_e32 v39, v17, v39
	v_mov_b32_e32 v3, v2
	v_mov_b32_e32 v4, v2
	v_mov_b32_e32 v5, v2
	v_mov_b32_e32 v6, v2
	v_mov_b32_e32 v7, v2
	v_mov_b32_e32 v8, v2
	v_mov_b32_e32 v9, v2
	v_mov_b32_e32 v10, v2
	v_mov_b32_e32 v11, v2
	v_mov_b32_e32 v12, v2
	v_mov_b32_e32 v13, v2
	v_mov_b32_e32 v14, v2
	v_mov_b32_e32 v15, v2
	v_mov_b32_e32 v16, v2
	v_mov_b32_e32 v17, v2
	s_waitcnt vmcnt(0) lgkmcnt(0)
	s_barrier
; #define WAIT_BAR(N) asm volatile("s_waitcnt vmcnt(" #N ") lgkmcnt(0)\n\ts_barrier":::"memory")
;   #define DMA_K(t,slot) glds16(ksrc+(long)(t)*KVBLK*PQ,(unsigned)__builtin_amdgcn_readfirstlane(kdst+(slot)))
;   #define DMA_V(t,slot) glds16(vsrc+(long)(t)*KVBLK*PQ,(unsigned)__builtin_amdgcn_readfirstlane(vdst+(slot)))
;   #define ROT() do{sl_prev=sl_cur;sl_cur=sl_next;sl_next=(sl_next==(NSLOT-1)*SLOTB)?0:sl_next+SLOTB;}while(0)
;   #define DMA_K(t,slot) glds16((const char*)Kh+(size_t)(t)*(KVBLK*PQ*2)+koff,(unsigned)__builtin_amdgcn_readfirstlane(kdst+(slot)))
;   #define DMA_V(t,slot) do{ glds16((const char*)Vh+(size_t)(t)*(KVBLK*PQ*2)+voff,(unsigned)__builtin_amdgcn_readfirstlane(vdst+2*(slot))); glds16((const char*)Vh+(size_t)(t)*(KVBLK*PQ*2)+128+voff,(unsigned)__builtin_amdgcn_readfirstlane(vdst+2*(slot)+8192)); }while(0)
;   #define ROT() do{sl_prev=sl_cur;sl_cur=sl_next;sl_next=(sl_next==(NSLOT-1)*SLOTB)?0:sl_next+SLOTB;}while(0)
; template<int THRL,int MODE> __device__ __forceinline__ void attn_unit128(const bf16*Qblk,const bf16*__restrict__ Kh,const bf16*__restrict__ Vh,bf16*Oblk,const int NT,char*shm,const bf16*O1blk,bf16*AOblk,const float lam,const float*sln,const float omli){
;     ...
;   _Pragma("unroll") for(int r=0;r<16;++r)pA1[r]=__builtin_amdgcn_exp2f(pA1[r]);
;   WAIT_BAR(0);
;   DMA_K(3,0);DMA_V(1,SLOTB);
;   ROT();
;   kload8(kf,kp0+sl_cur);
;   WAIT_BAR(3);
;   s16x4 vlo[8],vhi[8]; u32x4 pw0,pw1,pw2,pw3;
	v_exp_f32_e32 v55, v18
	v_exp_f32_e32 v56, v19
	v_lshl_add_u64 v[18:19], v[34:35], 0, s[10:11]
	s_mov_b32 s10, m0
	s_mov_b32 m0, s22
	s_nop 0
	global_load_lds_dwordx4 v[18:19], off
	s_mov_b32 m0, s10
	s_add_u32 s10, s0, 0x48800
	s_addc_u32 s11, s1, 0
	s_add_i32 s16, s22, 0xa000
	v_lshl_add_u64 v[18:19], s[10:11], 0, v[0:1]
	s_mov_b32 s17, m0
	s_mov_b32 m0, s16
	s_nop 0
	global_load_lds_dwordx4 v[18:19], off
	s_mov_b32 m0, s17
	s_add_u32 s16, s0, 0x48880
	s_addc_u32 s17, s1, 0
	v_lshl_add_u64 v[18:19], s[16:17], 0, v[0:1]
	s_add_i32 s18, s22, 0xc000
	s_mov_b32 s19, m0
	s_mov_b32 m0, s18
	s_nop 0
	global_load_lds_dwordx4 v[18:19], off
	s_mov_b32 m0, s19
	v_exp_f32_e32 v57, v20
	v_exp_f32_e32 v58, v21
	v_exp_f32_e32 v59, v22
	v_exp_f32_e32 v60, v23
	v_exp_f32_e32 v61, v24
	v_exp_f32_e32 v62, v25
	v_exp_f32_e32 v63, v26
	v_exp_f32_e32 v64, v27
	v_exp_f32_e32 v65, v28
	v_exp_f32_e32 v66, v29
	v_exp_f32_e32 v67, v30
	v_exp_f32_e32 v68, v31
	v_exp_f32_e32 v69, v32
	v_exp_f32_e32 v70, v33
	v_exp_f32_e32 v71, v40
	v_exp_f32_e32 v72, v41
	v_exp_f32_e32 v73, v42
	v_exp_f32_e32 v74, v43
	v_exp_f32_e32 v75, v44
	v_exp_f32_e32 v76, v45
	v_exp_f32_e32 v77, v46
	v_exp_f32_e32 v78, v47
	v_exp_f32_e32 v79, v48
	v_exp_f32_e32 v80, v49
	v_exp_f32_e32 v81, v39
	ds_read_b128 v[18:21], v235 offset:8192
	ds_read_b128 v[22:25], v235 offset:8704
	ds_read_b128 v[26:29], v235 offset:10240
	ds_read_b128 v[30:33], v235 offset:10752
	ds_read_b128 v[34:37], v235 offset:12288
	ds_read_b128 v[38:41], v235 offset:12800
	ds_read_b128 v[42:45], v235 offset:14336
	ds_read_b128 v[46:49], v235 offset:14848
	v_exp_f32_e32 v50, v50
	v_exp_f32_e32 v51, v51
	v_exp_f32_e32 v52, v52
	v_exp_f32_e32 v53, v53
	v_exp_f32_e32 v54, v54
	s_waitcnt vmcnt(3) lgkmcnt(0)
	s_barrier
	s_waitcnt lgkmcnt(7)
	v_mfma_f32_32x32x16_bf16 v[130:145], v[18:21], v[174:177], v[2:17]
	v_add_f32_e32 v82, v55, v56
	v_add_f32_e32 v82, v82, v57
	v_add_f32_e32 v82, v82, v58
	v_add_f32_e32 v82, v82, v59
	v_add_f32_e32 v82, v82, v60
	v_cvt_pk_bf16_f32 v146, v55, v56
	v_cvt_pk_bf16_f32 v147, v57, v58
	s_waitcnt lgkmcnt(6)
	v_mfma_f32_32x32x16_bf16 v[98:113], v[22:25], v[174:177], v[2:17]
	v_add_f32_e32 v18, v61, v82
	v_add_f32_e32 v18, v62, v18
	v_add_f32_e32 v18, v63, v18
	v_add_f32_e32 v18, v64, v18
	v_cvt_pk_bf16_f32 v148, v59, v60
	v_cvt_pk_bf16_f32 v149, v61, v62
	s_waitcnt lgkmcnt(5)
	v_mfma_f32_32x32x16_bf16 v[130:145], v[26:29], v[170:173], v[130:145]
	v_add_f32_e32 v18, v65, v18
	v_add_f32_e32 v18, v66, v18
	v_add_f32_e32 v18, v67, v18
	v_add_f32_e32 v18, v68, v18
	v_cvt_pk_bf16_f32 v150, v63, v64
	v_cvt_pk_bf16_f32 v151, v65, v66
	s_waitcnt lgkmcnt(4)
	v_mfma_f32_32x32x16_bf16 v[98:113], v[30:33], v[170:173], v[98:113]
	v_add_f32_e32 v18, v69, v18
	v_add_f32_e32 v18, v70, v18
	v_add_f32_e32 v18, v71, v18
	v_add_f32_e32 v18, v72, v18
	v_cvt_pk_bf16_f32 v152, v67, v68
	v_cvt_pk_bf16_f32 v153, v69, v70
	s_waitcnt lgkmcnt(3)
	v_mfma_f32_32x32x16_bf16 v[130:145], v[34:37], v[166:169], v[130:145]
	v_add_f32_e32 v18, v73, v18
	v_add_f32_e32 v18, v74, v18
	v_add_f32_e32 v18, v75, v18
	v_add_f32_e32 v18, v76, v18
	v_cvt_pk_bf16_f32 v154, v71, v72
	v_cvt_pk_bf16_f32 v155, v73, v74
	s_waitcnt lgkmcnt(2)
	v_mfma_f32_32x32x16_bf16 v[98:113], v[38:41], v[166:169], v[98:113]
	v_add_f32_e32 v18, v77, v18
	v_add_f32_e32 v18, v78, v18
	v_add_f32_e32 v18, v79, v18
	v_add_f32_e32 v18, v80, v18
	v_cvt_pk_bf16_f32 v156, v75, v76
	v_cvt_pk_bf16_f32 v157, v77, v78
	s_waitcnt lgkmcnt(1)
	v_mfma_f32_32x32x16_bf16 v[130:145], v[42:45], v[162:165], v[130:145]
	v_add_f32_e32 v18, v50, v18
	v_add_f32_e32 v18, v51, v18
	v_add_f32_e32 v18, v52, v18
	v_add_f32_e32 v18, v53, v18
	v_cvt_pk_bf16_f32 v158, v79, v80
	v_cvt_pk_bf16_f32 v159, v50, v51
	s_waitcnt lgkmcnt(0)
	v_mfma_f32_32x32x16_bf16 v[98:113], v[46:49], v[162:165], v[98:113]
	v_add_f32_e32 v18, v54, v18
	v_add_f32_e32 v18, v81, v18
	v_add_f32_e32 v18, 0, v18
	v_cvt_pk_bf16_f32 v160, v52, v53
	v_cvt_pk_bf16_f32 v161, v54, v81
	s_nop 0
	v_add_f32_e32 v236, 0, v18
	ds_read_b64_tr_b16 v[18:19], v233 offset:24576
	ds_read_b64_tr_b16 v[20:21], v233 offset:25088
	ds_read_b64_tr_b16 v[34:35], v233 offset:28672
	ds_read_b64_tr_b16 v[36:37], v233 offset:29184
	ds_read_b64_tr_b16 v[70:71], v233 offset:25600
	ds_read_b64_tr_b16 v[72:73], v233 offset:26112
	ds_read_b64_tr_b16 v[66:67], v233 offset:29696
	ds_read_b64_tr_b16 v[68:69], v233 offset:30208
	ds_read_b64_tr_b16 v[62:63], v233 offset:26624
	ds_read_b64_tr_b16 v[64:65], v233 offset:27136
	ds_read_b64_tr_b16 v[54:55], v233 offset:27648
	ds_read_b64_tr_b16 v[56:57], v233 offset:28160
	ds_read_b64_tr_b16 v[58:59], v233 offset:30720
	ds_read_b64_tr_b16 v[60:61], v233 offset:31232
	ds_read_b64_tr_b16 v[50:51], v233 offset:31744
	ds_read_b64_tr_b16 v[52:53], v233 offset:32256
	s_add_u32 s18, s0, 0x90800
	s_addc_u32 s19, s1, 0
	s_add_i32 s20, s22, 0xe000
	v_lshl_add_u64 v[22:23], s[18:19], 0, v[0:1]
	s_mov_b32 s21, m0
	s_mov_b32 m0, s20
	s_nop 0
	global_load_lds_dwordx4 v[22:23], off
	s_mov_b32 m0, s21
	s_add_u32 s20, s0, 0x90880
	s_addc_u32 s21, s1, 0
	v_lshl_add_u64 v[22:23], s[20:21], 0, v[0:1]
	s_add_i32 s0, s22, 0x10000
	s_mov_b32 s1, m0
	s_mov_b32 m0, s0
	s_nop 0
	global_load_lds_dwordx4 v[22:23], off
	s_mov_b32 m0, s1
	v_max_f32_e32 v22, v131, v131
	v_max_f32_e32 v23, v130, v130
	v_max_f32_e32 v22, v23, v22
	v_max3_f32 v23, v132, v133, v99
	v_max3_f32 v22, v22, v98, v100
	v_max3_f32 v22, v22, v101, v134
	v_max3_f32 v23, v23, v136, v137
	v_max3_f32 v22, v22, v135, v102
	v_max3_f32 v23, v23, v104, v105
	v_max3_f32 v22, v22, v103, v138
	v_max3_f32 v23, v23, v140, v141
	v_max3_f32 v22, v22, v139, v106
	v_max3_f32 v23, v23, v108, v109
	v_max3_f32 v22, v22, v107, v142
	v_max3_f32 v23, v23, v144, v145
	v_max3_f32 v22, v22, v143, v110
	v_max3_f32 v23, v23, v112, v113
	v_max3_f32 v22, v22, v111, v23
	v_mov_b32_e32 v23, v22
	s_nop 1
	v_permlane32_swap_b32_e32 v22, v23
	v_max_f32_e32 v23, v23, v23
	v_max_f32_e32 v22, v22, v22
	v_max_f32_e32 v22, v22, v23
	v_cmp_lt_f32_e32 vcc, s15, v22
	s_cbranch_vccnz .LBB0_606
	s_mov_b64 s[0:1], 0

.LBB0_519:
	s_waitcnt lgkmcnt(7)
	v_mfma_f32_32x32x16_bf16 v[114:129], v[82:85], v[174:177], v[2:17]
	v_add_f32_e32 v86, v130, v131
	v_add_f32_e32 v86, v132, v86
	v_add_f32_e32 v86, v133, v86
	v_add_f32_e32 v86, v134, v86
	v_add_f32_e32 v86, v135, v86
	v_cvt_pk_bf16_f32 v146, v130, v131
	v_cvt_pk_bf16_f32 v147, v132, v133
	s_nop 0
	v_add_f32_e32 v82, v136, v86
	v_add_f32_e32 v82, v137, v82
	v_add_f32_e32 v82, v138, v82
	v_add_f32_e32 v130, v139, v82
	s_waitcnt lgkmcnt(6)
	v_mfma_f32_32x32x16_bf16 v[82:97], v[198:201], v[174:177], v[2:17]
	v_cvt_pk_bf16_f32 v148, v134, v135
	v_cvt_pk_bf16_f32 v149, v136, v137
	s_waitcnt lgkmcnt(5)
	v_mfma_f32_32x32x16_bf16 v[114:129], v[202:205], v[170:173], v[114:129]
	v_add_f32_e32 v130, v140, v130
	v_add_f32_e32 v130, v141, v130
	v_add_f32_e32 v130, v142, v130
	v_add_f32_e32 v130, v143, v130
	v_cvt_pk_bf16_f32 v150, v138, v139
	v_cvt_pk_bf16_f32 v151, v140, v141
	s_waitcnt lgkmcnt(4)
	v_mfma_f32_32x32x16_bf16 v[82:97], v[194:197], v[170:173], v[82:97]
	v_add_f32_e32 v130, v144, v130
	v_add_f32_e32 v130, v145, v130
	v_add_f32_e32 v130, v98, v130
	v_add_f32_e32 v130, v99, v130
	v_cvt_pk_bf16_f32 v152, v142, v143
	v_cvt_pk_bf16_f32 v153, v144, v145
	s_waitcnt lgkmcnt(3)
	v_mfma_f32_32x32x16_bf16 v[114:129], v[190:193], v[166:169], v[114:129]
	v_add_f32_e32 v130, v100, v130
	v_add_f32_e32 v130, v101, v130
	v_add_f32_e32 v130, v102, v130
	v_add_f32_e32 v130, v103, v130
	v_cvt_pk_bf16_f32 v154, v98, v99
	v_cvt_pk_bf16_f32 v155, v100, v101
	s_waitcnt lgkmcnt(2)
	v_mfma_f32_32x32x16_bf16 v[82:97], v[186:189], v[166:169], v[82:97]
	v_add_f32_e32 v98, v104, v130
	v_add_f32_e32 v98, v105, v98
	v_add_f32_e32 v98, v106, v98
	v_add_f32_e32 v98, v107, v98
	v_cvt_pk_bf16_f32 v156, v102, v103
	v_cvt_pk_bf16_f32 v157, v104, v105
	s_waitcnt lgkmcnt(1)
	v_mfma_f32_32x32x16_bf16 v[114:129], v[182:185], v[162:165], v[114:129]
	v_add_f32_e32 v98, v108, v98
	v_add_f32_e32 v98, v109, v98
	v_add_f32_e32 v98, v110, v98
	v_add_f32_e32 v98, v111, v98
	v_cvt_pk_bf16_f32 v158, v106, v107
	v_cvt_pk_bf16_f32 v159, v108, v109
	s_waitcnt lgkmcnt(0)
	v_mfma_f32_32x32x16_bf16 v[82:97], v[178:181], v[162:165], v[82:97]
	v_add_f32_e32 v98, v112, v98
	v_add_f32_e32 v98, v113, v98
	v_add_f32_e32 v98, 0, v98
	v_cvt_pk_bf16_f32 v160, v110, v111
	v_cvt_pk_bf16_f32 v161, v112, v113
	ds_read_b64_tr_b16 v[142:143], v233 offset:40960
	ds_read_b64_tr_b16 v[144:145], v233 offset:41472
	ds_read_b64_tr_b16 v[138:139], v233 offset:45056
	ds_read_b64_tr_b16 v[140:141], v233 offset:45568
	ds_read_b64_tr_b16 v[134:135], v233 offset:41984
	ds_read_b64_tr_b16 v[136:137], v233 offset:42496
	ds_read_b64_tr_b16 v[130:131], v233 offset:46080
	ds_read_b64_tr_b16 v[132:133], v233 offset:46592
	v_add_f32_e32 v194, v236, v98
	ds_read_b64_tr_b16 v[110:111], v233 offset:43008
	ds_read_b64_tr_b16 v[112:113], v233 offset:43520
	ds_read_b64_tr_b16 v[102:103], v233 offset:44032
	ds_read_b64_tr_b16 v[104:105], v233 offset:44544
	ds_read_b64_tr_b16 v[106:107], v233 offset:47104
	ds_read_b64_tr_b16 v[108:109], v233 offset:47616
	ds_read_b64_tr_b16 v[98:99], v233 offset:48128
	ds_read_b64_tr_b16 v[100:101], v233 offset:48640
	s_add_u32 s22, s4, 0xd8000
	s_addc_u32 s23, s5, 0
	s_add_u32 s24, s4, 0xd8080
	v_lshl_add_u64 v[178:179], s[22:23], 0, v[0:1]
	s_addc_u32 s25, s5, 0
	s_mov_b32 s0, m0
	s_mov_b32 m0, s26
	s_nop 0
	global_load_lds_dwordx4 v[178:179], off
	s_mov_b32 m0, s0
	v_lshl_add_u64 v[178:179], s[24:25], 0, v[0:1]
	s_addk_i32 s26, 0x2000
	s_mov_b32 s0, m0
	s_mov_b32 m0, s26
	s_nop 0
	global_load_lds_dwordx4 v[178:179], off
	s_mov_b32 m0, s0
	v_max_f32_e32 v0, v115, v115
	v_max_f32_e32 v178, v114, v114
	v_max_f32_e32 v0, v178, v0
	v_max3_f32 v178, v116, v117, v83
	v_max3_f32 v0, v0, v82, v84
	v_max3_f32 v0, v0, v85, v118
	v_max3_f32 v178, v178, v120, v121
	v_max3_f32 v0, v0, v119, v86
	v_max3_f32 v178, v178, v88, v89
	v_max3_f32 v0, v0, v87, v122
	v_max3_f32 v178, v178, v124, v125
	v_max3_f32 v0, v0, v123, v90
	v_max3_f32 v178, v178, v92, v93
	v_max3_f32 v0, v0, v91, v126
	v_max3_f32 v178, v178, v128, v129
	v_max3_f32 v0, v0, v127, v94
	v_max3_f32 v178, v178, v96, v97
	v_max3_f32 v0, v0, v95, v178
	v_mov_b32_e32 v178, v0
	s_nop 1
	v_permlane32_swap_b32_e32 v0, v178
	v_max_f32_e32 v178, v178, v178
	v_max_f32_e32 v0, v0, v0
	v_max_f32_e32 v0, v0, v178
	v_cmp_lt_f32_e32 vcc, s15, v0
	s_cbranch_vccnz .LBB0_609
	s_mov_b64 s[0:1], 0

; __device__ __forceinline__ int crow(int r,int hi){return (r&3)+8*(r>>2)+4*hi;}
; #define SBAR() __builtin_amdgcn_sched_barrier(0)
;   #define PKW(P,B) cvtpk_s(P[B],P[B+1])
;   #define PKW(P,B) cvtpk_s(P[B],P[B+1])
; template<int THRL,int MODE> __device__ __forceinline__ void attn_unit128(const bf16*Qblk,const bf16*__restrict__ Kh,const bf16*__restrict__ Vh,bf16*Oblk,const int NT,char*shm,const bf16*O1blk,bf16*AOblk,const float lam,const float*sln,const float omli){
;     ...
;   { float sacc=pB0[0]+pB0[1]; _Pragma("unroll") for(int r=2;r<16;++r)sacc+=pB0[r]; _Pragma("unroll") for(int r=0;r<16;++r)sacc+=pB1[r]; l_reg+=sacc;
;     pw0=(u32x4){PKW(pB0,0),PKW(pB0,2),PKW(pB0,4),PKW(pB0,6)};pw1=(u32x4){PKW(pB0,8),PKW(pB0,10),PKW(pB0,12),PKW(pB0,14)};pw2=(u32x4){PKW(pB1,0),PKW(pB1,2),PKW(pB1,4),PKW(pB1,6)};pw3=(u32x4){PKW(pB1,8),PKW(pB1,10),PKW(pB1,12),PKW(pB1,14)};
;     SBAR(); { const int vb0=(int)(unsigned)(size_t)vp0; pv(o,vb0+2*sl_cur,PAF(0),PAF(1),PAF(2),PAF(3)); pv(o+2,vb0+2*sl_cur+8192,PAF(0),PAF(1),PAF(2),PAF(3)); } }
;     ...
;   {auto rr=__builtin_amdgcn_permlane32_swap(__float_as_uint(l_reg),__float_as_uint(l_reg),false,false);l_reg=__uint_as_float(rr[0])+__uint_as_float(rr[1]);}
;   if(hi==0)wsf[32+r32]=l_reg;asm volatile("s_waitcnt lgkmcnt(0)":::"memory");
;   float rli[16];
;   #pragma unroll
;   for(int r=0;r<16;++r)rli[r]=__builtin_amdgcn_rcpf(wsf[32+crow(r,hi)]);
;   bf16*Ow=Oblk+(long)wid*QBLK*PO;
.LBB0_525:
	v_add_f32_e32 v83, v98, v99
	v_add_f32_e32 v83, v100, v83
	v_add_f32_e32 v83, v101, v83
	v_add_f32_e32 v83, v102, v83
	v_add_f32_e32 v83, v103, v83
	v_add_f32_e32 v83, v104, v83
	v_add_f32_e32 v83, v105, v83
	v_add_f32_e32 v83, v106, v83
	v_add_f32_e32 v83, v107, v83
	v_add_f32_e32 v83, v108, v83
	v_add_f32_e32 v83, v109, v83
	v_add_f32_e32 v83, v110, v83
	v_add_f32_e32 v83, v111, v83
	v_add_f32_e32 v83, v112, v83
	v_add_f32_e32 v83, v113, v83
	v_add_f32_e32 v83, v83, v2
	v_add_f32_e32 v83, v3, v83
	v_add_f32_e32 v83, v4, v83
	v_add_f32_e32 v83, v5, v83
	v_add_f32_e32 v83, v6, v83
	v_add_f32_e32 v83, v7, v83
	v_add_f32_e32 v83, v8, v83
	v_add_f32_e32 v83, v9, v83
	v_add_f32_e32 v83, v10, v83
	v_add_f32_e32 v83, v11, v83
	v_add_f32_e32 v83, v12, v83
	v_add_f32_e32 v83, v13, v83
	v_add_f32_e32 v83, v14, v83
	v_add_f32_e32 v83, v15, v83
	v_add_f32_e32 v83, v16, v83
	v_add_f32_e32 v83, v17, v83
	v_add_f32_e32 v0, v0, v83
	v_cvt_pk_bf16_f32 v2, v2, v3
	v_cvt_pk_bf16_f32 v84, v98, v99
	v_cvt_pk_bf16_f32 v85, v100, v101
	v_cvt_pk_bf16_f32 v86, v102, v103
	v_cvt_pk_bf16_f32 v87, v104, v105
	v_cvt_pk_bf16_f32 v88, v106, v107
	v_cvt_pk_bf16_f32 v89, v108, v109
	v_cvt_pk_bf16_f32 v90, v110, v111
	v_cvt_pk_bf16_f32 v91, v112, v113
	v_cvt_pk_bf16_f32 v3, v4, v5
	v_cvt_pk_bf16_f32 v4, v6, v7
	v_cvt_pk_bf16_f32 v5, v8, v9
	v_cvt_pk_bf16_f32 v6, v10, v11
	v_cvt_pk_bf16_f32 v7, v12, v13
	v_cvt_pk_bf16_f32 v8, v14, v15
	v_cvt_pk_bf16_f32 v9, v16, v17
	ds_read_b64_tr_b16 v[10:11],v82 offset:0
	ds_read_b64_tr_b16 v[12:13],v82 offset:512
	ds_read_b64_tr_b16 v[14:15],v82 offset:1024
	ds_read_b64_tr_b16 v[16:17],v82 offset:1536
	ds_read_b64_tr_b16 v[92:93],v82 offset:2048
	ds_read_b64_tr_b16 v[94:95],v82 offset:2560
	ds_read_b64_tr_b16 v[96:97],v82 offset:3072
	ds_read_b64_tr_b16 v[98:99],v82 offset:3584
	s_waitcnt lgkmcnt(0)
	s_nop 0
	v_mfma_f32_32x32x16_bf16 v[18:33], v[84:87], v[10:13], v[18:33]
	ds_read_b64_tr_b16 v[10:11],v82 offset:4096
	ds_read_b64_tr_b16 v[12:13],v82 offset:4608
	v_mfma_f32_32x32x16_bf16 v[18:33], v[88:91], v[14:17], v[18:33]
	ds_read_b64_tr_b16 v[14:15],v82 offset:5120
	ds_read_b64_tr_b16 v[16:17],v82 offset:5632
	v_mfma_f32_32x32x16_bf16 v[18:33], v[2:5], v[92:95], v[18:33]
	ds_read_b64_tr_b16 v[92:93],v82 offset:6144
	ds_read_b64_tr_b16 v[94:95],v82 offset:6656
	v_mfma_f32_32x32x16_bf16 v[18:33], v[6:9], v[96:99], v[18:33]
	ds_read_b64_tr_b16 v[96:97],v82 offset:7168
	ds_read_b64_tr_b16 v[98:99],v82 offset:7680
	s_waitcnt lgkmcnt(0)
	v_mfma_f32_32x32x16_bf16 v[34:49], v[84:87], v[10:13], v[34:49]
	v_add_u32_e32 v82, 0x2000, v82
	ds_read_b64_tr_b16 v[10:11],v82 offset:0
	ds_read_b64_tr_b16 v[12:13],v82 offset:512
	v_mfma_f32_32x32x16_bf16 v[34:49], v[88:91], v[14:17], v[34:49]
	ds_read_b64_tr_b16 v[14:15],v82 offset:1024
	ds_read_b64_tr_b16 v[16:17],v82 offset:1536
	v_mfma_f32_32x32x16_bf16 v[34:49], v[2:5], v[92:95], v[34:49]
	ds_read_b64_tr_b16 v[92:93],v82 offset:2048
	ds_read_b64_tr_b16 v[94:95],v82 offset:2560
	v_mfma_f32_32x32x16_bf16 v[34:49], v[6:9], v[96:99], v[34:49]
	ds_read_b64_tr_b16 v[96:97],v82 offset:3072
	ds_read_b64_tr_b16 v[98:99],v82 offset:3584
	s_waitcnt lgkmcnt(0)
	v_mfma_f32_32x32x16_bf16 v[50:65], v[84:87], v[10:13], v[50:65]
	ds_read_b64_tr_b16 v[10:11],v82 offset:4096
	ds_read_b64_tr_b16 v[12:13],v82 offset:4608
	v_mfma_f32_32x32x16_bf16 v[50:65], v[88:91], v[14:17], v[50:65]
	ds_read_b64_tr_b16 v[14:15],v82 offset:5120
	ds_read_b64_tr_b16 v[16:17],v82 offset:5632
	v_mfma_f32_32x32x16_bf16 v[50:65], v[2:5], v[92:95], v[50:65]
	ds_read_b64_tr_b16 v[92:93],v82 offset:6144
	ds_read_b64_tr_b16 v[94:95],v82 offset:6656
	v_mfma_f32_32x32x16_bf16 v[50:65], v[6:9], v[96:99], v[50:65]
	ds_read_b64_tr_b16 v[96:97],v82 offset:7168
	ds_read_b64_tr_b16 v[98:99],v82 offset:7680
	s_waitcnt lgkmcnt(0)
	v_mfma_f32_32x32x16_bf16 v[66:81], v[84:87], v[10:13], v[66:81]
	v_mfma_f32_32x32x16_bf16 v[66:81], v[88:91], v[14:17], v[66:81]
	v_mfma_f32_32x32x16_bf16 v[66:81], v[2:5], v[92:95], v[66:81]
	v_mov_b32_e32 v2, v0
	s_nop 1
	v_permlane32_swap_b32_e32 v0, v2
	v_mfma_f32_32x32x16_bf16 v[66:81], v[6:9], v[96:99], v[66:81]
	s_and_saveexec_b64 s[0:1], s[40:41]
	v_add_f32_e32 v0, v0, v2
	ds_write_b32 v216, v0 offset:128
	s_or_b64 exec, exec, s[0:1]
	s_waitcnt lgkmcnt(0)
	ds_read_b128 v[2:5], v217 offset:128
	ds_read_b128 v[6:9], v217 offset:160
	s_mul_i32 s1, s28, 0x30c0000
	v_readlane_b32 s26, v254, 63
	s_mul_hi_u32 s0, s28, 0x30c0000
	s_add_u32 s1, s26, s1
	v_readlane_b32 s26, v255, 0
	s_addc_u32 s26, s26, s0
	s_lshl_b32 s0, s36, 9
	s_add_u32 s0, s1, s0
	s_waitcnt lgkmcnt(1)
	v_rcp_f32_e32 v12, v2
	v_rcp_f32_e32 v13, v3
	v_rcp_f32_e32 v14, v4
	v_rcp_f32_e32 v15, v5
	ds_read_b128 v[2:5], v217 offset:192
	s_addc_u32 s1, s26, 0
	s_waitcnt lgkmcnt(1)
	v_rcp_f32_e32 v16, v6
	v_rcp_f32_e32 v17, v7
	v_rcp_f32_e32 v82, v8
	v_rcp_f32_e32 v83, v9
	ds_read_b128 v[6:9], v217 offset:224
	s_mul_i32 s26, s33, 0x18000
	s_mul_hi_i32 s27, s33, 0x18000
	s_add_u32 s26, s0, s26
	s_addc_u32 s27, s1, s27
	s_lshl_b32 s31, s33, 12
	s_add_i32 s31, s31, 0
	s_waitcnt lgkmcnt(1)
	v_rcp_f32_e32 v84, v2
	s_add_i32 s31, s31, 0x12800
	v_lshlrev_b32_e32 v0, 9, v214
	v_lshlrev_b32_e32 v2, 1, v213
	s_waitcnt lgkmcnt(0)
; __device__ __forceinline__ int crow(int r,int hi){return (r&3)+8*(r>>2)+4*hi;}
; template<int THRL,int MODE> __device__ __forceinline__ void attn_unit128(const bf16*Qblk,const bf16*__restrict__ Kh,const bf16*__restrict__ Vh,bf16*Oblk,const int NT,char*shm,const bf16*O1blk,bf16*AOblk,const float lam,const float*sln,const float omli){
;     ...
;   bf16*Ow=Oblk+(long)wid*QBLK*PO;
;   if constexpr(MODE==0)
;   { bf16*stg=(bf16*)(shm+LDS_OST8)+wid*2048;
;     #pragma unroll
;     for(int h2=0;h2<2;++h2){
;       #pragma unroll
;       for(int r=0;r<16;++r){const int orow=crow(r,hi);
;         #pragma unroll
;         for(int d0=0;d0<2;++d0)stg[orow*64+d0*32+r32]=__float2bfloat16(o[2*h2+d0][r]*rli[r]);}
;       asm volatile("s_waitcnt lgkmcnt(0)":::"memory");
;       #pragma unroll
;       for(int i=0;i<4;++i){const int row=i*8+(lane>>3),ch=lane&7; const u32x4 v=*(const u32x4*)(stg+row*64+ch*8); ATTN_STORE16(Ow+(long)row*PO+h2*64+ch*8,v);}
;       asm volatile("s_waitcnt lgkmcnt(0)":::"memory");
	v_rcp_f32_e32 v90, v8
	v_add3_u32 v92, s31, v0, v2
	v_lshrrev_b32_e32 v8, 3, v212
	v_lshlrev_b32_e32 v0, 1, v215
	v_and_b32_e32 v0, 0x70, v0
	v_lshlrev_b32_e32 v2, 7, v8
	v_rcp_f32_e32 v88, v6
	v_rcp_f32_e32 v89, v7
	v_lshl_add_u64 v[6:7], s[26:27], 0, v[0:1]
	v_add3_u32 v93, s31, v0, v2
	v_mul_f32_e32 v0, v18, v12
	v_cvt_pk_bf16_f32 v0, v0, s0
	ds_write_b16 v92, v0
	v_mul_f32_e32 v0, v34, v12
	v_cvt_pk_bf16_f32 v0, v0, s0
	ds_write_b16 v92, v0 offset:64
	v_mul_f32_e32 v0, v19, v13
	v_cvt_pk_bf16_f32 v0, v0, s0
	ds_write_b16 v92, v0 offset:128
	v_mul_f32_e32 v0, v35, v13
	v_cvt_pk_bf16_f32 v0, v0, s0
	ds_write_b16 v92, v0 offset:192
	v_mul_f32_e32 v0, v20, v14
	v_cvt_pk_bf16_f32 v0, v0, s0
	ds_write_b16 v92, v0 offset:256
	v_mul_f32_e32 v0, v36, v14
	v_cvt_pk_bf16_f32 v0, v0, s0
	ds_write_b16 v92, v0 offset:320
	v_mul_f32_e32 v0, v21, v15
	v_cvt_pk_bf16_f32 v0, v0, s0
	ds_write_b16 v92, v0 offset:384
	v_mul_f32_e32 v0, v37, v15
	v_cvt_pk_bf16_f32 v0, v0, s0
	ds_write_b16 v92, v0 offset:448
	v_mul_f32_e32 v0, v22, v16
	v_cvt_pk_bf16_f32 v0, v0, s0
	ds_write_b16 v92, v0 offset:1024
	v_mul_f32_e32 v0, v38, v16
	v_cvt_pk_bf16_f32 v0, v0, s0
	ds_write_b16 v92, v0 offset:1088
	v_mul_f32_e32 v0, v23, v17
	v_cvt_pk_bf16_f32 v0, v0, s0
	ds_write_b16 v92, v0 offset:1152
	v_mul_f32_e32 v0, v39, v17
	v_cvt_pk_bf16_f32 v0, v0, s0
	ds_write_b16 v92, v0 offset:1216
	v_mul_f32_e32 v0, v24, v82
	v_cvt_pk_bf16_f32 v0, v0, s0
	ds_write_b16 v92, v0 offset:1280
	v_mul_f32_e32 v0, v40, v82
	v_cvt_pk_bf16_f32 v0, v0, s0
	ds_write_b16 v92, v0 offset:1344
	v_mul_f32_e32 v0, v25, v83
	v_cvt_pk_bf16_f32 v0, v0, s0
	ds_write_b16 v92, v0 offset:1408
	v_mul_f32_e32 v0, v41, v83
	v_cvt_pk_bf16_f32 v0, v0, s0
	v_rcp_f32_e32 v85, v3
	ds_write_b16 v92, v0 offset:1472
	v_mul_f32_e32 v0, v26, v84
	v_cvt_pk_bf16_f32 v0, v0, s0
	ds_write_b16 v92, v0 offset:2048
	v_mul_f32_e32 v0, v42, v84
	v_cvt_pk_bf16_f32 v0, v0, s0
	v_rcp_f32_e32 v86, v4
	ds_write_b16 v92, v0 offset:2112
	v_mul_f32_e32 v0, v27, v85
	v_cvt_pk_bf16_f32 v0, v0, s0
	ds_write_b16 v92, v0 offset:2176
	v_mul_f32_e32 v0, v43, v85
	v_cvt_pk_bf16_f32 v0, v0, s0
	v_rcp_f32_e32 v87, v5
	ds_write_b16 v92, v0 offset:2240
	v_mul_f32_e32 v0, v28, v86
	v_cvt_pk_bf16_f32 v0, v0, s0
	ds_write_b16 v92, v0 offset:2304
	v_mul_f32_e32 v0, v44, v86
	v_cvt_pk_bf16_f32 v0, v0, s0
	ds_write_b16 v92, v0 offset:2368
	v_mul_f32_e32 v0, v29, v87
	v_cvt_pk_bf16_f32 v0, v0, s0
	ds_write_b16 v92, v0 offset:2432
	v_mul_f32_e32 v0, v45, v87
	v_cvt_pk_bf16_f32 v0, v0, s0
	ds_write_b16 v92, v0 offset:2496
	v_mul_f32_e32 v0, v30, v88
	v_cvt_pk_bf16_f32 v0, v0, s0
	ds_write_b16 v92, v0 offset:3072
	v_mul_f32_e32 v0, v46, v88
	v_cvt_pk_bf16_f32 v0, v0, s0
	ds_write_b16 v92, v0 offset:3136
	v_mul_f32_e32 v0, v31, v89
	v_cvt_pk_bf16_f32 v0, v0, s0
	ds_write_b16 v92, v0 offset:3200
	v_mul_f32_e32 v0, v47, v89
	v_cvt_pk_bf16_f32 v0, v0, s0
	v_rcp_f32_e32 v91, v9
	ds_write_b16 v92, v0 offset:3264
	v_mul_f32_e32 v0, v32, v90
	v_cvt_pk_bf16_f32 v0, v0, s0
	ds_write_b16 v92, v0 offset:3328
	v_mul_f32_e32 v0, v48, v90
	v_cvt_pk_bf16_f32 v0, v0, s0
	ds_write_b16 v92, v0 offset:3392
	v_mul_f32_e32 v0, v33, v91
	v_cvt_pk_bf16_f32 v0, v0, s0
	ds_write_b16 v92, v0 offset:3456
	v_mul_f32_e32 v0, v49, v91
	v_cvt_pk_bf16_f32 v0, v0, s0
	ds_write_b16 v92, v0 offset:3520
	s_waitcnt lgkmcnt(0)
	ds_read_b128 v[2:5], v93
	v_mul_u32_u24_e32 v0, 0x600, v8
	v_lshlrev_b32_e32 v0, 1, v0
	v_lshl_add_u64 v[18:19], v[6:7], 0, v[0:1]
	ds_read_b128 v[6:9], v93 offset:1024
	s_mov_b64 s[26:27], 0x6000
	v_lshl_add_u64 v[20:21], v[18:19], 0, s[26:27]
	s_movk_i32 s26, 0x6000
	s_waitcnt lgkmcnt(1)
	global_store_dwordx4 v[18:19], v[2:5], off
	v_mul_f32_e32 v0, v50, v12
	v_cvt_pk_bf16_f32 v0, v0, s0
	v_add_co_u32_e32 v2, vcc, s26, v18
	s_mov_b64 s[26:27], 0xc000
	s_nop 0
	v_addc_co_u32_e32 v3, vcc, 0, v19, vcc
	s_waitcnt lgkmcnt(0)
	global_store_dwordx4 v[2:3], v[6:9], off
	ds_read_b128 v[2:5], v93 offset:2048
	ds_read_b128 v[6:9], v93 offset:3072
	v_lshl_add_u64 v[22:23], v[18:19], 0, s[26:27]
	s_mov_b32 s26, 0xc000
	v_add_co_u32_e32 v10, vcc, s26, v18
	s_mov_b32 s26, 0x12000
	s_nop 0
	v_addc_co_u32_e32 v11, vcc, 0, v19, vcc
	s_waitcnt lgkmcnt(1)
	global_store_dwordx4 v[10:11], v[2:5], off
	v_mov_b32_e32 v213, v220
	s_nop 0
	v_add_co_u32_e32 v2, vcc, s26, v18
	s_mov_b64 s[26:27], 0x12000
	s_nop 0
	v_addc_co_u32_e32 v3, vcc, 0, v19, vcc
	s_waitcnt lgkmcnt(0)
	global_store_dwordx4 v[2:3], v[6:9], off
	s_waitcnt lgkmcnt(0)
; __device__ __forceinline__ int crow(int r,int hi){return (r&3)+8*(r>>2)+4*hi;}
; #define WAIT_BAR(N) asm volatile("s_waitcnt vmcnt(" #N ") lgkmcnt(0)\n\ts_barrier":::"memory")
;   #define DMA_K(t,slot) glds16(ksrc+(long)(t)*KVBLK*PQ,(unsigned)__builtin_amdgcn_readfirstlane(kdst+(slot)))
;   #define DMA_V(t,slot) glds16(vsrc+(long)(t)*KVBLK*PQ,(unsigned)__builtin_amdgcn_readfirstlane(vdst+(slot)))
; template<int THRL,int MODE> __device__ __forceinline__ void attn_unit128(const bf16*Qblk,const bf16*__restrict__ Kh,const bf16*__restrict__ Vh,bf16*Oblk,const int NT,char*shm,const bf16*O1blk,bf16*AOblk,const float lam,const float*sln,const float omli){
;   int tid_=threadIdx.x; asm volatile("":"+v"(tid_));
;   const int tid=tid_,lane=tid&63,r32=lane&31,hi=lane>>5; const int wid=__builtin_amdgcn_readfirstlane(tid>>6);
;   const bf16*Qw=Qblk+(long)wid*QBLK*PQ;
;   const unsigned lds0=(unsigned)(uintptr_t)shm;
;   float*wsf=(float*)(shm+LDS_WS8)+wid*64;
;   const unsigned koff=(unsigned)(lane*PQ+wid*8)*2u;
;   const unsigned voff=(unsigned)((16*(wid&3)+(lane>>2))*PQ+(wid>>2)*32+(lane&3)*8)*2u;
;   const unsigned kdst=lds0+LDS_K+wid*1024, vdst=lds0+LDS_V+wid*1024;
;     ...
;   const char*Kbase=shm+LDS_K; bf16x8 kf[8];
;   const lds_cptr shm3=(lds_cptr)shm; const lds_cptr kp0=shm3+LDS_K+hi*1024+r32*16; const lds_cptr vp0=shm3+LDS_V+((lane>>4)&1)*32+(lane&3)*8+(4*hi+((lane&15)>>2))*64;
;   DMA_K(0,0);DMA_V(0,0);DMA_K(1,SLOTB);
;   bf16x8 qr[4];
;   #pragma unroll
;   for(int d0=0;d0<4;++d0)qr[d0]=*reinterpret_cast<const bf16x8*>(&Qw[(long)r32*PQ+d0*16+hi*8]);
;   float mhat=0.f,l_reg=0.f;f32x16 o[4];o[0]=f32x16{};o[1]=f32x16{};o[2]=f32x16{};o[3]=f32x16{};f32x16 negm=f32x16{};asm volatile("":"+v"(negm));
;     ...
;   bool resc=false;
;     ...
;   f32x16 pA0,pA1,pB0,pB1;
;   int sl_prev=0,sl_cur=0,sl_next=SLOTB;
;     ...
;   DMA_K(2,2*SLOTB);
;   WAIT_BAR(4);
;     ...
;       for(int r=0;r<16;++r){const int orow=crow(r,hi);
;         #pragma unroll
;         for(int d0=0;d0<2;++d0)stg[orow*64+d0*32+r32]=__float2bfloat16(o[2*h2+d0][r]*rli[r]);}
;       asm volatile("s_waitcnt lgkmcnt(0)":::"memory");
;       #pragma unroll
;       for(int i=0;i<4;++i){const int row=i*8+(lane>>3),ch=lane&7; const u32x4 v=*(const u32x4*)(stg+row*64+ch*8); ATTN_STORE16(Ow+(long)row*PO+h2*64+ch*8,v);}
;       asm volatile("s_waitcnt lgkmcnt(0)":::"memory");
	ds_write_b16 v92, v0
	v_mul_f32_e32 v0, v66, v12
	v_cvt_pk_bf16_f32 v0, v0, s0
	ds_write_b16 v92, v0 offset:64
	v_mul_f32_e32 v0, v51, v13
	v_cvt_pk_bf16_f32 v0, v0, s0
	ds_write_b16 v92, v0 offset:128
	v_mul_f32_e32 v0, v67, v13
	v_cvt_pk_bf16_f32 v0, v0, s0
	ds_write_b16 v92, v0 offset:192
	v_mul_f32_e32 v0, v52, v14
	v_cvt_pk_bf16_f32 v0, v0, s0
	ds_write_b16 v92, v0 offset:256
	v_mul_f32_e32 v0, v68, v14
	v_cvt_pk_bf16_f32 v0, v0, s0
	ds_write_b16 v92, v0 offset:320
	v_mul_f32_e32 v0, v53, v15
	v_cvt_pk_bf16_f32 v0, v0, s0
	ds_write_b16 v92, v0 offset:384
	v_mul_f32_e32 v0, v69, v15
	v_cvt_pk_bf16_f32 v0, v0, s0
	ds_write_b16 v92, v0 offset:448
	v_mul_f32_e32 v0, v54, v16
	v_cvt_pk_bf16_f32 v0, v0, s0
	ds_write_b16 v92, v0 offset:1024
	v_mul_f32_e32 v0, v70, v16
	v_cvt_pk_bf16_f32 v0, v0, s0
	ds_write_b16 v92, v0 offset:1088
	v_mul_f32_e32 v0, v55, v17
	v_cvt_pk_bf16_f32 v0, v0, s0
	ds_write_b16 v92, v0 offset:1152
	v_mul_f32_e32 v0, v71, v17
	v_cvt_pk_bf16_f32 v0, v0, s0
	ds_write_b16 v92, v0 offset:1216
	v_mul_f32_e32 v0, v56, v82
	v_cvt_pk_bf16_f32 v0, v0, s0
	ds_write_b16 v92, v0 offset:1280
	v_mul_f32_e32 v0, v72, v82
	v_cvt_pk_bf16_f32 v0, v0, s0
	ds_write_b16 v92, v0 offset:1344
	v_mul_f32_e32 v0, v57, v83
	v_cvt_pk_bf16_f32 v0, v0, s0
	ds_write_b16 v92, v0 offset:1408
	v_mul_f32_e32 v0, v73, v83
	v_cvt_pk_bf16_f32 v0, v0, s0
	ds_write_b16 v92, v0 offset:1472
	v_mul_f32_e32 v0, v58, v84
	v_cvt_pk_bf16_f32 v0, v0, s0
	ds_write_b16 v92, v0 offset:2048
	v_mul_f32_e32 v0, v74, v84
	v_cvt_pk_bf16_f32 v0, v0, s0
	ds_write_b16 v92, v0 offset:2112
	v_mul_f32_e32 v0, v59, v85
	v_cvt_pk_bf16_f32 v0, v0, s0
	ds_write_b16 v92, v0 offset:2176
	v_mul_f32_e32 v0, v75, v85
	v_cvt_pk_bf16_f32 v0, v0, s0
	ds_write_b16 v92, v0 offset:2240
	v_mul_f32_e32 v0, v60, v86
	v_cvt_pk_bf16_f32 v0, v0, s0
	ds_write_b16 v92, v0 offset:2304
	v_mul_f32_e32 v0, v76, v86
	v_cvt_pk_bf16_f32 v0, v0, s0
	ds_write_b16 v92, v0 offset:2368
	v_mul_f32_e32 v0, v61, v87
	v_cvt_pk_bf16_f32 v0, v0, s0
	ds_write_b16 v92, v0 offset:2432
	v_mul_f32_e32 v0, v77, v87
	v_cvt_pk_bf16_f32 v0, v0, s0
	ds_write_b16 v92, v0 offset:2496
	v_mul_f32_e32 v0, v62, v88
	v_cvt_pk_bf16_f32 v0, v0, s0
	ds_write_b16 v92, v0 offset:3072
	v_mul_f32_e32 v0, v78, v88
	v_cvt_pk_bf16_f32 v0, v0, s0
	ds_write_b16 v92, v0 offset:3136
	v_mul_f32_e32 v0, v63, v89
	v_cvt_pk_bf16_f32 v0, v0, s0
	ds_write_b16 v92, v0 offset:3200
	v_mul_f32_e32 v0, v79, v89
	v_cvt_pk_bf16_f32 v0, v0, s0
	ds_write_b16 v92, v0 offset:3264
	v_mul_f32_e32 v0, v64, v90
	v_cvt_pk_bf16_f32 v0, v0, s0
	ds_write_b16 v92, v0 offset:3328
	v_mul_f32_e32 v0, v80, v90
	v_cvt_pk_bf16_f32 v0, v0, s0
	ds_write_b16 v92, v0 offset:3392
	v_mul_f32_e32 v0, v65, v91
	v_cvt_pk_bf16_f32 v0, v0, s0
	ds_write_b16 v92, v0 offset:3456
	v_mul_f32_e32 v0, v81, v91
	v_cvt_pk_bf16_f32 v0, v0, s0
	ds_write_b16 v92, v0 offset:3520
	s_waitcnt lgkmcnt(0)
	ds_read_b128 v[2:5], v93
	ds_read_b128 v[6:9], v93 offset:1024
	ds_read_b128 v[10:13], v93 offset:2048
	ds_read_b128 v[14:17], v93 offset:3072
	v_lshl_add_u64 v[24:25], v[18:19], 0, s[26:27]
	s_waitcnt lgkmcnt(3)
	global_store_dwordx4 v[18:19], v[2:5], off offset:128
	s_waitcnt lgkmcnt(2)
	global_store_dwordx4 v[20:21], v[6:9], off offset:128
	s_waitcnt lgkmcnt(1)
	global_store_dwordx4 v[22:23], v[10:13], off offset:128
	s_waitcnt lgkmcnt(0)
	global_store_dwordx4 v[24:25], v[14:17], off offset:128
	s_waitcnt lgkmcnt(0)
	s_waitcnt lgkmcnt(0)
	s_barrier
	v_mov_b32_e32 v5, v1
	v_readfirstlane_b32 s26, v213
	s_ashr_i32 s36, s26, 6
	s_mul_i32 s31, s36, 0x24000
	s_mul_hi_i32 s27, s36, 0x24000
	s_add_u32 s40, s6, s31
	s_addc_u32 s41, s7, s27
	s_and_b32 s31, s26, 0x3fffffc0
	s_ashr_i32 s26, s26, 3
	s_lshl_b32 s27, s36, 4
	v_bfe_u32 v2, v213, 2, 4
	s_and_b32 s26, s26, 0x7fffffe0
	v_and_or_b32 v2, s27, 48, v2
	v_mov_b32_e32 v3, s26
	s_movk_i32 s26, 0x900
	v_mad_u32_u24 v2, v2, s26, v3
	v_lshlrev_b32_e32 v3, 3, v213
	v_and_b32_e32 v39, 63, v213
	v_mov_b32_e32 v0, s27
	v_and_b32_e32 v36, 24, v3
	s_lshl_b32 s26, s36, 10
	v_mad_u32_u24 v0, v39, s81, v0
	v_or_b32_e32 v2, v2, v36
	s_cmp_lg_u32 0, -1
	v_lshlrev_b32_e32 v4, 1, v2
	s_cselect_b32 s27, 0, 0
	v_lshl_add_u64 v[34:35], s[6:7], 0, v[0:1]
	s_mov_b64 s[6:7], 0x600
	s_add_i32 s27, s27, s26
	v_lshl_add_u64 v[2:3], v[34:35], 0, s[6:7]
	s_mov_b32 s6, m0
	s_mov_b32 m0, s27
	s_nop 0
	global_load_lds_dwordx4 v[2:3], off
	s_mov_b32 m0, s6
	v_mov_b32_e32 v0, v4
	s_add_i32 s26, s27, 0x6000
	v_lshl_add_u64 v[2:3], s[4:5], 0, v[0:1]
	s_mov_b32 s4, m0
	s_mov_b32 m0, s26
	s_nop 0
	global_load_lds_dwordx4 v[2:3], off
	s_mov_b32 m0, s4
	v_lshl_add_u64 v[2:3], s[8:9], 0, v[0:1]
	s_add_i32 s4, s27, 0x8000
	s_mov_b32 s5, m0
	s_mov_b32 m0, s4
	s_nop 0
	global_load_lds_dwordx4 v[2:3], off
	s_mov_b32 m0, s5
	s_mov_b64 s[4:5], 0x48600
	v_and_b32_e32 v212, 31, v213
	v_lshl_add_u64 v[2:3], v[34:35], 0, s[4:5]
	s_add_i32 s4, s27, 0x2000
	s_mov_b32 s5, m0
	s_mov_b32 m0, s4
	s_nop 0
	global_load_lds_dwordx4 v[2:3], off
	s_mov_b32 m0, s5
	v_mul_u32_u24_e32 v2, 0x900, v212
	v_bfe_u32 v38, v213, 5, 1
	v_lshlrev_b32_e32 v2, 1, v2
	v_lshl_or_b32 v2, v38, 4, v2
	global_load_dwordx4 v[174:177], v2, s[40:41] offset:512
	global_load_dwordx4 v[170:173], v2, s[40:41] offset:544
	global_load_dwordx4 v[166:169], v2, s[40:41] offset:576
	global_load_dwordx4 v[162:165], v2, s[40:41] offset:608
	v_lshlrev_b32_e32 v214, 10, v38
	v_lshlrev_b32_e32 v3, 4, v212
	v_add_u32_e32 v2, 0, v214
	v_add_u32_e32 v234, v2, v3
	v_mov_b32_e32 v2, v1
	v_mov_b32_e32 v3, v1
	v_mov_b32_e32 v4, v1
	v_mov_b32_e32 v6, v1
	v_mov_b32_e32 v7, v1
	v_mov_b32_e32 v8, v1
	v_mov_b32_e32 v9, v1
	v_mov_b32_e32 v10, v1
	v_mov_b32_e32 v11, v1
	v_mov_b32_e32 v12, v1
	v_mov_b32_e32 v13, v1
	v_mov_b32_e32 v14, v1
	v_mov_b32_e32 v15, v1
	v_mov_b32_e32 v16, v1
	v_mov_b32_e32 v17, v1
	s_mov_b64 s[4:5], 0x90600
	v_lshl_add_u64 v[18:19], v[34:35], 0, s[4:5]
	s_add_i32 s4, s27, 0x4000
	s_mov_b32 s5, m0
	s_mov_b32 m0, s4
	s_nop 0
	global_load_lds_dwordx4 v[18:19], off
	s_mov_b32 m0, s5
	s_waitcnt vmcnt(4) lgkmcnt(0)
	s_barrier
; #define WAIT_BAR(N) asm volatile("s_waitcnt vmcnt(" #N ") lgkmcnt(0)\n\ts_barrier":::"memory")
;   #define DMA_K(t,slot) glds16(ksrc+(long)(t)*KVBLK*PQ,(unsigned)__builtin_amdgcn_readfirstlane(kdst+(slot)))
;   #define DMA_V(t,slot) glds16(vsrc+(long)(t)*KVBLK*PQ,(unsigned)__builtin_amdgcn_readfirstlane(vdst+(slot)))
;   #define CMASK(P0,P1,t) do{}while(0)
;   #define START(P0,P1) do{ const float rm=rowmax(P0,P1); resc=false; \
;     { const float dl=rm; mhat=fadd_s(mhat,dl); \
;       _Pragma("unroll") for(int r=0;r<16;++r){P0[r]=fsub_s(P0[r],dl);P1[r]=fsub_s(P1[r],dl);} \
;       _Pragma("unroll") for(int r=0;r<16;++r)negm[r]=-mhat; asm volatile("":"+v"(negm)); } \
;     _Pragma("unroll") for(int r=0;r<16;++r)P0[r]=__builtin_amdgcn_exp2f(P0[r]); }while(0)
;   #define ROT() do{sl_prev=sl_cur;sl_cur=sl_next;sl_next=(sl_next==(NSLOT-1)*SLOTB)?0:sl_next+SLOTB;}while(0)
;   #define CMASK(P0,P1,t) do{}while(0)
;   #define CMASK(P0,P1,t) do{}while(0)
;   #define DMA_K(t,slot) glds16((const char*)Kh+(size_t)(t)*(KVBLK*PQ*2)+koff,(unsigned)__builtin_amdgcn_readfirstlane(kdst+(slot)))
;   #define DMA_V(t,slot) do{ glds16((const char*)Vh+(size_t)(t)*(KVBLK*PQ*2)+voff,(unsigned)__builtin_amdgcn_readfirstlane(vdst+2*(slot))); glds16((const char*)Vh+(size_t)(t)*(KVBLK*PQ*2)+128+voff,(unsigned)__builtin_amdgcn_readfirstlane(vdst+2*(slot)+8192)); }while(0)
;   #define CMASK(P0,P1,t) do{}while(0)
;   #define ROT() do{sl_prev=sl_cur;sl_cur=sl_next;sl_next=(sl_next==(NSLOT-1)*SLOTB)?0:sl_next+SLOTB;}while(0)
;   #define CMASK(P0,P1,t) do{}while(0)
;   #define CMASK(P0,P1,t) do{}while(0)
; template<int THRL,int MODE> __device__ __forceinline__ void attn_unit128(const bf16*Qblk,const bf16*__restrict__ Kh,const bf16*__restrict__ Vh,bf16*Oblk,const int NT,char*shm,const bf16*O1blk,bf16*AOblk,const float lam,const float*sln,const float omli){
;     ...
;   DMA_K(2,2*SLOTB);
;   WAIT_BAR(4);
;   qkt(pA0,pA1,Kbase,qr,negm,r32,hi);asm volatile("s_nop 15\n\ts_nop 7":"+v"(pA0),"+v"(pA1));CMASK(pA0,pA1,0);
;   START(pA0,pA1);
;   _Pragma("unroll") for(int r=0;r<16;++r)pA1[r]=__builtin_amdgcn_exp2f(pA1[r]);
;   WAIT_BAR(0);
;   DMA_K(3,0);DMA_V(1,SLOTB);
;   ROT();
;   kload8(kf,kp0+sl_cur);
;   WAIT_BAR(3);
	ds_read_b128 v[40:43], v234
	ds_read_b128 v[44:47], v234 offset:512
	s_waitcnt vmcnt(3) lgkmcnt(1)
	v_mfma_f32_32x32x16_bf16 v[18:33], v[40:43], v[174:177], v[2:17]
	s_lshl_b32 s4, s31, 2
	s_add_i32 s8, s4, 0
	s_mov_b64 s[4:5], 0xd8600
	v_lshlrev_b32_e32 v37, 1, v213
	v_and_b32_e32 v37, 32, v37
	v_add3_u32 v36, 0, v37, v36
	v_lshlrev_b32_e32 v37, 8, v38
	s_waitcnt lgkmcnt(0)
	v_mfma_f32_32x32x16_bf16 v[2:17], v[44:47], v[174:177], v[2:17]
	ds_read_b128 v[40:43], v234 offset:2048
	ds_read_b128 v[44:47], v234 offset:2560
	s_add_i32 s8, s8, 0x12000
	v_cmp_gt_u32_e64 s[40:41], 32, v39
	v_lshl_add_u32 v215, v212, 2, s8
	s_waitcnt vmcnt(2) lgkmcnt(1)
	v_mfma_f32_32x32x16_bf16 v[18:33], v[40:43], v[170:173], v[18:33]
	s_waitcnt lgkmcnt(0)
	v_mfma_f32_32x32x16_bf16 v[2:17], v[44:47], v[170:173], v[2:17]
	ds_read_b128 v[40:43], v234 offset:4096
	ds_read_b128 v[44:47], v234 offset:4608
	s_waitcnt vmcnt(1) lgkmcnt(1)
	v_mfma_f32_32x32x16_bf16 v[18:33], v[40:43], v[166:169], v[18:33]
	s_waitcnt lgkmcnt(0)
	v_mfma_f32_32x32x16_bf16 v[2:17], v[44:47], v[166:169], v[2:17]
	ds_read_b128 v[40:43], v234 offset:6144
	ds_read_b128 v[44:47], v234 offset:6656
	s_waitcnt vmcnt(0) lgkmcnt(1)
	v_mfma_f32_32x32x16_bf16 v[18:33], v[40:43], v[162:165], v[18:33]
	v_lshlrev_b32_e32 v40, 4, v213
	v_and_b32_e32 v40, 0xc0, v40
	v_add3_u32 v217, v36, v37, v40
	s_waitcnt lgkmcnt(0)
	v_mfma_f32_32x32x16_bf16 v[2:17], v[44:47], v[162:165], v[2:17]
	s_nop 15
	s_nop 7
	s_nop 0
	v_max3_f32 v41, v18, v19, v2
	v_max3_f32 v42, v20, v21, v3
	s_nop 0
	v_max3_f32 v41, v41, v4, v5
	v_max3_f32 v42, v42, v24, v25
	s_nop 0
	v_max3_f32 v41, v41, v22, v23
	v_max3_f32 v42, v42, v8, v9
	s_nop 0
	v_max3_f32 v41, v41, v6, v7
	v_max3_f32 v42, v42, v28, v29
	s_nop 0
	v_max3_f32 v41, v41, v26, v27
	v_max3_f32 v42, v42, v12, v13
	s_nop 0
	v_max3_f32 v41, v41, v10, v11
	v_max3_f32 v42, v42, v32, v33
	s_nop 0
	v_max3_f32 v41, v41, v30, v31
	v_max3_f32 v42, v42, v16, v17
	s_nop 0
	v_max3_f32 v41, v41, v14, v15
	s_nop 0
	v_max_f32_e32 v41, v41, v42
	s_nop 0
	v_mov_b32_e32 v42, v41
	s_nop 1
	v_permlane32_swap_b32_e32 v41, v42
	v_max_f32_e32 v41, v41, v42
	s_nop 0
	v_add_f32_e32 v233, v1, v41
	v_sub_f32_e32 v42, v2, v41
	v_sub_f32_e32 v18, v18, v41
	v_sub_f32_e32 v19, v19, v41
	v_sub_f32_e32 v43, v3, v41
	v_sub_f32_e32 v20, v20, v41
	s_nop 0
	v_xor_b32_e32 v2, 0x80000000, v233
	v_sub_f32_e32 v44, v4, v41
	v_sub_f32_e32 v21, v21, v41
	v_sub_f32_e32 v45, v5, v41
	v_sub_f32_e32 v22, v22, v41
	v_sub_f32_e32 v46, v6, v41
	v_sub_f32_e32 v23, v23, v41
	v_sub_f32_e32 v47, v7, v41
	v_sub_f32_e32 v24, v24, v41
	v_sub_f32_e32 v48, v8, v41
	v_sub_f32_e32 v25, v25, v41
	v_sub_f32_e32 v49, v9, v41
	v_sub_f32_e32 v26, v26, v41
	v_sub_f32_e32 v50, v10, v41
	v_sub_f32_e32 v27, v27, v41
	v_sub_f32_e32 v51, v11, v41
	v_sub_f32_e32 v28, v28, v41
	v_sub_f32_e32 v52, v12, v41
	v_sub_f32_e32 v29, v29, v41
	v_sub_f32_e32 v53, v13, v41
	v_sub_f32_e32 v30, v30, v41
	v_sub_f32_e32 v54, v14, v41
	v_sub_f32_e32 v31, v31, v41
	v_sub_f32_e32 v55, v15, v41
	v_sub_f32_e32 v32, v32, v41
	v_sub_f32_e32 v56, v16, v41
	v_sub_f32_e32 v33, v33, v41
	v_sub_f32_e32 v41, v17, v41
	v_mov_b32_e32 v3, v2
	v_mov_b32_e32 v4, v2
	v_mov_b32_e32 v5, v2
	v_mov_b32_e32 v6, v2
	v_mov_b32_e32 v7, v2
	v_mov_b32_e32 v8, v2
	v_mov_b32_e32 v9, v2
	v_mov_b32_e32 v10, v2
	v_mov_b32_e32 v11, v2
	v_mov_b32_e32 v12, v2
	v_mov_b32_e32 v13, v2
	v_mov_b32_e32 v14, v2
	v_mov_b32_e32 v15, v2
	v_mov_b32_e32 v16, v2
	v_mov_b32_e32 v17, v2
	s_waitcnt vmcnt(0) lgkmcnt(0)
	s_barrier
	v_exp_f32_e32 v57, v18
	v_exp_f32_e32 v58, v19
	v_lshl_add_u64 v[18:19], v[34:35], 0, s[4:5]
	s_mov_b32 s4, m0
	s_mov_b32 m0, s27
	s_nop 0
	global_load_lds_dwordx4 v[18:19], off
	s_mov_b32 m0, s4
	v_lshl_add_u64 v[18:19], s[10:11], 0, v[0:1]
	s_add_i32 s4, s27, 0xa000
	s_mov_b32 s5, m0
	s_mov_b32 m0, s4
	s_nop 0
	global_load_lds_dwordx4 v[18:19], off
	s_mov_b32 m0, s5
	v_lshl_add_u64 v[18:19], s[16:17], 0, v[0:1]
	s_add_i32 s4, s27, 0xc000
	s_mov_b32 s5, m0
	s_mov_b32 m0, s4
	s_nop 0
	global_load_lds_dwordx4 v[18:19], off
	s_mov_b32 m0, s5
	v_exp_f32_e32 v59, v20
	v_exp_f32_e32 v60, v21
	v_exp_f32_e32 v61, v22
	v_exp_f32_e32 v62, v23
	v_exp_f32_e32 v63, v24
	v_exp_f32_e32 v64, v25
	v_exp_f32_e32 v65, v26
	v_exp_f32_e32 v66, v27
	v_exp_f32_e32 v67, v28
	v_exp_f32_e32 v68, v29
	v_exp_f32_e32 v69, v30
	v_exp_f32_e32 v70, v31
	v_exp_f32_e32 v71, v32
	v_exp_f32_e32 v72, v33
	v_exp_f32_e32 v73, v42
	v_exp_f32_e32 v74, v43
	v_exp_f32_e32 v75, v44
	v_exp_f32_e32 v76, v45
	v_exp_f32_e32 v77, v46
	v_exp_f32_e32 v78, v47
	v_exp_f32_e32 v79, v48
	v_exp_f32_e32 v80, v49
	v_exp_f32_e32 v81, v50
	v_exp_f32_e32 v82, v51
	v_exp_f32_e32 v83, v41
	ds_read_b128 v[18:21], v234 offset:8192
	ds_read_b128 v[22:25], v234 offset:8704
	ds_read_b128 v[26:29], v234 offset:10240
	ds_read_b128 v[30:33], v234 offset:10752
	ds_read_b128 v[34:37], v234 offset:12288
	ds_read_b128 v[40:43], v234 offset:12800
	ds_read_b128 v[44:47], v234 offset:14336
	ds_read_b128 v[48:51], v234 offset:14848
	v_exp_f32_e32 v52, v52
	v_exp_f32_e32 v53, v53
	v_exp_f32_e32 v54, v54
	v_exp_f32_e32 v55, v55
	v_exp_f32_e32 v56, v56
	s_waitcnt vmcnt(3) lgkmcnt(0)
	s_barrier
	s_waitcnt lgkmcnt(7)
	v_mfma_f32_32x32x16_bf16 v[130:145], v[18:21], v[174:177], v[2:17]
	v_add_f32_e32 v39, v57, v58
	v_add_f32_e32 v39, v39, v59
	v_add_f32_e32 v39, v39, v60
	v_add_f32_e32 v39, v39, v61
	v_add_f32_e32 v39, v39, v62
	v_cvt_pk_bf16_f32 v146, v57, v58
	v_cvt_pk_bf16_f32 v147, v59, v60
	s_waitcnt lgkmcnt(6)
	v_mfma_f32_32x32x16_bf16 v[98:113], v[22:25], v[174:177], v[2:17]
	v_add_f32_e32 v18, v63, v39
	v_add_f32_e32 v18, v64, v18
	v_add_f32_e32 v18, v65, v18
	v_add_f32_e32 v18, v66, v18
	v_cvt_pk_bf16_f32 v148, v61, v62
	v_cvt_pk_bf16_f32 v149, v63, v64
	s_waitcnt lgkmcnt(5)
	v_mfma_f32_32x32x16_bf16 v[130:145], v[26:29], v[170:173], v[130:145]
	v_add_f32_e32 v18, v67, v18
	v_add_f32_e32 v18, v68, v18
	v_add_f32_e32 v18, v69, v18
	v_add_f32_e32 v18, v70, v18
	v_cvt_pk_bf16_f32 v150, v65, v66
	v_cvt_pk_bf16_f32 v151, v67, v68
	s_waitcnt lgkmcnt(4)
	v_mfma_f32_32x32x16_bf16 v[98:113], v[30:33], v[170:173], v[98:113]
	v_add_f32_e32 v18, v71, v18
	v_add_f32_e32 v18, v72, v18
	v_add_f32_e32 v18, v73, v18
	v_add_f32_e32 v18, v74, v18
	v_cvt_pk_bf16_f32 v152, v69, v70
	v_cvt_pk_bf16_f32 v153, v71, v72
	s_waitcnt lgkmcnt(3)
	v_mfma_f32_32x32x16_bf16 v[130:145], v[34:37], v[166:169], v[130:145]
	v_add_f32_e32 v18, v75, v18
	v_add_f32_e32 v18, v76, v18
	v_add_f32_e32 v18, v77, v18
	v_add_f32_e32 v18, v78, v18
	v_cvt_pk_bf16_f32 v154, v73, v74
	v_cvt_pk_bf16_f32 v155, v75, v76
	s_waitcnt lgkmcnt(2)
	v_mfma_f32_32x32x16_bf16 v[98:113], v[40:43], v[166:169], v[98:113]
	v_add_f32_e32 v18, v79, v18
	v_add_f32_e32 v18, v80, v18
	v_add_f32_e32 v18, v81, v18
	v_add_f32_e32 v18, v82, v18
	v_cvt_pk_bf16_f32 v156, v77, v78
	v_cvt_pk_bf16_f32 v157, v79, v80
	s_waitcnt lgkmcnt(1)
	v_mfma_f32_32x32x16_bf16 v[130:145], v[44:47], v[162:165], v[130:145]
	v_add_f32_e32 v18, v52, v18
	v_add_f32_e32 v18, v53, v18
	v_add_f32_e32 v18, v54, v18
	v_add_f32_e32 v18, v55, v18
	v_cvt_pk_bf16_f32 v158, v81, v82
	v_cvt_pk_bf16_f32 v159, v52, v53
	s_waitcnt lgkmcnt(0)
	v_mfma_f32_32x32x16_bf16 v[98:113], v[48:51], v[162:165], v[98:113]
	v_add_f32_e32 v18, v56, v18
	v_add_f32_e32 v18, v83, v18
	v_add_f32_e32 v18, 0, v18
	v_cvt_pk_bf16_f32 v160, v54, v55
	v_cvt_pk_bf16_f32 v161, v56, v83
	s_nop 0
	v_add_f32_e32 v235, 0, v18
	ds_read_b64_tr_b16 v[18:19], v217 offset:24576
	ds_read_b64_tr_b16 v[20:21], v217 offset:25088
	ds_read_b64_tr_b16 v[34:35], v217 offset:28672
	ds_read_b64_tr_b16 v[36:37], v217 offset:29184
	ds_read_b64_tr_b16 v[70:71], v217 offset:25600
	ds_read_b64_tr_b16 v[72:73], v217 offset:26112
	ds_read_b64_tr_b16 v[66:67], v217 offset:29696
	ds_read_b64_tr_b16 v[68:69], v217 offset:30208
	ds_read_b64_tr_b16 v[62:63], v217 offset:26624
	ds_read_b64_tr_b16 v[64:65], v217 offset:27136
	ds_read_b64_tr_b16 v[54:55], v217 offset:27648
	ds_read_b64_tr_b16 v[56:57], v217 offset:28160
	ds_read_b64_tr_b16 v[58:59], v217 offset:30720
	ds_read_b64_tr_b16 v[60:61], v217 offset:31232
	ds_read_b64_tr_b16 v[50:51], v217 offset:31744
	ds_read_b64_tr_b16 v[52:53], v217 offset:32256
	v_lshl_add_u64 v[22:23], s[18:19], 0, v[0:1]
	s_add_i32 s4, s27, 0xe000
	s_mov_b32 s5, m0
	s_mov_b32 m0, s4
	s_nop 0
	global_load_lds_dwordx4 v[22:23], off
	s_mov_b32 m0, s5
	v_lshl_add_u64 v[22:23], s[20:21], 0, v[0:1]
	s_add_i32 s4, s27, 0x10000
	s_mov_b32 s5, m0
	s_mov_b32 m0, s4
	s_nop 0
	global_load_lds_dwordx4 v[22:23], off
	s_mov_b32 m0, s5
	v_max_f32_e32 v22, v131, v131
	v_max_f32_e32 v23, v130, v130
	v_max_f32_e32 v22, v23, v22
	v_max3_f32 v23, v132, v133, v99
	v_max3_f32 v22, v22, v98, v100
	v_max3_f32 v22, v22, v101, v134
	v_max3_f32 v23, v23, v136, v137
	v_max3_f32 v22, v22, v135, v102
	v_max3_f32 v23, v23, v104, v105
	v_max3_f32 v22, v22, v103, v138
	v_max3_f32 v23, v23, v140, v141
	v_max3_f32 v22, v22, v139, v106
	v_max3_f32 v23, v23, v108, v109
	v_max3_f32 v22, v22, v107, v142
	v_max3_f32 v23, v23, v144, v145
	v_max3_f32 v22, v22, v143, v110
	v_max3_f32 v23, v23, v112, v113
	v_max3_f32 v22, v22, v111, v23
	v_mov_b32_e32 v23, v22
	s_nop 1
	v_permlane32_swap_b32_e32 v22, v23
	v_max_f32_e32 v23, v23, v23
	v_max_f32_e32 v22, v22, v22
	v_max_f32_e32 v22, v22, v23
	v_cmp_lt_f32_e32 vcc, s15, v22
	s_cbranch_vccnz .LBB0_615
	s_mov_b64 s[4:5], 0

.LBB0_530:
	s_waitcnt lgkmcnt(7)
	v_mfma_f32_32x32x16_bf16 v[114:129], v[82:85], v[174:177], v[2:17]
	v_add_f32_e32 v86, v130, v131
	v_add_f32_e32 v86, v132, v86
	v_add_f32_e32 v86, v133, v86
	v_add_f32_e32 v86, v134, v86
	v_add_f32_e32 v86, v135, v86
	v_cvt_pk_bf16_f32 v146, v130, v131
	v_cvt_pk_bf16_f32 v147, v132, v133
	s_nop 0
	v_add_f32_e32 v82, v136, v86
	v_add_f32_e32 v82, v137, v82
	v_add_f32_e32 v82, v138, v82
	v_add_f32_e32 v130, v139, v82
	s_waitcnt lgkmcnt(6)
	v_mfma_f32_32x32x16_bf16 v[82:97], v[198:201], v[174:177], v[2:17]
	v_cvt_pk_bf16_f32 v148, v134, v135
	v_cvt_pk_bf16_f32 v149, v136, v137
	s_waitcnt lgkmcnt(5)
	v_mfma_f32_32x32x16_bf16 v[114:129], v[202:205], v[170:173], v[114:129]
	v_add_f32_e32 v130, v140, v130
	v_add_f32_e32 v130, v141, v130
	v_add_f32_e32 v130, v142, v130
	v_add_f32_e32 v130, v143, v130
	v_cvt_pk_bf16_f32 v150, v138, v139
	v_cvt_pk_bf16_f32 v151, v140, v141
	s_waitcnt lgkmcnt(4)
	v_mfma_f32_32x32x16_bf16 v[82:97], v[194:197], v[170:173], v[82:97]
	v_add_f32_e32 v130, v144, v130
	v_add_f32_e32 v130, v145, v130
	v_add_f32_e32 v130, v98, v130
	v_add_f32_e32 v130, v99, v130
	v_cvt_pk_bf16_f32 v152, v142, v143
	v_cvt_pk_bf16_f32 v153, v144, v145
	s_waitcnt lgkmcnt(3)
	v_mfma_f32_32x32x16_bf16 v[114:129], v[190:193], v[166:169], v[114:129]
	v_add_f32_e32 v130, v100, v130
	v_add_f32_e32 v130, v101, v130
	v_add_f32_e32 v130, v102, v130
	v_add_f32_e32 v130, v103, v130
	v_cvt_pk_bf16_f32 v154, v98, v99
	v_cvt_pk_bf16_f32 v155, v100, v101
	s_waitcnt lgkmcnt(2)
	v_mfma_f32_32x32x16_bf16 v[82:97], v[186:189], v[166:169], v[82:97]
	v_add_f32_e32 v98, v104, v130
	v_add_f32_e32 v98, v105, v98
	v_add_f32_e32 v98, v106, v98
	v_add_f32_e32 v98, v107, v98
	v_cvt_pk_bf16_f32 v156, v102, v103
	v_cvt_pk_bf16_f32 v157, v104, v105
	s_waitcnt lgkmcnt(1)
	v_mfma_f32_32x32x16_bf16 v[114:129], v[182:185], v[162:165], v[114:129]
	v_add_f32_e32 v98, v108, v98
	v_add_f32_e32 v98, v109, v98
	v_add_f32_e32 v98, v110, v98
	v_add_f32_e32 v98, v111, v98
	v_cvt_pk_bf16_f32 v158, v106, v107
	v_cvt_pk_bf16_f32 v159, v108, v109
	s_waitcnt lgkmcnt(0)
	v_mfma_f32_32x32x16_bf16 v[82:97], v[178:181], v[162:165], v[82:97]
	v_add_f32_e32 v98, v112, v98
	v_add_f32_e32 v98, v113, v98
	v_add_f32_e32 v98, 0, v98
	v_cvt_pk_bf16_f32 v160, v110, v111
	v_cvt_pk_bf16_f32 v161, v112, v113
	ds_read_b64_tr_b16 v[142:143], v217 offset:40960
	ds_read_b64_tr_b16 v[144:145], v217 offset:41472
	ds_read_b64_tr_b16 v[138:139], v217 offset:45056
	ds_read_b64_tr_b16 v[140:141], v217 offset:45568
	ds_read_b64_tr_b16 v[134:135], v217 offset:41984
	ds_read_b64_tr_b16 v[136:137], v217 offset:42496
	ds_read_b64_tr_b16 v[130:131], v217 offset:46080
	ds_read_b64_tr_b16 v[132:133], v217 offset:46592
	v_add_f32_e32 v194, v235, v98
	ds_read_b64_tr_b16 v[110:111], v217 offset:43008
	ds_read_b64_tr_b16 v[112:113], v217 offset:43520
	ds_read_b64_tr_b16 v[102:103], v217 offset:44032
	ds_read_b64_tr_b16 v[104:105], v217 offset:44544
	ds_read_b64_tr_b16 v[106:107], v217 offset:47104
	ds_read_b64_tr_b16 v[108:109], v217 offset:47616
	ds_read_b64_tr_b16 v[98:99], v217 offset:48128
	ds_read_b64_tr_b16 v[100:101], v217 offset:48640
	v_lshl_add_u64 v[178:179], s[22:23], 0, v[0:1]
	s_mov_b32 s4, m0
	s_mov_b32 m0, s26
	s_nop 0
	global_load_lds_dwordx4 v[178:179], off
	s_mov_b32 m0, s4
	v_lshl_add_u64 v[178:179], s[24:25], 0, v[0:1]
	s_add_i32 s4, s26, 0x2000
	s_mov_b32 s5, m0
	s_mov_b32 m0, s4
	s_nop 0
	global_load_lds_dwordx4 v[178:179], off
	s_mov_b32 m0, s5
	v_max_f32_e32 v0, v115, v115
	v_max_f32_e32 v178, v114, v114
	v_max_f32_e32 v0, v178, v0
	v_max3_f32 v178, v116, v117, v83
	v_max3_f32 v0, v0, v82, v84
	v_max3_f32 v0, v0, v85, v118
	v_max3_f32 v178, v178, v120, v121
	v_max3_f32 v0, v0, v119, v86
	v_max3_f32 v178, v178, v88, v89
	v_max3_f32 v0, v0, v87, v122
	v_max3_f32 v178, v178, v124, v125
	v_max3_f32 v0, v0, v123, v90
	v_max3_f32 v178, v178, v92, v93
	v_max3_f32 v0, v0, v91, v126
	v_max3_f32 v178, v178, v128, v129
	v_max3_f32 v0, v0, v127, v94
	v_max3_f32 v178, v178, v96, v97
	v_max3_f32 v0, v0, v95, v178
	v_mov_b32_e32 v178, v0
	s_nop 1
	v_permlane32_swap_b32_e32 v0, v178
	v_max_f32_e32 v178, v178, v178
	v_max_f32_e32 v0, v0, v0
	v_max_f32_e32 v0, v0, v178
	v_cmp_lt_f32_e32 vcc, s15, v0
	s_cbranch_vccnz .LBB0_618
	s_mov_b64 s[4:5], 0

.LBB0_541:
	v_mfma_f32_32x32x16_bf16 v[130:145], v[114:117], v[190:193], v[66:81]
	v_add_f32_e32 v118, v98, v99
	v_add_f32_e32 v118, v100, v118
	v_add_f32_e32 v118, v101, v118
	s_lshl_b32 s18, s18, 1
	v_add_f32_e32 v118, v102, v118
	v_add_u32_e32 v243, s18, v238
	v_add_f32_e32 v114, v103, v118
	v_cvt_pk_bf16_f32 v174, v98, v99
	v_cvt_pk_bf16_f32 v175, v100, v101
	s_nop 0
	v_add_f32_e32 v98, v104, v114
	v_mfma_f32_32x32x16_bf16 v[114:129], v[198:201], v[190:193], v[66:81]
	v_add_f32_e32 v98, v105, v98
	v_add_f32_e32 v98, v106, v98
	v_add_f32_e32 v98, v107, v98
	v_cvt_pk_bf16_f32 v176, v102, v103
	v_cvt_pk_bf16_f32 v177, v104, v105
	v_mfma_f32_32x32x16_bf16 v[130:145], v[202:205], v[186:189], v[130:145]
	v_add_f32_e32 v98, v108, v98
	v_add_f32_e32 v98, v109, v98
	v_add_f32_e32 v98, v110, v98
	v_add_f32_e32 v98, v111, v98
	v_cvt_pk_bf16_f32 v170, v106, v107
	v_cvt_pk_bf16_f32 v171, v108, v109
	v_mfma_f32_32x32x16_bf16 v[114:129], v[194:197], v[186:189], v[114:129]
	v_add_f32_e32 v98, v112, v98
	v_add_f32_e32 v98, v113, v98
	v_add_f32_e32 v98, v82, v98
	v_add_f32_e32 v98, v83, v98
	v_cvt_pk_bf16_f32 v172, v110, v111
	v_cvt_pk_bf16_f32 v173, v112, v113
	v_mfma_f32_32x32x16_bf16 v[130:145], v[158:161], v[182:185], v[130:145]
	v_add_f32_e32 v98, v84, v98
	v_add_f32_e32 v98, v85, v98
	v_add_f32_e32 v98, v86, v98
	v_add_f32_e32 v98, v87, v98
	v_cvt_pk_bf16_f32 v166, v82, v83
	v_cvt_pk_bf16_f32 v167, v84, v85
	v_mfma_f32_32x32x16_bf16 v[114:129], v[154:157], v[182:185], v[114:129]
	v_add_f32_e32 v82, v88, v98
	v_add_f32_e32 v82, v89, v82
	v_add_f32_e32 v82, v90, v82
	v_add_f32_e32 v82, v91, v82
	v_cvt_pk_bf16_f32 v168, v86, v87
	v_cvt_pk_bf16_f32 v169, v88, v89
	v_mfma_f32_32x32x16_bf16 v[130:145], v[150:153], v[178:181], v[130:145]
	v_add_f32_e32 v82, v92, v82
	v_add_f32_e32 v82, v93, v82
	v_add_f32_e32 v82, v94, v82
	v_add_f32_e32 v82, v95, v82
	v_cvt_pk_bf16_f32 v162, v90, v91
	v_cvt_pk_bf16_f32 v163, v92, v93
	v_mfma_f32_32x32x16_bf16 v[114:129], v[146:149], v[178:181], v[114:129]
	v_add_f32_e32 v82, v96, v82
	v_add_f32_e32 v82, v97, v82
	v_add_f32_e32 v242, v242, v82
	v_cvt_pk_bf16_f32 v164, v94, v95
	v_cvt_pk_bf16_f32 v165, v96, v97
	ds_read_b64_tr_b16 v[110:111], v243 offset:24576
	ds_read_b64_tr_b16 v[112:113], v243 offset:25088
	ds_read_b64_tr_b16 v[102:103], v243 offset:25600
	ds_read_b64_tr_b16 v[104:105], v243 offset:26112
	ds_read_b64_tr_b16 v[106:107], v243 offset:28672
	ds_read_b64_tr_b16 v[108:109], v243 offset:29184
	ds_read_b64_tr_b16 v[98:99], v243 offset:29696
	ds_read_b64_tr_b16 v[100:101], v243 offset:30208
	ds_read_b64_tr_b16 v[94:95], v243 offset:26624
	ds_read_b64_tr_b16 v[96:97], v243 offset:27136
	ds_read_b64_tr_b16 v[86:87], v243 offset:27648
	ds_read_b64_tr_b16 v[88:89], v243 offset:28160
	ds_read_b64_tr_b16 v[90:91], v243 offset:30720
	ds_read_b64_tr_b16 v[92:93], v243 offset:31232
	ds_read_b64_tr_b16 v[82:83], v243 offset:31744
	ds_read_b64_tr_b16 v[84:85], v243 offset:32256
	v_subrev_u32_e32 v216, s100, v212
	s_lshl_b32 s45, s33, 1
	v_max3_f32 v146, v130, v131, v132
	v_max3_f32 v147, v133, v134, v135
	v_max3_f32 v146, v146, v136, v137
	v_max3_f32 v147, v147, v138, v139
	v_max3_f32 v146, v146, v140, v141
	v_max3_f32 v147, v147, v142, v143
	v_max3_f32 v146, v146, v144, v145
	v_max3_f32 v147, v147, v114, v115
	v_max3_f32 v146, v146, v116, v117
	v_max3_f32 v147, v147, v118, v119
	v_max3_f32 v146, v146, v120, v121
	v_max3_f32 v147, v147, v122, v123
	v_max3_f32 v146, v146, v124, v125
	v_max3_f32 v147, v147, v126, v127
	v_max3_f32 v146, v146, v128, v129
	v_max_f32_e32 v146, v146, v147
	v_mov_b32_e32 v147, v146
	s_nop 1
	v_permlane32_swap_b32_e32 v146, v147
	v_max_f32_e32 v146, v146, v147
	v_cmp_lt_f32_e32 vcc, s15, v146
	s_cbranch_vccnz .LBB0_549
	s_mov_b64 s[18:19], 0

.LBB0_544:
	s_add_i32 s18, s33, 0x2000
	s_cmpk_lg_i32 s33, 0x4000
	s_cselect_b32 s46, s18, 0
	v_mfma_f32_32x32x16_bf16 v[98:113], v[82:85], v[190:193], v[66:81]
	v_add_f32_e32 v86, v130, v131
	v_add_f32_e32 v86, v132, v86
	v_add_f32_e32 v86, v133, v86
	s_lshl_b32 s18, s43, 1
	v_add_f32_e32 v86, v134, v86
	v_add_u32_e32 v243, s18, v238
	v_add_f32_e32 v82, v135, v86
	v_cvt_pk_bf16_f32 v174, v130, v131
	v_cvt_pk_bf16_f32 v175, v132, v133
	s_nop 0
	v_add_f32_e32 v82, v136, v82
	v_add_f32_e32 v82, v137, v82
	v_add_f32_e32 v82, v138, v82
	v_add_f32_e32 v130, v139, v82
	v_mfma_f32_32x32x16_bf16 v[82:97], v[198:201], v[190:193], v[66:81]
	v_cvt_pk_bf16_f32 v176, v134, v135
	v_cvt_pk_bf16_f32 v177, v136, v137
	v_mfma_f32_32x32x16_bf16 v[98:113], v[202:205], v[186:189], v[98:113]
	v_add_f32_e32 v130, v140, v130
	v_add_f32_e32 v130, v141, v130
	v_add_f32_e32 v130, v142, v130
	v_add_f32_e32 v130, v143, v130
	v_cvt_pk_bf16_f32 v170, v138, v139
	v_cvt_pk_bf16_f32 v171, v140, v141
	v_mfma_f32_32x32x16_bf16 v[82:97], v[194:197], v[186:189], v[82:97]
	v_add_f32_e32 v130, v144, v130
	v_add_f32_e32 v130, v145, v130
	v_add_f32_e32 v130, v114, v130
	v_add_f32_e32 v130, v115, v130
	v_cvt_pk_bf16_f32 v172, v142, v143
	v_cvt_pk_bf16_f32 v173, v144, v145
	v_mfma_f32_32x32x16_bf16 v[98:113], v[158:161], v[182:185], v[98:113]
	v_add_f32_e32 v130, v116, v130
	v_add_f32_e32 v130, v117, v130
	v_add_f32_e32 v130, v118, v130
	v_add_f32_e32 v130, v119, v130
	v_cvt_pk_bf16_f32 v166, v114, v115
	v_cvt_pk_bf16_f32 v167, v116, v117
	v_mfma_f32_32x32x16_bf16 v[82:97], v[154:157], v[182:185], v[82:97]
	v_add_f32_e32 v114, v120, v130
	v_add_f32_e32 v114, v121, v114
	v_add_f32_e32 v114, v122, v114
	v_add_f32_e32 v114, v123, v114
	v_cvt_pk_bf16_f32 v168, v118, v119
	v_cvt_pk_bf16_f32 v169, v120, v121
	v_mfma_f32_32x32x16_bf16 v[98:113], v[150:153], v[178:181], v[98:113]
	v_add_f32_e32 v114, v124, v114
	v_add_f32_e32 v114, v125, v114
	v_add_f32_e32 v114, v126, v114
	v_add_f32_e32 v114, v127, v114
	v_cvt_pk_bf16_f32 v162, v122, v123
	v_cvt_pk_bf16_f32 v163, v124, v125
	v_mfma_f32_32x32x16_bf16 v[82:97], v[146:149], v[178:181], v[82:97]
	v_add_f32_e32 v114, v128, v114
	v_add_f32_e32 v114, v129, v114
	v_add_f32_e32 v242, v242, v114
	v_cvt_pk_bf16_f32 v164, v126, v127
	v_cvt_pk_bf16_f32 v165, v128, v129
	ds_read_b64_tr_b16 v[142:143], v243 offset:24576
	ds_read_b64_tr_b16 v[144:145], v243 offset:25088
	ds_read_b64_tr_b16 v[134:135], v243 offset:25600
	ds_read_b64_tr_b16 v[136:137], v243 offset:26112
	ds_read_b64_tr_b16 v[138:139], v243 offset:28672
	ds_read_b64_tr_b16 v[140:141], v243 offset:29184
	ds_read_b64_tr_b16 v[130:131], v243 offset:29696
	ds_read_b64_tr_b16 v[132:133], v243 offset:30208
	ds_read_b64_tr_b16 v[126:127], v243 offset:26624
	ds_read_b64_tr_b16 v[128:129], v243 offset:27136
	ds_read_b64_tr_b16 v[118:119], v243 offset:27648
	ds_read_b64_tr_b16 v[120:121], v243 offset:28160
	ds_read_b64_tr_b16 v[122:123], v243 offset:30720
	ds_read_b64_tr_b16 v[124:125], v243 offset:31232
	ds_read_b64_tr_b16 v[114:115], v243 offset:31744
	ds_read_b64_tr_b16 v[116:117], v243 offset:32256
	s_add_u32 s18, s100, s16
	s_addc_u32 s19, s101, s17
	s_add_u32 s18, s18, 0x168000
	s_addc_u32 s19, s19, 0
	s_add_i32 m0, s33, s22
	s_nop 0
	global_load_lds_dwordx4 v216, s[18:19]
	s_lshl_b32 s43, s46, 1
	v_max3_f32 v146, v98, v99, v100
	v_max3_f32 v147, v101, v102, v103
	v_max3_f32 v146, v146, v104, v105
	v_max3_f32 v147, v147, v106, v107
	v_max3_f32 v146, v146, v108, v109
	v_max3_f32 v147, v147, v110, v111
	v_max3_f32 v146, v146, v112, v113
	v_max3_f32 v147, v147, v82, v83
	v_max3_f32 v146, v146, v84, v85
	v_max3_f32 v147, v147, v86, v87
	v_max3_f32 v146, v146, v88, v89
	v_max3_f32 v147, v147, v90, v91
	v_max3_f32 v146, v146, v92, v93
	v_max3_f32 v147, v147, v94, v95
	v_max3_f32 v146, v146, v96, v97
	v_max_f32_e32 v146, v146, v147
	v_mov_b32_e32 v147, v146
	s_nop 1
	v_permlane32_swap_b32_e32 v146, v147
	v_max_f32_e32 v146, v146, v147
	v_cmp_lt_f32_e32 vcc, s15, v146
	s_cbranch_vccnz .LBB0_552
	s_mov_b64 s[18:19], 0

.LBB0_549:
	v_max_f32_e32 v66, v146, v146
	v_max_f32_e32 v146, 0, v66
	v_exp_f32_e64 v147, -v146
	v_add_f32_e32 v239, v239, v146
	v_xor_b32_e32 v66, 0x80000000, v239
	v_mov_b32_e32 v67, v66
	v_mov_b32_e32 v68, v66
	v_mov_b32_e32 v69, v66
	v_mov_b32_e32 v70, v66
	v_mov_b32_e32 v71, v66
	v_mov_b32_e32 v72, v66
	v_mov_b32_e32 v73, v66
	v_mov_b32_e32 v74, v66
	v_mov_b32_e32 v75, v66
	v_mov_b32_e32 v76, v66
	v_mov_b32_e32 v77, v66
	v_mov_b32_e32 v78, v66
	v_mov_b32_e32 v79, v66
	v_mov_b32_e32 v80, v66
	v_mov_b32_e32 v81, v66
	s_and_saveexec_b64 s[20:21], s[40:41]
	ds_write_b32 v237, v147
	s_or_b64 exec, exec, s[20:21]
	v_sub_f32_e32 v145, v145, v146
	v_sub_f32_e32 v144, v144, v146
	v_sub_f32_e32 v143, v143, v146
	v_sub_f32_e32 v142, v142, v146
	v_sub_f32_e32 v141, v141, v146
	v_sub_f32_e32 v140, v140, v146
	v_sub_f32_e32 v139, v139, v146
	v_sub_f32_e32 v138, v138, v146
	v_sub_f32_e32 v137, v137, v146
	v_sub_f32_e32 v136, v136, v146
	v_sub_f32_e32 v135, v135, v146
	v_sub_f32_e32 v134, v134, v146
	v_sub_f32_e32 v133, v133, v146
	v_sub_f32_e32 v132, v132, v146
	v_sub_f32_e32 v131, v131, v146
	v_sub_f32_e32 v130, v130, v146
	v_sub_f32_e32 v129, v129, v146
	v_sub_f32_e32 v128, v128, v146
	v_sub_f32_e32 v127, v127, v146
	v_sub_f32_e32 v126, v126, v146
	v_sub_f32_e32 v125, v125, v146
	v_sub_f32_e32 v124, v124, v146
	v_sub_f32_e32 v123, v123, v146
	v_sub_f32_e32 v122, v122, v146
	v_sub_f32_e32 v121, v121, v146
	v_sub_f32_e32 v120, v120, v146
	v_sub_f32_e32 v119, v119, v146
	v_sub_f32_e32 v118, v118, v146
	v_sub_f32_e32 v117, v117, v146
	v_sub_f32_e32 v116, v116, v146
	v_sub_f32_e32 v115, v115, v146
	v_sub_f32_e32 v114, v114, v146
	v_mul_f32_e32 v242, v242, v147
	s_mov_b64 s[18:19], -1
	s_branch .LBB0_542
.LBB0_552:
	v_max_f32_e32 v66, v146, v146
	v_max_f32_e32 v146, 0, v66
	v_exp_f32_e64 v147, -v146
	v_add_f32_e32 v239, v239, v146
	v_xor_b32_e32 v66, 0x80000000, v239
	v_mov_b32_e32 v67, v66
	v_mov_b32_e32 v68, v66
	v_mov_b32_e32 v69, v66
	v_mov_b32_e32 v70, v66
	v_mov_b32_e32 v71, v66
	v_mov_b32_e32 v72, v66
	v_mov_b32_e32 v73, v66
	v_mov_b32_e32 v74, v66
	v_mov_b32_e32 v75, v66
	v_mov_b32_e32 v76, v66
	v_mov_b32_e32 v77, v66
	v_mov_b32_e32 v78, v66
	v_mov_b32_e32 v79, v66
	v_mov_b32_e32 v80, v66
	v_mov_b32_e32 v81, v66
	s_and_saveexec_b64 s[20:21], s[40:41]
	ds_write_b32 v237, v147
	s_or_b64 exec, exec, s[20:21]
	v_sub_f32_e32 v113, v113, v146
	v_sub_f32_e32 v112, v112, v146
	v_sub_f32_e32 v111, v111, v146
	v_sub_f32_e32 v110, v110, v146
	v_sub_f32_e32 v109, v109, v146
	v_sub_f32_e32 v108, v108, v146
	v_sub_f32_e32 v107, v107, v146
	v_sub_f32_e32 v106, v106, v146
	v_sub_f32_e32 v105, v105, v146
	v_sub_f32_e32 v104, v104, v146
	v_sub_f32_e32 v103, v103, v146
	v_sub_f32_e32 v102, v102, v146
	v_sub_f32_e32 v101, v101, v146
	v_sub_f32_e32 v100, v100, v146
	v_sub_f32_e32 v99, v99, v146
	v_sub_f32_e32 v98, v98, v146
	v_sub_f32_e32 v97, v97, v146
	v_sub_f32_e32 v96, v96, v146
	v_sub_f32_e32 v95, v95, v146
	v_sub_f32_e32 v94, v94, v146
	v_sub_f32_e32 v93, v93, v146
	v_sub_f32_e32 v92, v92, v146
	v_sub_f32_e32 v91, v91, v146
	v_sub_f32_e32 v90, v90, v146
	v_sub_f32_e32 v89, v89, v146
	v_sub_f32_e32 v88, v88, v146
	v_sub_f32_e32 v87, v87, v146
	v_sub_f32_e32 v86, v86, v146
	v_sub_f32_e32 v85, v85, v146
	v_sub_f32_e32 v84, v84, v146
	v_sub_f32_e32 v83, v83, v146
	v_sub_f32_e32 v82, v82, v146
	v_mul_f32_e32 v242, v242, v147
	s_mov_b64 s[18:19], -1
	s_branch .LBB0_545
.LBB0_555:
	s_waitcnt lgkmcnt(7)
	v_mfma_f32_32x32x16_bf16 v[130:145], v[114:117], v[190:193], v[66:81]
	v_add_f32_e32 v118, v98, v99
	v_add_f32_e32 v118, v100, v118
	v_add_f32_e32 v118, v101, v118
	v_add_f32_e32 v118, v102, v118
	v_add_u32_e32 v214, s45, v238
	v_add_f32_e32 v118, v103, v118
	v_cvt_pk_bf16_f32 v174, v98, v99
	v_cvt_pk_bf16_f32 v175, v100, v101
	s_nop 0
	v_add_f32_e32 v98, v104, v118
	s_waitcnt lgkmcnt(6)
	v_mfma_f32_32x32x16_bf16 v[114:129], v[198:201], v[190:193], v[66:81]
	v_add_f32_e32 v98, v105, v98
	v_add_f32_e32 v98, v106, v98
	v_add_f32_e32 v98, v107, v98
	v_cvt_pk_bf16_f32 v176, v102, v103
	v_cvt_pk_bf16_f32 v177, v104, v105
	s_waitcnt lgkmcnt(5)
	v_mfma_f32_32x32x16_bf16 v[130:145], v[202:205], v[186:189], v[130:145]
	v_add_f32_e32 v98, v108, v98
	v_add_f32_e32 v98, v109, v98
	v_add_f32_e32 v98, v110, v98
	v_add_f32_e32 v98, v111, v98
	v_cvt_pk_bf16_f32 v170, v106, v107
	v_cvt_pk_bf16_f32 v171, v108, v109
	s_waitcnt lgkmcnt(4)
	v_mfma_f32_32x32x16_bf16 v[114:129], v[194:197], v[186:189], v[114:129]
	v_add_f32_e32 v98, v112, v98
	v_add_f32_e32 v98, v113, v98
	v_add_f32_e32 v98, v82, v98
	v_add_f32_e32 v98, v83, v98
	v_cvt_pk_bf16_f32 v172, v110, v111
	v_cvt_pk_bf16_f32 v173, v112, v113
	s_waitcnt lgkmcnt(3)
	v_mfma_f32_32x32x16_bf16 v[130:145], v[158:161], v[182:185], v[130:145]
	v_add_f32_e32 v98, v84, v98
	v_add_f32_e32 v98, v85, v98
	v_add_f32_e32 v98, v86, v98
	v_add_f32_e32 v98, v87, v98
	v_cvt_pk_bf16_f32 v166, v82, v83
	v_cvt_pk_bf16_f32 v167, v84, v85
	s_waitcnt lgkmcnt(2)
	v_mfma_f32_32x32x16_bf16 v[114:129], v[154:157], v[182:185], v[114:129]
	v_add_f32_e32 v82, v88, v98
	v_add_f32_e32 v82, v89, v82
	v_add_f32_e32 v82, v90, v82
	v_add_f32_e32 v82, v91, v82
	v_cvt_pk_bf16_f32 v168, v86, v87
	v_cvt_pk_bf16_f32 v169, v88, v89
	s_waitcnt lgkmcnt(1)
	v_mfma_f32_32x32x16_bf16 v[130:145], v[150:153], v[178:181], v[130:145]
	v_add_f32_e32 v82, v92, v82
	v_add_f32_e32 v82, v93, v82
	v_add_f32_e32 v82, v94, v82
	v_add_f32_e32 v82, v95, v82
	v_cvt_pk_bf16_f32 v162, v90, v91
	v_cvt_pk_bf16_f32 v163, v92, v93
	s_waitcnt lgkmcnt(0)
	v_mfma_f32_32x32x16_bf16 v[114:129], v[146:149], v[178:181], v[114:129]
	v_add_f32_e32 v82, v96, v82
	v_add_f32_e32 v82, v97, v82
	v_add_f32_e32 v82, 0, v82
	v_cvt_pk_bf16_f32 v164, v94, v95
	v_cvt_pk_bf16_f32 v165, v96, v97
	ds_read_b64_tr_b16 v[110:111], v214 offset:24576
	ds_read_b64_tr_b16 v[112:113], v214 offset:25088
	ds_read_b64_tr_b16 v[106:107], v214 offset:28672
	ds_read_b64_tr_b16 v[108:109], v214 offset:29184
	ds_read_b64_tr_b16 v[102:103], v214 offset:25600
	ds_read_b64_tr_b16 v[104:105], v214 offset:26112
	ds_read_b64_tr_b16 v[98:99], v214 offset:29696
	ds_read_b64_tr_b16 v[100:101], v214 offset:30208
	v_add_f32_e32 v215, v242, v82
	ds_read_b64_tr_b16 v[94:95], v214 offset:26624
	ds_read_b64_tr_b16 v[96:97], v214 offset:27136
	ds_read_b64_tr_b16 v[86:87], v214 offset:27648
	ds_read_b64_tr_b16 v[88:89], v214 offset:28160
	ds_read_b64_tr_b16 v[90:91], v214 offset:30720
	ds_read_b64_tr_b16 v[92:93], v214 offset:31232
	ds_read_b64_tr_b16 v[82:83], v214 offset:31744
	ds_read_b64_tr_b16 v[84:85], v214 offset:32256
	s_mov_b64 s[16:17], 0x4890000
	v_lshl_add_u64 v[146:147], v[212:213], 0, s[16:17]
	s_add_i32 s16, s46, s22
	s_add_u32 s52, s36, 0x4800000
	s_addc_u32 s53, s37, 0
	s_lshl_b32 s20, s21, 1
	s_mov_b32 s17, m0
	s_mov_b32 m0, s16
	s_nop 0
	global_load_lds_dwordx4 v[146:147], off
	s_mov_b32 m0, s17
	s_add_i32 s16, s20, s24
	s_add_u32 s74, s36, 0x4800080
	v_lshl_add_u64 v[146:147], s[52:53], 0, v[0:1]
	s_addc_u32 s75, s37, 0
	s_mov_b32 s17, m0
	s_mov_b32 m0, s16
	s_nop 0
	global_load_lds_dwordx4 v[146:147], off
	s_mov_b32 m0, s17
	v_lshl_add_u64 v[146:147], s[74:75], 0, v[0:1]
	s_addk_i32 s16, 0x2000
	s_mov_b32 s17, m0
	s_mov_b32 m0, s16
	s_nop 0
	global_load_lds_dwordx4 v[146:147], off
	s_mov_b32 m0, s17
	v_max_f32_e32 v146, v131, v131
	v_max_f32_e32 v147, v130, v130
	v_max_f32_e32 v146, v147, v146
	v_max3_f32 v147, v132, v133, v115
	v_max3_f32 v146, v146, v114, v116
	v_max3_f32 v146, v146, v117, v134
	v_max3_f32 v147, v147, v136, v137
	v_max3_f32 v146, v146, v135, v118
	v_max3_f32 v147, v147, v120, v121
	v_max3_f32 v146, v146, v119, v138
	v_max3_f32 v147, v147, v140, v141
	v_max3_f32 v146, v146, v139, v122
	v_max3_f32 v147, v147, v124, v125
	v_max3_f32 v146, v146, v123, v142
	v_max3_f32 v147, v147, v144, v145
	v_max3_f32 v146, v146, v143, v126
	v_max3_f32 v147, v147, v128, v129
	v_max3_f32 v146, v146, v127, v147
	v_mov_b32_e32 v147, v146
	s_nop 1
	v_permlane32_swap_b32_e32 v146, v147
	v_max_f32_e32 v147, v147, v147
	v_max_f32_e32 v146, v146, v146
	v_max_f32_e32 v146, v146, v147
	v_cmp_lt_f32_e32 vcc, s15, v146
	s_cbranch_vccnz .LBB0_624
	s_mov_b64 s[16:17], 0

.LBB0_558:
	s_add_i32 s16, s21, 0x2000
	s_cmpk_lg_i32 s21, 0x4000
	s_cselect_b32 s23, s16, 0
	s_waitcnt lgkmcnt(7)
	v_mfma_f32_32x32x16_bf16 v[146:161], v[82:85], v[190:193], v[66:81]
	v_add_f32_e32 v86, v130, v131
	v_add_f32_e32 v86, v132, v86
	v_add_f32_e32 v86, v133, v86
	v_add_f32_e32 v86, v134, v86
	v_add_u32_e32 v216, s43, v238
	v_add_f32_e32 v86, v135, v86
	v_cvt_pk_bf16_f32 v174, v130, v131
	v_cvt_pk_bf16_f32 v175, v132, v133
	s_nop 0
	v_add_f32_e32 v82, v136, v86
	v_add_f32_e32 v82, v137, v82
	v_add_f32_e32 v82, v138, v82
	v_add_f32_e32 v130, v139, v82
	s_waitcnt lgkmcnt(6)
	v_mfma_f32_32x32x16_bf16 v[82:97], v[198:201], v[190:193], v[66:81]
	v_cvt_pk_bf16_f32 v176, v134, v135
	v_cvt_pk_bf16_f32 v177, v136, v137
	s_waitcnt lgkmcnt(5)
	v_mfma_f32_32x32x16_bf16 v[146:161], v[202:205], v[186:189], v[146:161]
	v_add_f32_e32 v130, v140, v130
	v_add_f32_e32 v130, v141, v130
	v_add_f32_e32 v130, v142, v130
	v_add_f32_e32 v130, v143, v130
	v_cvt_pk_bf16_f32 v170, v138, v139
	v_cvt_pk_bf16_f32 v171, v140, v141
	s_waitcnt lgkmcnt(4)
	v_mfma_f32_32x32x16_bf16 v[82:97], v[194:197], v[186:189], v[82:97]
	v_add_f32_e32 v130, v144, v130
	v_add_f32_e32 v130, v145, v130
	v_add_f32_e32 v130, v114, v130
	v_add_f32_e32 v130, v115, v130
	v_cvt_pk_bf16_f32 v172, v142, v143
	v_cvt_pk_bf16_f32 v173, v144, v145
	s_waitcnt lgkmcnt(3)
	v_mfma_f32_32x32x16_bf16 v[146:161], v[110:113], v[182:185], v[146:161]
	v_add_f32_e32 v110, v116, v130
	v_add_f32_e32 v110, v117, v110
	v_add_f32_e32 v110, v118, v110
	v_add_f32_e32 v110, v119, v110
	v_cvt_pk_bf16_f32 v166, v114, v115
	v_cvt_pk_bf16_f32 v167, v116, v117
	s_waitcnt lgkmcnt(2)
	v_mfma_f32_32x32x16_bf16 v[82:97], v[106:109], v[182:185], v[82:97]
	v_add_f32_e32 v106, v120, v110
	v_add_f32_e32 v106, v121, v106
	v_add_f32_e32 v106, v122, v106
	v_add_f32_e32 v106, v123, v106
	v_cvt_pk_bf16_f32 v168, v118, v119
	v_cvt_pk_bf16_f32 v169, v120, v121
	s_waitcnt lgkmcnt(1)
	v_mfma_f32_32x32x16_bf16 v[146:161], v[102:105], v[178:181], v[146:161]
	v_add_f32_e32 v102, v124, v106
	v_add_f32_e32 v102, v125, v102
	v_add_f32_e32 v102, v126, v102
	v_add_f32_e32 v102, v127, v102
	v_cvt_pk_bf16_f32 v162, v122, v123
	v_cvt_pk_bf16_f32 v163, v124, v125
	s_waitcnt lgkmcnt(0)
	v_mfma_f32_32x32x16_bf16 v[82:97], v[98:101], v[178:181], v[82:97]
	v_add_f32_e32 v98, v128, v102
	v_add_f32_e32 v98, v129, v98
	v_add_f32_e32 v98, 0, v98
	v_cvt_pk_bf16_f32 v164, v126, v127
	v_cvt_pk_bf16_f32 v165, v128, v129
	ds_read_b64_tr_b16 v[126:127], v216 offset:24576
	ds_read_b64_tr_b16 v[128:129], v216 offset:25088
	ds_read_b64_tr_b16 v[122:123], v216 offset:28672
	ds_read_b64_tr_b16 v[124:125], v216 offset:29184
	ds_read_b64_tr_b16 v[118:119], v216 offset:25600
	ds_read_b64_tr_b16 v[120:121], v216 offset:26112
	ds_read_b64_tr_b16 v[114:115], v216 offset:29696
	ds_read_b64_tr_b16 v[116:117], v216 offset:30208
	v_add_f32_e32 v215, v215, v98
	ds_read_b64_tr_b16 v[110:111], v216 offset:26624
	ds_read_b64_tr_b16 v[112:113], v216 offset:27136
	ds_read_b64_tr_b16 v[102:103], v216 offset:27648
	ds_read_b64_tr_b16 v[104:105], v216 offset:28160
	ds_read_b64_tr_b16 v[106:107], v216 offset:30720
	ds_read_b64_tr_b16 v[108:109], v216 offset:31232
	ds_read_b64_tr_b16 v[98:99], v216 offset:31744
	ds_read_b64_tr_b16 v[100:101], v216 offset:32256
	s_mov_b64 s[16:17], 0x48d8000
	v_lshl_add_u64 v[130:131], v[212:213], 0, s[16:17]
	s_add_i32 s16, s21, s22
	s_add_u32 s96, s36, 0x4848000
	s_addc_u32 s97, s37, 0
	s_lshl_b32 s25, s23, 1
	s_mov_b32 s17, m0
	s_mov_b32 m0, s16
	s_nop 0
	global_load_lds_dwordx4 v[130:131], off
	s_mov_b32 m0, s17
	s_add_i32 s16, s25, s24
	s_add_u32 s46, s36, 0x4848080
	v_lshl_add_u64 v[130:131], s[96:97], 0, v[0:1]
	s_addc_u32 s47, s37, 0
	s_mov_b32 s17, m0
	s_mov_b32 m0, s16
	s_nop 0
	global_load_lds_dwordx4 v[130:131], off
	s_mov_b32 m0, s17
	v_lshl_add_u64 v[130:131], s[46:47], 0, v[0:1]
	s_addk_i32 s16, 0x2000
	s_mov_b32 s17, m0
	s_mov_b32 m0, s16
	s_nop 0
	global_load_lds_dwordx4 v[130:131], off
	s_mov_b32 m0, s17
	v_max_f32_e32 v130, v147, v147
	v_max_f32_e32 v131, v146, v146
	v_max_f32_e32 v130, v131, v130
	v_max3_f32 v131, v148, v149, v83
	v_max3_f32 v130, v130, v82, v84
	v_max3_f32 v130, v130, v85, v150
	v_max3_f32 v131, v131, v152, v153
	v_max3_f32 v130, v130, v151, v86
	v_max3_f32 v131, v131, v88, v89
	v_max3_f32 v130, v130, v87, v154
	v_max3_f32 v131, v131, v156, v157
	v_max3_f32 v130, v130, v155, v90
	v_max3_f32 v131, v131, v92, v93
	v_max3_f32 v130, v130, v91, v158
	v_max3_f32 v131, v131, v160, v161
	v_max3_f32 v130, v130, v159, v94
	v_max3_f32 v131, v131, v96, v97
	v_max3_f32 v130, v130, v95, v131
	v_mov_b32_e32 v131, v130
	s_nop 1
	v_permlane32_swap_b32_e32 v130, v131
	v_max_f32_e32 v131, v131, v131
	v_max_f32_e32 v130, v130, v130
	v_max_f32_e32 v130, v130, v131
	v_cmp_lt_f32_e32 vcc, s15, v130
	s_cbranch_vccnz .LBB0_627
	s_mov_b64 s[16:17], 0

.LBB0_561:
	s_add_i32 s16, s23, 0x2000
	s_cmpk_lg_i32 s23, 0x4000
	s_cselect_b32 s31, s16, 0
	s_waitcnt lgkmcnt(7)
	v_mfma_f32_32x32x16_bf16 v[130:145], v[98:101], v[190:193], v[66:81]
	v_add_f32_e32 v102, v146, v147
	v_add_f32_e32 v102, v148, v102
	v_add_f32_e32 v102, v149, v102
	v_add_f32_e32 v102, v150, v102
	v_add_u32_e32 v213, s20, v238
	v_add_f32_e32 v102, v151, v102
	v_cvt_pk_bf16_f32 v174, v146, v147
	v_cvt_pk_bf16_f32 v175, v148, v149
	s_nop 0
	v_add_f32_e32 v98, v152, v102
	v_add_f32_e32 v98, v153, v98
	v_add_f32_e32 v98, v154, v98
	v_add_f32_e32 v146, v155, v98
	s_waitcnt lgkmcnt(6)
	v_mfma_f32_32x32x16_bf16 v[98:113], v[198:201], v[190:193], v[66:81]
	v_cvt_pk_bf16_f32 v176, v150, v151
	v_cvt_pk_bf16_f32 v177, v152, v153
	s_waitcnt lgkmcnt(5)
	v_mfma_f32_32x32x16_bf16 v[130:145], v[202:205], v[186:189], v[130:145]
	v_add_f32_e32 v146, v156, v146
	v_add_f32_e32 v146, v157, v146
	v_add_f32_e32 v146, v158, v146
	v_add_f32_e32 v146, v159, v146
	v_cvt_pk_bf16_f32 v170, v154, v155
	v_cvt_pk_bf16_f32 v171, v156, v157
	s_waitcnt lgkmcnt(4)
	v_mfma_f32_32x32x16_bf16 v[98:113], v[194:197], v[186:189], v[98:113]
	v_add_f32_e32 v146, v160, v146
	v_add_f32_e32 v146, v161, v146
	v_add_f32_e32 v146, v82, v146
	v_add_f32_e32 v146, v83, v146
	v_cvt_pk_bf16_f32 v172, v158, v159
	v_cvt_pk_bf16_f32 v173, v160, v161
	s_waitcnt lgkmcnt(3)
	v_mfma_f32_32x32x16_bf16 v[130:145], v[126:129], v[182:185], v[130:145]
	v_add_f32_e32 v126, v84, v146
	v_add_f32_e32 v126, v85, v126
	v_add_f32_e32 v126, v86, v126
	v_add_f32_e32 v126, v87, v126
	v_cvt_pk_bf16_f32 v166, v82, v83
	v_cvt_pk_bf16_f32 v167, v84, v85
	s_waitcnt lgkmcnt(2)
	v_mfma_f32_32x32x16_bf16 v[98:113], v[122:125], v[182:185], v[98:113]
	v_add_f32_e32 v82, v88, v126
	v_add_f32_e32 v82, v89, v82
	v_add_f32_e32 v82, v90, v82
	v_add_f32_e32 v82, v91, v82
	v_cvt_pk_bf16_f32 v168, v86, v87
	v_cvt_pk_bf16_f32 v169, v88, v89
	s_waitcnt lgkmcnt(1)
	v_mfma_f32_32x32x16_bf16 v[130:145], v[118:121], v[178:181], v[130:145]
	v_add_f32_e32 v82, v92, v82
	v_add_f32_e32 v82, v93, v82
	v_add_f32_e32 v82, v94, v82
	v_add_f32_e32 v82, v95, v82
	v_cvt_pk_bf16_f32 v162, v90, v91
	v_cvt_pk_bf16_f32 v163, v92, v93
	s_waitcnt lgkmcnt(0)
	v_mfma_f32_32x32x16_bf16 v[98:113], v[114:117], v[178:181], v[98:113]
	v_add_f32_e32 v82, v96, v82
	v_add_f32_e32 v82, v97, v82
	v_add_f32_e32 v82, 0, v82
	v_cvt_pk_bf16_f32 v164, v94, v95
	v_cvt_pk_bf16_f32 v165, v96, v97
	ds_read_b64_tr_b16 v[126:127], v213 offset:24576
	ds_read_b64_tr_b16 v[128:129], v213 offset:25088
	ds_read_b64_tr_b16 v[122:123], v213 offset:28672
	ds_read_b64_tr_b16 v[124:125], v213 offset:29184
	ds_read_b64_tr_b16 v[118:119], v213 offset:25600
	ds_read_b64_tr_b16 v[120:121], v213 offset:26112
	ds_read_b64_tr_b16 v[114:115], v213 offset:29696
	ds_read_b64_tr_b16 v[116:117], v213 offset:30208
	v_add_f32_e32 v212, v215, v82
	ds_read_b64_tr_b16 v[94:95], v213 offset:26624
	ds_read_b64_tr_b16 v[96:97], v213 offset:27136
	ds_read_b64_tr_b16 v[86:87], v213 offset:27648
	ds_read_b64_tr_b16 v[88:89], v213 offset:28160
	ds_read_b64_tr_b16 v[90:91], v213 offset:30720
	ds_read_b64_tr_b16 v[92:93], v213 offset:31232
	ds_read_b64_tr_b16 v[82:83], v213 offset:31744
	ds_read_b64_tr_b16 v[84:85], v213 offset:32256
	s_add_u32 s16, s36, 0x4890000
	s_addc_u32 s17, s37, 0
	s_lshl_b32 s33, s31, 1
	v_lshl_add_u64 v[146:147], s[16:17], 0, v[0:1]
	s_add_i32 s20, s33, s24
	s_mov_b32 s18, m0
	s_mov_b32 m0, s20
	s_nop 0
	global_load_lds_dwordx4 v[146:147], off
	s_mov_b32 m0, s18
	s_add_u32 s18, s36, 0x4890080
	s_addc_u32 s19, s37, 0
	v_lshl_add_u64 v[146:147], s[18:19], 0, v[0:1]
	s_addk_i32 s20, 0x2000
	s_mov_b32 s21, m0
	s_mov_b32 m0, s20
	s_nop 0
	global_load_lds_dwordx4 v[146:147], off
	s_mov_b32 m0, s21
	v_max_f32_e32 v146, v131, v131
	v_max_f32_e32 v147, v130, v130
	v_max_f32_e32 v146, v147, v146
	v_max3_f32 v147, v132, v133, v99
	v_max3_f32 v146, v146, v98, v100
	v_max3_f32 v146, v146, v101, v134
	v_max3_f32 v147, v147, v136, v137
	v_max3_f32 v146, v146, v135, v102
	v_max3_f32 v147, v147, v104, v105
	v_max3_f32 v146, v146, v103, v138
	v_max3_f32 v147, v147, v140, v141
	v_max3_f32 v146, v146, v139, v106
	v_max3_f32 v147, v147, v108, v109
	v_max3_f32 v146, v146, v107, v142
	v_max3_f32 v147, v147, v144, v145
	v_max3_f32 v146, v146, v143, v110
	v_max3_f32 v147, v147, v112, v113
	v_max3_f32 v146, v146, v111, v147
	v_mov_b32_e32 v147, v146
	s_nop 1
	v_permlane32_swap_b32_e32 v146, v147
	v_max_f32_e32 v147, v147, v147
	v_max_f32_e32 v146, v146, v146
	v_max_f32_e32 v146, v146, v147
	v_cmp_lt_f32_e32 vcc, s15, v146
	s_cbranch_vccnz .LBB0_630
	s_mov_b64 s[20:21], 0

.LBB0_564:
	s_add_i32 s20, s31, 0x2000
	s_cmpk_lg_i32 s31, 0x4000
	s_cselect_b32 s31, s20, 0
	s_waitcnt lgkmcnt(7)
	v_mfma_f32_32x32x16_bf16 v[114:129], v[82:85], v[190:193], v[66:81]
	v_add_f32_e32 v86, v130, v131
	v_add_f32_e32 v86, v132, v86
	v_add_f32_e32 v86, v133, v86
	v_add_f32_e32 v86, v134, v86
	v_add_u32_e32 v213, s25, v238
	v_add_f32_e32 v86, v135, v86
	v_cvt_pk_bf16_f32 v174, v130, v131
	v_cvt_pk_bf16_f32 v175, v132, v133
	s_nop 0
	v_add_f32_e32 v82, v136, v86
	v_add_f32_e32 v82, v137, v82
	v_add_f32_e32 v82, v138, v82
	v_add_f32_e32 v130, v139, v82
	s_waitcnt lgkmcnt(6)
	v_mfma_f32_32x32x16_bf16 v[82:97], v[198:201], v[190:193], v[66:81]
	v_cvt_pk_bf16_f32 v176, v134, v135
	v_cvt_pk_bf16_f32 v177, v136, v137
	s_waitcnt lgkmcnt(5)
	v_mfma_f32_32x32x16_bf16 v[114:129], v[202:205], v[186:189], v[114:129]
	v_add_f32_e32 v130, v140, v130
	v_add_f32_e32 v130, v141, v130
	v_add_f32_e32 v130, v142, v130
	v_add_f32_e32 v130, v143, v130
	v_cvt_pk_bf16_f32 v170, v138, v139
	v_cvt_pk_bf16_f32 v171, v140, v141
	s_waitcnt lgkmcnt(4)
	v_mfma_f32_32x32x16_bf16 v[82:97], v[194:197], v[186:189], v[82:97]
	v_add_f32_e32 v130, v144, v130
	v_add_f32_e32 v130, v145, v130
	v_add_f32_e32 v130, v98, v130
	v_add_f32_e32 v130, v99, v130
	v_cvt_pk_bf16_f32 v172, v142, v143
	v_cvt_pk_bf16_f32 v173, v144, v145
	s_waitcnt lgkmcnt(3)
	v_mfma_f32_32x32x16_bf16 v[114:129], v[158:161], v[182:185], v[114:129]
	v_add_f32_e32 v130, v100, v130
	v_add_f32_e32 v130, v101, v130
	v_add_f32_e32 v130, v102, v130
	v_add_f32_e32 v130, v103, v130
	v_cvt_pk_bf16_f32 v166, v98, v99
	v_cvt_pk_bf16_f32 v167, v100, v101
	s_waitcnt lgkmcnt(2)
	v_mfma_f32_32x32x16_bf16 v[82:97], v[154:157], v[182:185], v[82:97]
	v_add_f32_e32 v98, v104, v130
	v_add_f32_e32 v98, v105, v98
	v_add_f32_e32 v98, v106, v98
	v_add_f32_e32 v98, v107, v98
	v_cvt_pk_bf16_f32 v168, v102, v103
	v_cvt_pk_bf16_f32 v169, v104, v105
	s_waitcnt lgkmcnt(1)
	v_mfma_f32_32x32x16_bf16 v[114:129], v[150:153], v[178:181], v[114:129]
	v_add_f32_e32 v98, v108, v98
	v_add_f32_e32 v98, v109, v98
	v_add_f32_e32 v98, v110, v98
	v_add_f32_e32 v98, v111, v98
	v_cvt_pk_bf16_f32 v162, v106, v107
	v_cvt_pk_bf16_f32 v163, v108, v109
	s_waitcnt lgkmcnt(0)
	v_mfma_f32_32x32x16_bf16 v[82:97], v[146:149], v[178:181], v[82:97]
	v_add_f32_e32 v98, v112, v98
	v_add_f32_e32 v98, v113, v98
	v_add_f32_e32 v98, 0, v98
	v_cvt_pk_bf16_f32 v164, v110, v111
	v_cvt_pk_bf16_f32 v165, v112, v113
	ds_read_b64_tr_b16 v[142:143], v213 offset:24576
	ds_read_b64_tr_b16 v[144:145], v213 offset:25088
	ds_read_b64_tr_b16 v[138:139], v213 offset:28672
	ds_read_b64_tr_b16 v[140:141], v213 offset:29184
	ds_read_b64_tr_b16 v[134:135], v213 offset:25600
	ds_read_b64_tr_b16 v[136:137], v213 offset:26112
	ds_read_b64_tr_b16 v[130:131], v213 offset:29696
	ds_read_b64_tr_b16 v[132:133], v213 offset:30208
	v_add_f32_e32 v194, v212, v98
	ds_read_b64_tr_b16 v[110:111], v213 offset:26624
	ds_read_b64_tr_b16 v[112:113], v213 offset:27136
	ds_read_b64_tr_b16 v[102:103], v213 offset:27648
	ds_read_b64_tr_b16 v[104:105], v213 offset:28160
	ds_read_b64_tr_b16 v[106:107], v213 offset:30720
	ds_read_b64_tr_b16 v[108:109], v213 offset:31232
	ds_read_b64_tr_b16 v[98:99], v213 offset:31744
	ds_read_b64_tr_b16 v[100:101], v213 offset:32256
	s_add_u32 s20, s36, 0x48d8000
	s_addc_u32 s21, s37, 0
	s_lshl_b32 s43, s31, 1
	v_lshl_add_u64 v[146:147], s[20:21], 0, v[0:1]
	s_add_i32 s24, s43, s24
	s_mov_b32 s22, m0
	s_mov_b32 m0, s24
	s_nop 0
	global_load_lds_dwordx4 v[146:147], off
	s_mov_b32 m0, s22
	s_add_u32 s22, s36, 0x48d8080
	s_addc_u32 s23, s37, 0
	v_lshl_add_u64 v[146:147], s[22:23], 0, v[0:1]
	s_addk_i32 s24, 0x2000
	s_mov_b32 s25, m0
	s_mov_b32 m0, s24
	s_nop 0
	global_load_lds_dwordx4 v[146:147], off
	s_mov_b32 m0, s25
	v_max_f32_e32 v0, v115, v115
	v_max_f32_e32 v146, v114, v114
	v_max_f32_e32 v0, v146, v0
	v_max3_f32 v146, v116, v117, v83
	v_max3_f32 v0, v0, v82, v84
	v_max3_f32 v0, v0, v85, v118
	v_max3_f32 v146, v146, v120, v121
	v_max3_f32 v0, v0, v119, v86
	v_max3_f32 v146, v146, v88, v89
	v_max3_f32 v0, v0, v87, v122
	v_max3_f32 v146, v146, v124, v125
	v_max3_f32 v0, v0, v123, v90
	v_max3_f32 v146, v146, v92, v93
	v_max3_f32 v0, v0, v91, v126
	v_max3_f32 v146, v146, v128, v129
	v_max3_f32 v0, v0, v127, v94
	v_max3_f32 v146, v146, v96, v97
	v_max3_f32 v0, v0, v95, v146
	v_mov_b32_e32 v146, v0
	s_nop 1
	v_permlane32_swap_b32_e32 v0, v146
	v_max_f32_e32 v146, v146, v146
	v_max_f32_e32 v0, v0, v0
	v_max_f32_e32 v0, v0, v146
	v_cmp_lt_f32_e32 vcc, s15, v0
	s_cbranch_vccnz .LBB0_633
	s_mov_b64 s[24:25], 0

.LBB0_573:
	v_mfma_f32_32x32x16_bf16 v[130:145], v[114:117], v[190:193], v[66:81]
	v_add_f32_e32 v118, v98, v99
	v_add_f32_e32 v118, v100, v118
	v_add_f32_e32 v118, v101, v118
	s_lshl_b32 s6, s6, 1
	v_add_f32_e32 v118, v102, v118
	v_add_u32_e32 v243, s6, v238
	v_add_f32_e32 v114, v103, v118
	v_cvt_pk_bf16_f32 v174, v98, v99
	v_cvt_pk_bf16_f32 v175, v100, v101
	s_nop 0
	v_add_f32_e32 v98, v104, v114
	v_mfma_f32_32x32x16_bf16 v[114:129], v[198:201], v[190:193], v[66:81]
	v_add_f32_e32 v98, v105, v98
	v_add_f32_e32 v98, v106, v98
	v_add_f32_e32 v98, v107, v98
	v_cvt_pk_bf16_f32 v176, v102, v103
	v_cvt_pk_bf16_f32 v177, v104, v105
	v_mfma_f32_32x32x16_bf16 v[130:145], v[202:205], v[186:189], v[130:145]
	v_add_f32_e32 v98, v108, v98
	v_add_f32_e32 v98, v109, v98
	v_add_f32_e32 v98, v110, v98
	v_add_f32_e32 v98, v111, v98
	v_cvt_pk_bf16_f32 v170, v106, v107
	v_cvt_pk_bf16_f32 v171, v108, v109
	v_mfma_f32_32x32x16_bf16 v[114:129], v[194:197], v[186:189], v[114:129]
	v_add_f32_e32 v98, v112, v98
	v_add_f32_e32 v98, v113, v98
	v_add_f32_e32 v98, v82, v98
	v_add_f32_e32 v98, v83, v98
	v_cvt_pk_bf16_f32 v172, v110, v111
	v_cvt_pk_bf16_f32 v173, v112, v113
	v_mfma_f32_32x32x16_bf16 v[130:145], v[158:161], v[182:185], v[130:145]
	v_add_f32_e32 v98, v84, v98
	v_add_f32_e32 v98, v85, v98
	v_add_f32_e32 v98, v86, v98
	v_add_f32_e32 v98, v87, v98
	v_cvt_pk_bf16_f32 v166, v82, v83
	v_cvt_pk_bf16_f32 v167, v84, v85
	v_mfma_f32_32x32x16_bf16 v[114:129], v[154:157], v[182:185], v[114:129]
	v_add_f32_e32 v82, v88, v98
	v_add_f32_e32 v82, v89, v82
	v_add_f32_e32 v82, v90, v82
	v_add_f32_e32 v82, v91, v82
	v_cvt_pk_bf16_f32 v168, v86, v87
	v_cvt_pk_bf16_f32 v169, v88, v89
	v_mfma_f32_32x32x16_bf16 v[130:145], v[150:153], v[178:181], v[130:145]
	v_add_f32_e32 v82, v92, v82
	v_add_f32_e32 v82, v93, v82
	v_add_f32_e32 v82, v94, v82
	v_add_f32_e32 v82, v95, v82
	v_cvt_pk_bf16_f32 v162, v90, v91
	v_cvt_pk_bf16_f32 v163, v92, v93
	v_mfma_f32_32x32x16_bf16 v[114:129], v[146:149], v[178:181], v[114:129]
	v_add_f32_e32 v82, v96, v82
	v_add_f32_e32 v82, v97, v82
	v_add_f32_e32 v242, v242, v82
	v_cvt_pk_bf16_f32 v164, v94, v95
	v_cvt_pk_bf16_f32 v165, v96, v97
	ds_read_b64_tr_b16 v[110:111], v243 offset:24576
	ds_read_b64_tr_b16 v[112:113], v243 offset:25088
	ds_read_b64_tr_b16 v[102:103], v243 offset:25600
	ds_read_b64_tr_b16 v[104:105], v243 offset:26112
	ds_read_b64_tr_b16 v[106:107], v243 offset:28672
	ds_read_b64_tr_b16 v[108:109], v243 offset:29184
	ds_read_b64_tr_b16 v[98:99], v243 offset:29696
	ds_read_b64_tr_b16 v[100:101], v243 offset:30208
	ds_read_b64_tr_b16 v[94:95], v243 offset:26624
	ds_read_b64_tr_b16 v[96:97], v243 offset:27136
	ds_read_b64_tr_b16 v[86:87], v243 offset:27648
	ds_read_b64_tr_b16 v[88:89], v243 offset:28160
	ds_read_b64_tr_b16 v[90:91], v243 offset:30720
	ds_read_b64_tr_b16 v[92:93], v243 offset:31232
	ds_read_b64_tr_b16 v[82:83], v243 offset:31744
	ds_read_b64_tr_b16 v[84:85], v243 offset:32256
	v_subrev_u32_e32 v216, s100, v212
	s_lshl_b32 s11, s45, 1
	v_max3_f32 v146, v130, v131, v132
	v_max3_f32 v147, v133, v134, v135
	v_max3_f32 v146, v146, v136, v137
	v_max3_f32 v147, v147, v138, v139
	v_max3_f32 v146, v146, v140, v141
	v_max3_f32 v147, v147, v142, v143
	v_max3_f32 v146, v146, v144, v145
	v_max3_f32 v147, v147, v114, v115
	v_max3_f32 v146, v146, v116, v117
	v_max3_f32 v147, v147, v118, v119
	v_max3_f32 v146, v146, v120, v121
	v_max3_f32 v147, v147, v122, v123
	v_max3_f32 v146, v146, v124, v125
	v_max3_f32 v147, v147, v126, v127
	v_max3_f32 v146, v146, v128, v129
	v_max_f32_e32 v146, v146, v147
	v_mov_b32_e32 v147, v146
	s_nop 1
	v_permlane32_swap_b32_e32 v146, v147
	v_max_f32_e32 v146, v146, v147
	v_cmp_lt_f32_e32 vcc, s15, v146
	s_cbranch_vccnz .LBB0_581
	s_mov_b64 s[6:7], 0

.LBB0_576:
	s_add_i32 s6, s45, 0x2000
	s_cmpk_lg_i32 s45, 0x4000
	s_cselect_b32 s57, s6, 0
	v_mfma_f32_32x32x16_bf16 v[98:113], v[82:85], v[190:193], v[66:81]
	v_add_f32_e32 v86, v130, v131
	v_add_f32_e32 v86, v132, v86
	v_add_f32_e32 v86, v133, v86
	s_lshl_b32 s6, s56, 1
	v_add_f32_e32 v86, v134, v86
	v_add_u32_e32 v243, s6, v238
	v_add_f32_e32 v82, v135, v86
	v_cvt_pk_bf16_f32 v174, v130, v131
	v_cvt_pk_bf16_f32 v175, v132, v133
	s_nop 0
	v_add_f32_e32 v82, v136, v82
	v_add_f32_e32 v82, v137, v82
	v_add_f32_e32 v82, v138, v82
	v_add_f32_e32 v130, v139, v82
	v_mfma_f32_32x32x16_bf16 v[82:97], v[198:201], v[190:193], v[66:81]
	v_cvt_pk_bf16_f32 v176, v134, v135
	v_cvt_pk_bf16_f32 v177, v136, v137
	v_mfma_f32_32x32x16_bf16 v[98:113], v[202:205], v[186:189], v[98:113]
	v_add_f32_e32 v130, v140, v130
	v_add_f32_e32 v130, v141, v130
	v_add_f32_e32 v130, v142, v130
	v_add_f32_e32 v130, v143, v130
	v_cvt_pk_bf16_f32 v170, v138, v139
	v_cvt_pk_bf16_f32 v171, v140, v141
	v_mfma_f32_32x32x16_bf16 v[82:97], v[194:197], v[186:189], v[82:97]
	v_add_f32_e32 v130, v144, v130
	v_add_f32_e32 v130, v145, v130
	v_add_f32_e32 v130, v114, v130
	v_add_f32_e32 v130, v115, v130
	v_cvt_pk_bf16_f32 v172, v142, v143
	v_cvt_pk_bf16_f32 v173, v144, v145
	v_mfma_f32_32x32x16_bf16 v[98:113], v[158:161], v[182:185], v[98:113]
	v_add_f32_e32 v130, v116, v130
	v_add_f32_e32 v130, v117, v130
	v_add_f32_e32 v130, v118, v130
	v_add_f32_e32 v130, v119, v130
	v_cvt_pk_bf16_f32 v166, v114, v115
	v_cvt_pk_bf16_f32 v167, v116, v117
	v_mfma_f32_32x32x16_bf16 v[82:97], v[154:157], v[182:185], v[82:97]
	v_add_f32_e32 v114, v120, v130
	v_add_f32_e32 v114, v121, v114
	v_add_f32_e32 v114, v122, v114
	v_add_f32_e32 v114, v123, v114
	v_cvt_pk_bf16_f32 v168, v118, v119
	v_cvt_pk_bf16_f32 v169, v120, v121
	v_mfma_f32_32x32x16_bf16 v[98:113], v[150:153], v[178:181], v[98:113]
	v_add_f32_e32 v114, v124, v114
	v_add_f32_e32 v114, v125, v114
	v_add_f32_e32 v114, v126, v114
	v_add_f32_e32 v114, v127, v114
	v_cvt_pk_bf16_f32 v162, v122, v123
	v_cvt_pk_bf16_f32 v163, v124, v125
	v_mfma_f32_32x32x16_bf16 v[82:97], v[146:149], v[178:181], v[82:97]
	v_add_f32_e32 v114, v128, v114
	v_add_f32_e32 v114, v129, v114
	v_add_f32_e32 v242, v242, v114
	v_cvt_pk_bf16_f32 v164, v126, v127
	v_cvt_pk_bf16_f32 v165, v128, v129
	ds_read_b64_tr_b16 v[142:143], v243 offset:24576
	ds_read_b64_tr_b16 v[144:145], v243 offset:25088
	ds_read_b64_tr_b16 v[134:135], v243 offset:25600
	ds_read_b64_tr_b16 v[136:137], v243 offset:26112
	ds_read_b64_tr_b16 v[138:139], v243 offset:28672
	ds_read_b64_tr_b16 v[140:141], v243 offset:29184
	ds_read_b64_tr_b16 v[130:131], v243 offset:29696
	ds_read_b64_tr_b16 v[132:133], v243 offset:30208
	ds_read_b64_tr_b16 v[126:127], v243 offset:26624
	ds_read_b64_tr_b16 v[128:129], v243 offset:27136
	ds_read_b64_tr_b16 v[118:119], v243 offset:27648
	ds_read_b64_tr_b16 v[120:121], v243 offset:28160
	ds_read_b64_tr_b16 v[122:123], v243 offset:30720
	ds_read_b64_tr_b16 v[124:125], v243 offset:31232
	ds_read_b64_tr_b16 v[114:115], v243 offset:31744
	ds_read_b64_tr_b16 v[116:117], v243 offset:32256
	s_add_u32 s6, s100, s4
	s_addc_u32 s7, s101, s5
	s_add_u32 s6, s6, 0x168000
	s_addc_u32 s7, s7, 0
	s_add_i32 m0, s45, s33
	s_nop 0
	global_load_lds_dwordx4 v216, s[6:7]
	s_lshl_b32 s10, s57, 1
	v_max3_f32 v146, v98, v99, v100
	v_max3_f32 v147, v101, v102, v103
	v_max3_f32 v146, v146, v104, v105
	v_max3_f32 v147, v147, v106, v107
	v_max3_f32 v146, v146, v108, v109
	v_max3_f32 v147, v147, v110, v111
	v_max3_f32 v146, v146, v112, v113
	v_max3_f32 v147, v147, v82, v83
	v_max3_f32 v146, v146, v84, v85
	v_max3_f32 v147, v147, v86, v87
	v_max3_f32 v146, v146, v88, v89
	v_max3_f32 v147, v147, v90, v91
	v_max3_f32 v146, v146, v92, v93
	v_max3_f32 v147, v147, v94, v95
	v_max3_f32 v146, v146, v96, v97
	v_max_f32_e32 v146, v146, v147
	v_mov_b32_e32 v147, v146
	s_nop 1
	v_permlane32_swap_b32_e32 v146, v147
	v_max_f32_e32 v146, v146, v147
	v_cmp_lt_f32_e32 vcc, s15, v146
	s_cbranch_vccnz .LBB0_584
	s_mov_b64 s[6:7], 0

.LBB0_581:
	v_max_f32_e32 v66, v146, v146
	v_max_f32_e32 v146, 0, v66
	v_exp_f32_e64 v147, -v146
	v_add_f32_e32 v239, v239, v146
	v_xor_b32_e32 v66, 0x80000000, v239
	v_mov_b32_e32 v67, v66
	v_mov_b32_e32 v68, v66
	v_mov_b32_e32 v69, v66
	v_mov_b32_e32 v70, v66
	v_mov_b32_e32 v71, v66
	v_mov_b32_e32 v72, v66
	v_mov_b32_e32 v73, v66
	v_mov_b32_e32 v74, v66
	v_mov_b32_e32 v75, v66
	v_mov_b32_e32 v76, v66
	v_mov_b32_e32 v77, v66
	v_mov_b32_e32 v78, v66
	v_mov_b32_e32 v79, v66
	v_mov_b32_e32 v80, v66
	v_mov_b32_e32 v81, v66
	s_and_saveexec_b64 s[8:9], s[40:41]
	ds_write_b32 v237, v147
	s_or_b64 exec, exec, s[8:9]
	v_sub_f32_e32 v145, v145, v146
	v_sub_f32_e32 v144, v144, v146
	v_sub_f32_e32 v143, v143, v146
	v_sub_f32_e32 v142, v142, v146
	v_sub_f32_e32 v141, v141, v146
	v_sub_f32_e32 v140, v140, v146
	v_sub_f32_e32 v139, v139, v146
	v_sub_f32_e32 v138, v138, v146
	v_sub_f32_e32 v137, v137, v146
	v_sub_f32_e32 v136, v136, v146
	v_sub_f32_e32 v135, v135, v146
	v_sub_f32_e32 v134, v134, v146
	v_sub_f32_e32 v133, v133, v146
	v_sub_f32_e32 v132, v132, v146
	v_sub_f32_e32 v131, v131, v146
	v_sub_f32_e32 v130, v130, v146
	v_sub_f32_e32 v129, v129, v146
	v_sub_f32_e32 v128, v128, v146
	v_sub_f32_e32 v127, v127, v146
	v_sub_f32_e32 v126, v126, v146
	v_sub_f32_e32 v125, v125, v146
	v_sub_f32_e32 v124, v124, v146
	v_sub_f32_e32 v123, v123, v146
	v_sub_f32_e32 v122, v122, v146
	v_sub_f32_e32 v121, v121, v146
	v_sub_f32_e32 v120, v120, v146
	v_sub_f32_e32 v119, v119, v146
	v_sub_f32_e32 v118, v118, v146
	v_sub_f32_e32 v117, v117, v146
	v_sub_f32_e32 v116, v116, v146
	v_sub_f32_e32 v115, v115, v146
	v_sub_f32_e32 v114, v114, v146
	v_mul_f32_e32 v242, v242, v147
	s_movk_i32 s81, 0x1200
	s_mov_b64 s[6:7], -1
	s_branch .LBB0_574
.LBB0_584:
	v_max_f32_e32 v66, v146, v146
	v_max_f32_e32 v146, 0, v66
	v_exp_f32_e64 v147, -v146
	v_add_f32_e32 v239, v239, v146
	v_xor_b32_e32 v66, 0x80000000, v239
	v_mov_b32_e32 v67, v66
	v_mov_b32_e32 v68, v66
	v_mov_b32_e32 v69, v66
	v_mov_b32_e32 v70, v66
	v_mov_b32_e32 v71, v66
	v_mov_b32_e32 v72, v66
	v_mov_b32_e32 v73, v66
	v_mov_b32_e32 v74, v66
	v_mov_b32_e32 v75, v66
	v_mov_b32_e32 v76, v66
	v_mov_b32_e32 v77, v66
	v_mov_b32_e32 v78, v66
	v_mov_b32_e32 v79, v66
	v_mov_b32_e32 v80, v66
	v_mov_b32_e32 v81, v66
	s_and_saveexec_b64 s[8:9], s[40:41]
	ds_write_b32 v237, v147
	s_or_b64 exec, exec, s[8:9]
	v_sub_f32_e32 v113, v113, v146
	v_sub_f32_e32 v112, v112, v146
	v_sub_f32_e32 v111, v111, v146
	v_sub_f32_e32 v110, v110, v146
	v_sub_f32_e32 v109, v109, v146
	v_sub_f32_e32 v108, v108, v146
	v_sub_f32_e32 v107, v107, v146
	v_sub_f32_e32 v106, v106, v146
	v_sub_f32_e32 v105, v105, v146
	v_sub_f32_e32 v104, v104, v146
	v_sub_f32_e32 v103, v103, v146
	v_sub_f32_e32 v102, v102, v146
	v_sub_f32_e32 v101, v101, v146
	v_sub_f32_e32 v100, v100, v146
	v_sub_f32_e32 v99, v99, v146
	v_sub_f32_e32 v98, v98, v146
	v_sub_f32_e32 v97, v97, v146
	v_sub_f32_e32 v96, v96, v146
	v_sub_f32_e32 v95, v95, v146
	v_sub_f32_e32 v94, v94, v146
	v_sub_f32_e32 v93, v93, v146
	v_sub_f32_e32 v92, v92, v146
	v_sub_f32_e32 v91, v91, v146
	v_sub_f32_e32 v90, v90, v146
	v_sub_f32_e32 v89, v89, v146
	v_sub_f32_e32 v88, v88, v146
	v_sub_f32_e32 v87, v87, v146
	v_sub_f32_e32 v86, v86, v146
	v_sub_f32_e32 v85, v85, v146
	v_sub_f32_e32 v84, v84, v146
	v_sub_f32_e32 v83, v83, v146
	v_sub_f32_e32 v82, v82, v146
	v_mul_f32_e32 v242, v242, v147
	s_movk_i32 s81, 0x1200
	s_mov_b64 s[6:7], -1
	s_branch .LBB0_577

.LBB0_595:
	s_add_i32 s4, s11, 0x2000
	s_cmpk_lg_i32 s11, 0x4000
	s_cselect_b32 s10, s4, 0
	s_waitcnt lgkmcnt(7)
	v_mfma_f32_32x32x16_bf16 v[130:145], v[98:101], v[190:193], v[66:81]
	v_add_f32_e32 v102, v146, v147
	v_add_f32_e32 v102, v148, v102
	v_add_f32_e32 v102, v149, v102
	v_add_f32_e32 v102, v150, v102
	v_add_u32_e32 v213, s8, v238
	v_add_f32_e32 v102, v151, v102
	v_cvt_pk_bf16_f32 v174, v146, v147
	v_cvt_pk_bf16_f32 v175, v148, v149
	s_nop 0
	v_add_f32_e32 v98, v152, v102
	v_add_f32_e32 v98, v153, v98
	v_add_f32_e32 v98, v154, v98
	v_add_f32_e32 v146, v155, v98
	s_waitcnt lgkmcnt(6)
	v_mfma_f32_32x32x16_bf16 v[98:113], v[198:201], v[190:193], v[66:81]
	v_cvt_pk_bf16_f32 v176, v150, v151
	v_cvt_pk_bf16_f32 v177, v152, v153
	s_waitcnt lgkmcnt(5)
	v_mfma_f32_32x32x16_bf16 v[130:145], v[202:205], v[186:189], v[130:145]
	v_add_f32_e32 v146, v156, v146
	v_add_f32_e32 v146, v157, v146
	v_add_f32_e32 v146, v158, v146
	v_add_f32_e32 v146, v159, v146
	v_cvt_pk_bf16_f32 v170, v154, v155
	v_cvt_pk_bf16_f32 v171, v156, v157
	s_waitcnt lgkmcnt(4)
	v_mfma_f32_32x32x16_bf16 v[98:113], v[194:197], v[186:189], v[98:113]
	v_add_f32_e32 v146, v160, v146
	v_add_f32_e32 v146, v161, v146
	v_add_f32_e32 v146, v82, v146
	v_add_f32_e32 v146, v83, v146
	v_cvt_pk_bf16_f32 v172, v158, v159
	v_cvt_pk_bf16_f32 v173, v160, v161
	s_waitcnt lgkmcnt(3)
	v_mfma_f32_32x32x16_bf16 v[130:145], v[126:129], v[182:185], v[130:145]
	v_add_f32_e32 v126, v84, v146
	v_add_f32_e32 v126, v85, v126
	v_add_f32_e32 v126, v86, v126
	v_add_f32_e32 v126, v87, v126
	v_cvt_pk_bf16_f32 v166, v82, v83
	v_cvt_pk_bf16_f32 v167, v84, v85
	s_waitcnt lgkmcnt(2)
	v_mfma_f32_32x32x16_bf16 v[98:113], v[122:125], v[182:185], v[98:113]
	v_add_f32_e32 v82, v88, v126
	v_add_f32_e32 v82, v89, v82
	v_add_f32_e32 v82, v90, v82
	v_add_f32_e32 v82, v91, v82
	v_cvt_pk_bf16_f32 v168, v86, v87
	v_cvt_pk_bf16_f32 v169, v88, v89
	s_waitcnt lgkmcnt(1)
	v_mfma_f32_32x32x16_bf16 v[130:145], v[118:121], v[178:181], v[130:145]
	v_add_f32_e32 v82, v92, v82
	v_add_f32_e32 v82, v93, v82
	v_add_f32_e32 v82, v94, v82
	v_add_f32_e32 v82, v95, v82
	v_cvt_pk_bf16_f32 v162, v90, v91
	v_cvt_pk_bf16_f32 v163, v92, v93
	s_waitcnt lgkmcnt(0)
	v_mfma_f32_32x32x16_bf16 v[98:113], v[114:117], v[178:181], v[98:113]
	v_add_f32_e32 v82, v96, v82
	v_add_f32_e32 v82, v97, v82
	v_add_f32_e32 v82, 0, v82
	v_cvt_pk_bf16_f32 v164, v94, v95
	v_cvt_pk_bf16_f32 v165, v96, v97
	ds_read_b64_tr_b16 v[126:127], v213 offset:24576
	ds_read_b64_tr_b16 v[128:129], v213 offset:25088
	ds_read_b64_tr_b16 v[122:123], v213 offset:28672
	ds_read_b64_tr_b16 v[124:125], v213 offset:29184
	ds_read_b64_tr_b16 v[118:119], v213 offset:25600
	ds_read_b64_tr_b16 v[120:121], v213 offset:26112
	ds_read_b64_tr_b16 v[114:115], v213 offset:29696
	ds_read_b64_tr_b16 v[116:117], v213 offset:30208
	v_add_f32_e32 v212, v215, v82
	ds_read_b64_tr_b16 v[94:95], v213 offset:26624
	ds_read_b64_tr_b16 v[96:97], v213 offset:27136
	ds_read_b64_tr_b16 v[86:87], v213 offset:27648
	ds_read_b64_tr_b16 v[88:89], v213 offset:28160
	ds_read_b64_tr_b16 v[90:91], v213 offset:30720
	ds_read_b64_tr_b16 v[92:93], v213 offset:31232
	ds_read_b64_tr_b16 v[82:83], v213 offset:31744
	ds_read_b64_tr_b16 v[84:85], v213 offset:32256
	v_lshl_add_u64 v[146:147], s[16:17], 0, v[0:1]
	s_lshl_b32 s8, s10, 1
	s_add_i32 s4, s8, s28
	s_mov_b32 s5, m0
	s_mov_b32 m0, s4
	s_nop 0
	global_load_lds_dwordx4 v[146:147], off
	s_mov_b32 m0, s5
	v_lshl_add_u64 v[146:147], s[18:19], 0, v[0:1]
	s_addk_i32 s4, 0x2000
	s_mov_b32 s5, m0
	s_mov_b32 m0, s4
	s_nop 0
	global_load_lds_dwordx4 v[146:147], off
	s_mov_b32 m0, s5
	v_max_f32_e32 v146, v131, v131
	v_max_f32_e32 v147, v130, v130
	v_max_f32_e32 v146, v147, v146
	v_max3_f32 v147, v132, v133, v99
	v_max3_f32 v146, v146, v98, v100
	v_max3_f32 v146, v146, v101, v134
	v_max3_f32 v147, v147, v136, v137
	v_max3_f32 v146, v146, v135, v102
	v_max3_f32 v147, v147, v104, v105
	v_max3_f32 v146, v146, v103, v138
	v_max3_f32 v147, v147, v140, v141
	v_max3_f32 v146, v146, v139, v106
	v_max3_f32 v147, v147, v108, v109
	v_max3_f32 v146, v146, v107, v142
	v_max3_f32 v147, v147, v144, v145
	v_max3_f32 v146, v146, v143, v110
	v_max3_f32 v147, v147, v112, v113
	v_max3_f32 v146, v146, v111, v147
	v_mov_b32_e32 v147, v146
	s_nop 1
	v_permlane32_swap_b32_e32 v146, v147
	v_max_f32_e32 v147, v147, v147
	v_max_f32_e32 v146, v146, v146
	v_max_f32_e32 v146, v146, v147
	v_cmp_lt_f32_e32 vcc, s15, v146
	s_cbranch_vccnz .LBB0_645
	s_mov_b64 s[4:5], 0

.LBB0_598:
	s_add_i32 s4, s10, 0x2000
	s_cmpk_lg_i32 s10, 0x4000
	s_cselect_b32 s10, s4, 0
	s_waitcnt lgkmcnt(7)
	v_mfma_f32_32x32x16_bf16 v[114:129], v[82:85], v[190:193], v[66:81]
	v_add_f32_e32 v86, v130, v131
	v_add_f32_e32 v86, v132, v86
	v_add_f32_e32 v86, v133, v86
	v_add_f32_e32 v86, v134, v86
	v_add_u32_e32 v213, s9, v238
	v_add_f32_e32 v86, v135, v86
	v_cvt_pk_bf16_f32 v174, v130, v131
	v_cvt_pk_bf16_f32 v175, v132, v133
	s_nop 0
	v_add_f32_e32 v82, v136, v86
	v_add_f32_e32 v82, v137, v82
	v_add_f32_e32 v82, v138, v82
	v_add_f32_e32 v130, v139, v82
	s_waitcnt lgkmcnt(6)
	v_mfma_f32_32x32x16_bf16 v[82:97], v[198:201], v[190:193], v[66:81]
	v_cvt_pk_bf16_f32 v176, v134, v135
	v_cvt_pk_bf16_f32 v177, v136, v137
	s_waitcnt lgkmcnt(5)
	v_mfma_f32_32x32x16_bf16 v[114:129], v[202:205], v[186:189], v[114:129]
	v_add_f32_e32 v130, v140, v130
	v_add_f32_e32 v130, v141, v130
	v_add_f32_e32 v130, v142, v130
	v_add_f32_e32 v130, v143, v130
	v_cvt_pk_bf16_f32 v170, v138, v139
	v_cvt_pk_bf16_f32 v171, v140, v141
	s_waitcnt lgkmcnt(4)
	v_mfma_f32_32x32x16_bf16 v[82:97], v[194:197], v[186:189], v[82:97]
	v_add_f32_e32 v130, v144, v130
	v_add_f32_e32 v130, v145, v130
	v_add_f32_e32 v130, v98, v130
	v_add_f32_e32 v130, v99, v130
	v_cvt_pk_bf16_f32 v172, v142, v143
	v_cvt_pk_bf16_f32 v173, v144, v145
	s_waitcnt lgkmcnt(3)
	v_mfma_f32_32x32x16_bf16 v[114:129], v[158:161], v[182:185], v[114:129]
	v_add_f32_e32 v130, v100, v130
	v_add_f32_e32 v130, v101, v130
	v_add_f32_e32 v130, v102, v130
	v_add_f32_e32 v130, v103, v130
	v_cvt_pk_bf16_f32 v166, v98, v99
	v_cvt_pk_bf16_f32 v167, v100, v101
	s_waitcnt lgkmcnt(2)
	v_mfma_f32_32x32x16_bf16 v[82:97], v[154:157], v[182:185], v[82:97]
	v_add_f32_e32 v98, v104, v130
	v_add_f32_e32 v98, v105, v98
	v_add_f32_e32 v98, v106, v98
	v_add_f32_e32 v98, v107, v98
	v_cvt_pk_bf16_f32 v168, v102, v103
	v_cvt_pk_bf16_f32 v169, v104, v105
	s_waitcnt lgkmcnt(1)
	v_mfma_f32_32x32x16_bf16 v[114:129], v[150:153], v[178:181], v[114:129]
	v_add_f32_e32 v98, v108, v98
	v_add_f32_e32 v98, v109, v98
	v_add_f32_e32 v98, v110, v98
	v_add_f32_e32 v98, v111, v98
	v_cvt_pk_bf16_f32 v162, v106, v107
	v_cvt_pk_bf16_f32 v163, v108, v109
	s_waitcnt lgkmcnt(0)
	v_mfma_f32_32x32x16_bf16 v[82:97], v[146:149], v[178:181], v[82:97]
	v_add_f32_e32 v98, v112, v98
	v_add_f32_e32 v98, v113, v98
	v_add_f32_e32 v98, 0, v98
	v_cvt_pk_bf16_f32 v164, v110, v111
	v_cvt_pk_bf16_f32 v165, v112, v113
	ds_read_b64_tr_b16 v[142:143], v213 offset:24576
	ds_read_b64_tr_b16 v[144:145], v213 offset:25088
	ds_read_b64_tr_b16 v[138:139], v213 offset:28672
	ds_read_b64_tr_b16 v[140:141], v213 offset:29184
	ds_read_b64_tr_b16 v[134:135], v213 offset:25600
	ds_read_b64_tr_b16 v[136:137], v213 offset:26112
	ds_read_b64_tr_b16 v[130:131], v213 offset:29696
	ds_read_b64_tr_b16 v[132:133], v213 offset:30208
	v_add_f32_e32 v194, v212, v98
	ds_read_b64_tr_b16 v[110:111], v213 offset:26624
	ds_read_b64_tr_b16 v[112:113], v213 offset:27136
	ds_read_b64_tr_b16 v[102:103], v213 offset:27648
	ds_read_b64_tr_b16 v[104:105], v213 offset:28160
	ds_read_b64_tr_b16 v[106:107], v213 offset:30720
	ds_read_b64_tr_b16 v[108:109], v213 offset:31232
	ds_read_b64_tr_b16 v[98:99], v213 offset:31744
	ds_read_b64_tr_b16 v[100:101], v213 offset:32256
	v_lshl_add_u64 v[146:147], s[20:21], 0, v[0:1]
	s_lshl_b32 s9, s10, 1
	s_add_i32 s4, s9, s28
	s_mov_b32 s5, m0
	s_mov_b32 m0, s4
	s_nop 0
	global_load_lds_dwordx4 v[146:147], off
	s_mov_b32 m0, s5
	v_lshl_add_u64 v[146:147], s[22:23], 0, v[0:1]
	s_addk_i32 s4, 0x2000
	s_mov_b32 s5, m0
	s_mov_b32 m0, s4
	s_nop 0
	global_load_lds_dwordx4 v[146:147], off
	s_mov_b32 m0, s5
	v_max_f32_e32 v0, v115, v115
	v_max_f32_e32 v146, v114, v114
	v_max_f32_e32 v0, v146, v0
	v_max3_f32 v146, v116, v117, v83
	v_max3_f32 v0, v0, v82, v84
	v_max3_f32 v0, v0, v85, v118
	v_max3_f32 v146, v146, v120, v121
	v_max3_f32 v0, v0, v119, v86
	v_max3_f32 v146, v146, v88, v89
	v_max3_f32 v0, v0, v87, v122
	v_max3_f32 v146, v146, v124, v125
	v_max3_f32 v0, v0, v123, v90
	v_max3_f32 v146, v146, v92, v93
	v_max3_f32 v0, v0, v91, v126
	v_max3_f32 v146, v146, v128, v129
	v_max3_f32 v0, v0, v127, v94
	v_max3_f32 v146, v146, v96, v97
	v_max3_f32 v0, v0, v95, v146
	v_mov_b32_e32 v146, v0
	s_nop 1
	v_permlane32_swap_b32_e32 v0, v146
	v_max_f32_e32 v146, v146, v146
	v_max_f32_e32 v0, v0, v0
	v_max_f32_e32 v0, v0, v146
	v_cmp_lt_f32_e32 vcc, s15, v0
	s_cbranch_vccnz .LBB0_648
	s_mov_b64 s[4:5], 0

.LBB0_606:
	v_max_f32_e32 v2, v22, v22
	v_max_f32_e32 v22, 0, v2
	v_exp_f32_e64 v23, -v22
	v_add_f32_e32 v234, v234, v22
	v_xor_b32_e32 v2, 0x80000000, v234
	v_mov_b32_e32 v3, v2
	v_mov_b32_e32 v4, v2
	v_mov_b32_e32 v5, v2
	v_mov_b32_e32 v6, v2
	v_mov_b32_e32 v7, v2
	v_mov_b32_e32 v8, v2
	v_mov_b32_e32 v9, v2
	v_mov_b32_e32 v10, v2
	v_mov_b32_e32 v11, v2
	v_mov_b32_e32 v12, v2
	v_mov_b32_e32 v13, v2
	v_mov_b32_e32 v14, v2
	v_mov_b32_e32 v15, v2
	v_mov_b32_e32 v16, v2
	v_mov_b32_e32 v17, v2
	s_and_saveexec_b64 s[22:23], s[40:41]
	ds_write_b32 v216, v23
	s_or_b64 exec, exec, s[22:23]
	v_sub_f32_e32 v145, v145, v22
	v_sub_f32_e32 v144, v144, v22
	v_sub_f32_e32 v143, v143, v22
	v_sub_f32_e32 v142, v142, v22
	v_sub_f32_e32 v141, v141, v22
	v_sub_f32_e32 v140, v140, v22
	v_sub_f32_e32 v139, v139, v22
	v_sub_f32_e32 v138, v138, v22
	v_sub_f32_e32 v137, v137, v22
	v_sub_f32_e32 v136, v136, v22
	v_sub_f32_e32 v135, v135, v22
	v_sub_f32_e32 v134, v134, v22
	v_sub_f32_e32 v133, v133, v22
	v_sub_f32_e32 v132, v132, v22
	v_sub_f32_e32 v131, v131, v22
	v_sub_f32_e32 v130, v130, v22
	v_sub_f32_e32 v113, v113, v22
	v_sub_f32_e32 v112, v112, v22
	v_sub_f32_e32 v111, v111, v22
	v_sub_f32_e32 v110, v110, v22
	v_sub_f32_e32 v109, v109, v22
	v_sub_f32_e32 v108, v108, v22
	v_sub_f32_e32 v107, v107, v22
	v_sub_f32_e32 v106, v106, v22
	v_sub_f32_e32 v105, v105, v22
	v_sub_f32_e32 v104, v104, v22
	v_sub_f32_e32 v103, v103, v22
	v_sub_f32_e32 v102, v102, v22
	v_sub_f32_e32 v101, v101, v22
	v_sub_f32_e32 v100, v100, v22
	v_sub_f32_e32 v99, v99, v22
	v_sub_f32_e32 v98, v98, v22
	v_mul_f32_e32 v236, v236, v23
	s_mov_b64 s[0:1], -1
	s_branch .LBB0_517
.LBB0_609:
	v_max_f32_e32 v0, v0, v0
	v_max_f32_e32 v0, 0, v0
	v_exp_f32_e64 v178, -v0
	v_add_f32_e32 v234, v234, v0
	v_xor_b32_e32 v2, 0x80000000, v234
	v_mov_b32_e32 v3, v2
	v_mov_b32_e32 v4, v2
	v_mov_b32_e32 v5, v2
	v_mov_b32_e32 v6, v2
	v_mov_b32_e32 v7, v2
	v_mov_b32_e32 v8, v2
	v_mov_b32_e32 v9, v2
	v_mov_b32_e32 v10, v2
	v_mov_b32_e32 v11, v2
	v_mov_b32_e32 v12, v2
	v_mov_b32_e32 v13, v2
	v_mov_b32_e32 v14, v2
	v_mov_b32_e32 v15, v2
	v_mov_b32_e32 v16, v2
	v_mov_b32_e32 v17, v2
	s_and_saveexec_b64 s[26:27], s[40:41]
	ds_write_b32 v216, v178
	s_or_b64 exec, exec, s[26:27]
	v_sub_f32_e32 v129, v129, v0
	v_sub_f32_e32 v128, v128, v0
	v_sub_f32_e32 v127, v127, v0
	v_sub_f32_e32 v126, v126, v0
	v_sub_f32_e32 v125, v125, v0
	v_sub_f32_e32 v124, v124, v0
	v_sub_f32_e32 v123, v123, v0
	v_sub_f32_e32 v122, v122, v0
	v_sub_f32_e32 v121, v121, v0
	v_sub_f32_e32 v120, v120, v0
	v_sub_f32_e32 v119, v119, v0
	v_sub_f32_e32 v118, v118, v0
	v_sub_f32_e32 v117, v117, v0
	v_sub_f32_e32 v116, v116, v0
	v_sub_f32_e32 v115, v115, v0
	v_sub_f32_e32 v114, v114, v0
	v_sub_f32_e32 v97, v97, v0
	v_sub_f32_e32 v96, v96, v0
	v_sub_f32_e32 v95, v95, v0
	v_sub_f32_e32 v94, v94, v0
	v_sub_f32_e32 v93, v93, v0
	v_sub_f32_e32 v92, v92, v0
	v_sub_f32_e32 v91, v91, v0
	v_sub_f32_e32 v90, v90, v0
	v_sub_f32_e32 v89, v89, v0
	v_sub_f32_e32 v88, v88, v0
	v_sub_f32_e32 v87, v87, v0
	v_sub_f32_e32 v86, v86, v0
	v_sub_f32_e32 v85, v85, v0
	v_sub_f32_e32 v84, v84, v0
	v_sub_f32_e32 v83, v83, v0
	v_sub_f32_e32 v82, v82, v0
	v_mul_f32_e32 v194, v194, v178
	s_mov_b64 s[0:1], -1
	s_branch .LBB0_520

.LBB0_615:
	v_max_f32_e32 v2, v22, v22
	v_max_f32_e32 v22, 0, v2
	v_exp_f32_e64 v23, -v22
	v_add_f32_e32 v233, v233, v22
	v_xor_b32_e32 v2, 0x80000000, v233
	v_mov_b32_e32 v3, v2
	v_mov_b32_e32 v4, v2
	v_mov_b32_e32 v5, v2
	v_mov_b32_e32 v6, v2
	v_mov_b32_e32 v7, v2
	v_mov_b32_e32 v8, v2
	v_mov_b32_e32 v9, v2
	v_mov_b32_e32 v10, v2
	v_mov_b32_e32 v11, v2
	v_mov_b32_e32 v12, v2
	v_mov_b32_e32 v13, v2
	v_mov_b32_e32 v14, v2
	v_mov_b32_e32 v15, v2
	v_mov_b32_e32 v16, v2
	v_mov_b32_e32 v17, v2
	s_and_saveexec_b64 s[6:7], s[40:41]
	ds_write_b32 v215, v23
	s_or_b64 exec, exec, s[6:7]
	v_sub_f32_e32 v145, v145, v22
	v_sub_f32_e32 v144, v144, v22
	v_sub_f32_e32 v143, v143, v22
	v_sub_f32_e32 v142, v142, v22
	v_sub_f32_e32 v141, v141, v22
	v_sub_f32_e32 v140, v140, v22
	v_sub_f32_e32 v139, v139, v22
	v_sub_f32_e32 v138, v138, v22
	v_sub_f32_e32 v137, v137, v22
	v_sub_f32_e32 v136, v136, v22
	v_sub_f32_e32 v135, v135, v22
	v_sub_f32_e32 v134, v134, v22
	v_sub_f32_e32 v133, v133, v22
	v_sub_f32_e32 v132, v132, v22
	v_sub_f32_e32 v131, v131, v22
	v_sub_f32_e32 v130, v130, v22
	v_sub_f32_e32 v113, v113, v22
	v_sub_f32_e32 v112, v112, v22
	v_sub_f32_e32 v111, v111, v22
	v_sub_f32_e32 v110, v110, v22
	v_sub_f32_e32 v109, v109, v22
	v_sub_f32_e32 v108, v108, v22
	v_sub_f32_e32 v107, v107, v22
	v_sub_f32_e32 v106, v106, v22
	v_sub_f32_e32 v105, v105, v22
	v_sub_f32_e32 v104, v104, v22
	v_sub_f32_e32 v103, v103, v22
	v_sub_f32_e32 v102, v102, v22
	v_sub_f32_e32 v101, v101, v22
	v_sub_f32_e32 v100, v100, v22
	v_sub_f32_e32 v99, v99, v22
	v_sub_f32_e32 v98, v98, v22
	v_mul_f32_e32 v235, v235, v23
	s_mov_b64 s[4:5], -1
	s_branch .LBB0_528
.LBB0_618:
	v_max_f32_e32 v0, v0, v0
	v_max_f32_e32 v0, 0, v0
	v_exp_f32_e64 v178, -v0
	v_add_f32_e32 v233, v233, v0
	v_xor_b32_e32 v2, 0x80000000, v233
	v_mov_b32_e32 v3, v2
	v_mov_b32_e32 v4, v2
	v_mov_b32_e32 v5, v2
	v_mov_b32_e32 v6, v2
	v_mov_b32_e32 v7, v2
	v_mov_b32_e32 v8, v2
	v_mov_b32_e32 v9, v2
	v_mov_b32_e32 v10, v2
	v_mov_b32_e32 v11, v2
	v_mov_b32_e32 v12, v2
	v_mov_b32_e32 v13, v2
	v_mov_b32_e32 v14, v2
	v_mov_b32_e32 v15, v2
	v_mov_b32_e32 v16, v2
	v_mov_b32_e32 v17, v2
	s_and_saveexec_b64 s[6:7], s[40:41]
	ds_write_b32 v215, v178
	s_or_b64 exec, exec, s[6:7]
	v_sub_f32_e32 v129, v129, v0
	v_sub_f32_e32 v128, v128, v0
	v_sub_f32_e32 v127, v127, v0
	v_sub_f32_e32 v126, v126, v0
	v_sub_f32_e32 v125, v125, v0
	v_sub_f32_e32 v124, v124, v0
	v_sub_f32_e32 v123, v123, v0
	v_sub_f32_e32 v122, v122, v0
	v_sub_f32_e32 v121, v121, v0
	v_sub_f32_e32 v120, v120, v0
	v_sub_f32_e32 v119, v119, v0
	v_sub_f32_e32 v118, v118, v0
	v_sub_f32_e32 v117, v117, v0
	v_sub_f32_e32 v116, v116, v0
	v_sub_f32_e32 v115, v115, v0
	v_sub_f32_e32 v114, v114, v0
	v_sub_f32_e32 v97, v97, v0
	v_sub_f32_e32 v96, v96, v0
	v_sub_f32_e32 v95, v95, v0
	v_sub_f32_e32 v94, v94, v0
	v_sub_f32_e32 v93, v93, v0
	v_sub_f32_e32 v92, v92, v0
	v_sub_f32_e32 v91, v91, v0
	v_sub_f32_e32 v90, v90, v0
	v_sub_f32_e32 v89, v89, v0
	v_sub_f32_e32 v88, v88, v0
	v_sub_f32_e32 v87, v87, v0
	v_sub_f32_e32 v86, v86, v0
	v_sub_f32_e32 v85, v85, v0
	v_sub_f32_e32 v84, v84, v0
	v_sub_f32_e32 v83, v83, v0
	v_sub_f32_e32 v82, v82, v0
	v_mul_f32_e32 v194, v194, v178
	s_mov_b64 s[4:5], -1
	s_branch .LBB0_531

.LBB0_624:
	v_max_f32_e32 v66, v146, v146
	v_max_f32_e32 v146, 0, v66
	v_exp_f32_e64 v147, -v146
	v_add_f32_e32 v239, v239, v146
	v_xor_b32_e32 v66, 0x80000000, v239
	v_mov_b32_e32 v67, v66
	v_mov_b32_e32 v68, v66
	v_mov_b32_e32 v69, v66
	v_mov_b32_e32 v70, v66
	v_mov_b32_e32 v71, v66
	v_mov_b32_e32 v72, v66
	v_mov_b32_e32 v73, v66
	v_mov_b32_e32 v74, v66
	v_mov_b32_e32 v75, v66
	v_mov_b32_e32 v76, v66
	v_mov_b32_e32 v77, v66
	v_mov_b32_e32 v78, v66
	v_mov_b32_e32 v79, v66
	v_mov_b32_e32 v80, v66
	v_mov_b32_e32 v81, v66
	s_and_saveexec_b64 s[18:19], s[40:41]
	ds_write_b32 v237, v147
	s_or_b64 exec, exec, s[18:19]
	v_sub_f32_e32 v145, v145, v146
	v_sub_f32_e32 v144, v144, v146
	v_sub_f32_e32 v143, v143, v146
	v_sub_f32_e32 v142, v142, v146
	v_sub_f32_e32 v141, v141, v146
	v_sub_f32_e32 v140, v140, v146
	v_sub_f32_e32 v139, v139, v146
	v_sub_f32_e32 v138, v138, v146
	v_sub_f32_e32 v137, v137, v146
	v_sub_f32_e32 v136, v136, v146
	v_sub_f32_e32 v135, v135, v146
	v_sub_f32_e32 v134, v134, v146
	v_sub_f32_e32 v133, v133, v146
	v_sub_f32_e32 v132, v132, v146
	v_sub_f32_e32 v131, v131, v146
	v_sub_f32_e32 v130, v130, v146
	v_sub_f32_e32 v129, v129, v146
	v_sub_f32_e32 v128, v128, v146
	v_sub_f32_e32 v127, v127, v146
	v_sub_f32_e32 v126, v126, v146
	v_sub_f32_e32 v125, v125, v146
	v_sub_f32_e32 v124, v124, v146
	v_sub_f32_e32 v123, v123, v146
	v_sub_f32_e32 v122, v122, v146
	v_sub_f32_e32 v121, v121, v146
	v_sub_f32_e32 v120, v120, v146
	v_sub_f32_e32 v119, v119, v146
	v_sub_f32_e32 v118, v118, v146
	v_sub_f32_e32 v117, v117, v146
	v_sub_f32_e32 v116, v116, v146
	v_sub_f32_e32 v115, v115, v146
	v_sub_f32_e32 v114, v114, v146
	v_mul_f32_e32 v215, v215, v147
	s_mov_b64 s[16:17], -1
	s_branch .LBB0_556
.LBB0_627:
	v_max_f32_e32 v66, v130, v130
	v_max_f32_e32 v130, 0, v66
	v_exp_f32_e64 v131, -v130
	v_add_f32_e32 v239, v239, v130
	v_xor_b32_e32 v66, 0x80000000, v239
	v_mov_b32_e32 v67, v66
	v_mov_b32_e32 v68, v66
	v_mov_b32_e32 v69, v66
	v_mov_b32_e32 v70, v66
	v_mov_b32_e32 v71, v66
	v_mov_b32_e32 v72, v66
	v_mov_b32_e32 v73, v66
	v_mov_b32_e32 v74, v66
	v_mov_b32_e32 v75, v66
	v_mov_b32_e32 v76, v66
	v_mov_b32_e32 v77, v66
	v_mov_b32_e32 v78, v66
	v_mov_b32_e32 v79, v66
	v_mov_b32_e32 v80, v66
	v_mov_b32_e32 v81, v66
	s_and_saveexec_b64 s[18:19], s[40:41]
	ds_write_b32 v237, v131
	s_or_b64 exec, exec, s[18:19]
	v_sub_f32_e32 v161, v161, v130
	v_sub_f32_e32 v160, v160, v130
	v_sub_f32_e32 v159, v159, v130
	v_sub_f32_e32 v158, v158, v130
	v_sub_f32_e32 v157, v157, v130
	v_sub_f32_e32 v156, v156, v130
	v_sub_f32_e32 v155, v155, v130
	v_sub_f32_e32 v154, v154, v130
	v_sub_f32_e32 v153, v153, v130
	v_sub_f32_e32 v152, v152, v130
	v_sub_f32_e32 v151, v151, v130
	v_sub_f32_e32 v150, v150, v130
	v_sub_f32_e32 v149, v149, v130
	v_sub_f32_e32 v148, v148, v130
	v_sub_f32_e32 v147, v147, v130
	v_sub_f32_e32 v146, v146, v130
	v_sub_f32_e32 v97, v97, v130
	v_sub_f32_e32 v96, v96, v130
	v_sub_f32_e32 v95, v95, v130
	v_sub_f32_e32 v94, v94, v130
	v_sub_f32_e32 v93, v93, v130
	v_sub_f32_e32 v92, v92, v130
	v_sub_f32_e32 v91, v91, v130
	v_sub_f32_e32 v90, v90, v130
	v_sub_f32_e32 v89, v89, v130
	v_sub_f32_e32 v88, v88, v130
	v_sub_f32_e32 v87, v87, v130
	v_sub_f32_e32 v86, v86, v130
	v_sub_f32_e32 v85, v85, v130
	v_sub_f32_e32 v84, v84, v130
	v_sub_f32_e32 v83, v83, v130
	v_sub_f32_e32 v82, v82, v130
	v_mul_f32_e32 v215, v215, v131
	s_mov_b64 s[16:17], -1
	s_branch .LBB0_559
.LBB0_630:
	v_max_f32_e32 v66, v146, v146
	v_max_f32_e32 v146, 0, v66
	v_exp_f32_e64 v147, -v146
	v_add_f32_e32 v239, v239, v146
	v_xor_b32_e32 v66, 0x80000000, v239
	v_mov_b32_e32 v67, v66
	v_mov_b32_e32 v68, v66
	v_mov_b32_e32 v69, v66
	v_mov_b32_e32 v70, v66
	v_mov_b32_e32 v71, v66
	v_mov_b32_e32 v72, v66
	v_mov_b32_e32 v73, v66
	v_mov_b32_e32 v74, v66
	v_mov_b32_e32 v75, v66
	v_mov_b32_e32 v76, v66
	v_mov_b32_e32 v77, v66
	v_mov_b32_e32 v78, v66
	v_mov_b32_e32 v79, v66
	v_mov_b32_e32 v80, v66
	v_mov_b32_e32 v81, v66
	s_and_saveexec_b64 s[22:23], s[40:41]
	ds_write_b32 v237, v147
	s_or_b64 exec, exec, s[22:23]
	v_sub_f32_e32 v145, v145, v146
	v_sub_f32_e32 v144, v144, v146
	v_sub_f32_e32 v143, v143, v146
	v_sub_f32_e32 v142, v142, v146
	v_sub_f32_e32 v141, v141, v146
	v_sub_f32_e32 v140, v140, v146
	v_sub_f32_e32 v139, v139, v146
	v_sub_f32_e32 v138, v138, v146
	v_sub_f32_e32 v137, v137, v146
	v_sub_f32_e32 v136, v136, v146
	v_sub_f32_e32 v135, v135, v146
	v_sub_f32_e32 v134, v134, v146
	v_sub_f32_e32 v133, v133, v146
	v_sub_f32_e32 v132, v132, v146
	v_sub_f32_e32 v131, v131, v146
	v_sub_f32_e32 v130, v130, v146
	v_sub_f32_e32 v113, v113, v146
	v_sub_f32_e32 v112, v112, v146
	v_sub_f32_e32 v111, v111, v146
	v_sub_f32_e32 v110, v110, v146
	v_sub_f32_e32 v109, v109, v146
	v_sub_f32_e32 v108, v108, v146
	v_sub_f32_e32 v107, v107, v146
	v_sub_f32_e32 v106, v106, v146
	v_sub_f32_e32 v105, v105, v146
	v_sub_f32_e32 v104, v104, v146
	v_sub_f32_e32 v103, v103, v146
	v_sub_f32_e32 v102, v102, v146
	v_sub_f32_e32 v101, v101, v146
	v_sub_f32_e32 v100, v100, v146
	v_sub_f32_e32 v99, v99, v146
	v_sub_f32_e32 v98, v98, v146
	v_mul_f32_e32 v212, v212, v147
	s_mov_b64 s[20:21], -1
	s_branch .LBB0_562
.LBB0_633:
	v_max_f32_e32 v0, v0, v0
	v_max_f32_e32 v0, 0, v0
	v_exp_f32_e64 v146, -v0
	v_add_f32_e32 v239, v239, v0
	v_xor_b32_e32 v66, 0x80000000, v239
	v_mov_b32_e32 v67, v66
	v_mov_b32_e32 v68, v66
	v_mov_b32_e32 v69, v66
	v_mov_b32_e32 v70, v66
	v_mov_b32_e32 v71, v66
	v_mov_b32_e32 v72, v66
	v_mov_b32_e32 v73, v66
	v_mov_b32_e32 v74, v66
	v_mov_b32_e32 v75, v66
	v_mov_b32_e32 v76, v66
	v_mov_b32_e32 v77, v66
	v_mov_b32_e32 v78, v66
	v_mov_b32_e32 v79, v66
	v_mov_b32_e32 v80, v66
	v_mov_b32_e32 v81, v66
	s_and_saveexec_b64 vcc, s[40:41]
	ds_write_b32 v237, v146
	s_or_b64 exec, exec, vcc
	v_sub_f32_e32 v129, v129, v0
	v_sub_f32_e32 v128, v128, v0
	v_sub_f32_e32 v127, v127, v0
	v_sub_f32_e32 v126, v126, v0
	v_sub_f32_e32 v125, v125, v0
	v_sub_f32_e32 v124, v124, v0
	v_sub_f32_e32 v123, v123, v0
	v_sub_f32_e32 v122, v122, v0
	v_sub_f32_e32 v121, v121, v0
	v_sub_f32_e32 v120, v120, v0
	v_sub_f32_e32 v119, v119, v0
	v_sub_f32_e32 v118, v118, v0
	v_sub_f32_e32 v117, v117, v0
	v_sub_f32_e32 v116, v116, v0
	v_sub_f32_e32 v115, v115, v0
	v_sub_f32_e32 v114, v114, v0
	v_sub_f32_e32 v97, v97, v0
	v_sub_f32_e32 v96, v96, v0
	v_sub_f32_e32 v95, v95, v0
	v_sub_f32_e32 v94, v94, v0
	v_sub_f32_e32 v93, v93, v0
	v_sub_f32_e32 v92, v92, v0
	v_sub_f32_e32 v91, v91, v0
	v_sub_f32_e32 v90, v90, v0
	v_sub_f32_e32 v89, v89, v0
	v_sub_f32_e32 v88, v88, v0
	v_sub_f32_e32 v87, v87, v0
	v_sub_f32_e32 v86, v86, v0
	v_sub_f32_e32 v85, v85, v0
	v_sub_f32_e32 v84, v84, v0
	v_sub_f32_e32 v83, v83, v0
	v_sub_f32_e32 v82, v82, v0
	v_mul_f32_e32 v194, v194, v146
	s_mov_b64 s[24:25], -1
	s_branch .LBB0_565

.LBB0_645:
	v_max_f32_e32 v66, v146, v146
	v_max_f32_e32 v146, 0, v66
	v_exp_f32_e64 v147, -v146
	v_add_f32_e32 v239, v239, v146
	v_xor_b32_e32 v66, 0x80000000, v239
	v_mov_b32_e32 v67, v66
	v_mov_b32_e32 v68, v66
	v_mov_b32_e32 v69, v66
	v_mov_b32_e32 v70, v66
	v_mov_b32_e32 v71, v66
	v_mov_b32_e32 v72, v66
	v_mov_b32_e32 v73, v66
	v_mov_b32_e32 v74, v66
	v_mov_b32_e32 v75, v66
	v_mov_b32_e32 v76, v66
	v_mov_b32_e32 v77, v66
	v_mov_b32_e32 v78, v66
	v_mov_b32_e32 v79, v66
	v_mov_b32_e32 v80, v66
	v_mov_b32_e32 v81, v66
	s_and_saveexec_b64 s[6:7], s[40:41]
	ds_write_b32 v237, v147
	s_or_b64 exec, exec, s[6:7]
	v_sub_f32_e32 v145, v145, v146
	v_sub_f32_e32 v144, v144, v146
	v_sub_f32_e32 v143, v143, v146
	v_sub_f32_e32 v142, v142, v146
	v_sub_f32_e32 v141, v141, v146
	v_sub_f32_e32 v140, v140, v146
	v_sub_f32_e32 v139, v139, v146
	v_sub_f32_e32 v138, v138, v146
	v_sub_f32_e32 v137, v137, v146
	v_sub_f32_e32 v136, v136, v146
	v_sub_f32_e32 v135, v135, v146
	v_sub_f32_e32 v134, v134, v146
	v_sub_f32_e32 v133, v133, v146
	v_sub_f32_e32 v132, v132, v146
	v_sub_f32_e32 v131, v131, v146
	v_sub_f32_e32 v130, v130, v146
	v_sub_f32_e32 v113, v113, v146
	v_sub_f32_e32 v112, v112, v146
	v_sub_f32_e32 v111, v111, v146
	v_sub_f32_e32 v110, v110, v146
	v_sub_f32_e32 v109, v109, v146
	v_sub_f32_e32 v108, v108, v146
	v_sub_f32_e32 v107, v107, v146
	v_sub_f32_e32 v106, v106, v146
	v_sub_f32_e32 v105, v105, v146
	v_sub_f32_e32 v104, v104, v146
	v_sub_f32_e32 v103, v103, v146
	v_sub_f32_e32 v102, v102, v146
	v_sub_f32_e32 v101, v101, v146
	v_sub_f32_e32 v100, v100, v146
	v_sub_f32_e32 v99, v99, v146
	v_sub_f32_e32 v98, v98, v146
	v_mul_f32_e32 v212, v212, v147
	s_mov_b64 s[4:5], -1
	s_branch .LBB0_596
.LBB0_648:
	v_max_f32_e32 v0, v0, v0
	v_max_f32_e32 v0, 0, v0
	v_exp_f32_e64 v146, -v0
	v_add_f32_e32 v239, v239, v0
	v_xor_b32_e32 v66, 0x80000000, v239
	v_mov_b32_e32 v67, v66
	v_mov_b32_e32 v68, v66
	v_mov_b32_e32 v69, v66
	v_mov_b32_e32 v70, v66
	v_mov_b32_e32 v71, v66
	v_mov_b32_e32 v72, v66
	v_mov_b32_e32 v73, v66
	v_mov_b32_e32 v74, v66
	v_mov_b32_e32 v75, v66
	v_mov_b32_e32 v76, v66
	v_mov_b32_e32 v77, v66
	v_mov_b32_e32 v78, v66
	v_mov_b32_e32 v79, v66
	v_mov_b32_e32 v80, v66
	v_mov_b32_e32 v81, v66
	s_and_saveexec_b64 s[6:7], s[40:41]
	ds_write_b32 v237, v146
	s_or_b64 exec, exec, s[6:7]
	v_sub_f32_e32 v129, v129, v0
	v_sub_f32_e32 v128, v128, v0
	v_sub_f32_e32 v127, v127, v0
	v_sub_f32_e32 v126, v126, v0
	v_sub_f32_e32 v125, v125, v0
	v_sub_f32_e32 v124, v124, v0
	v_sub_f32_e32 v123, v123, v0
	v_sub_f32_e32 v122, v122, v0
	v_sub_f32_e32 v121, v121, v0
	v_sub_f32_e32 v120, v120, v0
	v_sub_f32_e32 v119, v119, v0
	v_sub_f32_e32 v118, v118, v0
	v_sub_f32_e32 v117, v117, v0
	v_sub_f32_e32 v116, v116, v0
	v_sub_f32_e32 v115, v115, v0
	v_sub_f32_e32 v114, v114, v0
	v_sub_f32_e32 v97, v97, v0
	v_sub_f32_e32 v96, v96, v0
	v_sub_f32_e32 v95, v95, v0
	v_sub_f32_e32 v94, v94, v0
	v_sub_f32_e32 v93, v93, v0
	v_sub_f32_e32 v92, v92, v0
	v_sub_f32_e32 v91, v91, v0
	v_sub_f32_e32 v90, v90, v0
	v_sub_f32_e32 v89, v89, v0
	v_sub_f32_e32 v88, v88, v0
	v_sub_f32_e32 v87, v87, v0
	v_sub_f32_e32 v86, v86, v0
	v_sub_f32_e32 v85, v85, v0
	v_sub_f32_e32 v84, v84, v0
	v_sub_f32_e32 v83, v83, v0
	v_sub_f32_e32 v82, v82, v0
	v_mul_f32_e32 v194, v194, v146
	s_mov_b64 s[4:5], -1
	s_branch .LBB0_599

; #define WAIT_BAR(N) asm volatile("s_waitcnt vmcnt(" #N ") lgkmcnt(0)\n\ts_barrier":::"memory")
; template<int THRL> __device__ __forceinline__ void attn_unit(const bf16*Qblk,const bf16*__restrict__ Kh,const bf16*__restrict__ Vh,bf16*Oblk,const int po,const int NT,char*shm){
;   int tid_=threadIdx.x; asm volatile("":"+v"(tid_));
;   const int tid=tid_,lane=tid&63,r32=lane&31,hi=lane>>5; const int wid=__builtin_amdgcn_readfirstlane(tid>>6);
;   const bf16*Qw=Qblk+(long)wid*QBLK*PQ;
;   const unsigned lds0=(unsigned)(uintptr_t)shm;
;   float*wsf=(float*)(shm+LDS_WS)+wid*64;
;   const bf16*ksrc=Kh+(long)lane*PQ+wid*8;
;   const bf16*vsrc=Vh+(long)(16*(wid&3)+(lane>>2))*PQ+(wid>>2)*32+(lane&3)*8;
;   const unsigned kdst=lds0+LDS_K+wid*1024, vdst=lds0+LDS_V+wid*1024;
;     ...
;   const int vb0=(int)(lds0+LDS_V)+((lane>>4)&1)*32+(lane&3)*8+(4*hi+((lane&15)>>2))*64;
;   const char*Kbase=shm+LDS_K; bf16x8 kf[8];
;   const lds_cptr shm3=(lds_cptr)shm; const lds_cptr kp0=shm3+LDS_K+hi*1024+r32*16; const lds_cptr vp0=shm3+LDS_V+((lane>>4)&1)*32+(lane&3)*8+(4*hi+((lane&15)>>2))*64;
;   DMA_K(0,0);DMA_V(0,0);DMA_K(1,SLOTB);
;   bf16x8 qr[4];
;   #pragma unroll
;   for(int d0=0;d0<4;++d0)qr[d0]=*reinterpret_cast<const bf16x8*>(&Qw[(long)r32*PQ+d0*16+hi*8]);
;   float mhat=0.f,l_reg=0.f;f32x16 o[2];o[0]=f32x16{};o[1]=f32x16{};f32x16 negm=f32x16{};asm volatile("":"+v"(negm));
;     ...
;   bool resc=false;
;     ...
;   f32x16 pA0,pA1,pB0,pB1;
;   int sl_prev=0,sl_cur=0,sl_next=SLOTB;
;     ...
;   DMA_K(2,2*SLOTB);
;   WAIT_BAR(3);
;   qkt(pA0,pA1,Kbase,qr,negm,r32,hi);asm volatile("s_nop 15\n\ts_nop 7":"+v"(pA0),"+v"(pA1));CMASK(pA0,pA1,0);
;   START(pA0,pA1);
;   _Pragma("unroll") for(int r=0;r<16;++r)pA1[r]=__builtin_amdgcn_exp2f(pA1[r]);
;   WAIT_BAR(0);
; DI void p_attn(const bfu* QKV, bfu* AOR, bfu* AO, const float* lq1, const float* lk1, const float* lq2, const float* lk2, const float* subln, float lam_init, bool ctx_out, char* lds, int bx, int G, int vcu, int xmap) {
;     ...
;         if (xmap) { if (i >= 4) { u = 1024 + (i - 4) * G + bx; if (i > 4 || !(u < ngqa)) break; } else u = (2 * (vcu >> 5) + (i >> 1)) * 64 + (i & 1) * 32 + (vcu & 31); }
;         else { u = i * G + bx; if (u >= ngqa) break; }
;         if (u < 1024) attn_gqa(QKV, AO, (u >> 6) >> 3, (u >> 6) & 7, CTXL + (size_t)(u & 63) * 256, SEGR / 64, lds);
;         else attn_gqa(QKV, AO, (u - 1024) >> 3, (u - 1024) & 7, 0, CTXL / 64, lds);
.LBB0_666:
	s_andn2_b64 vcc, exec, s[2:3]
	s_mov_b64 s[2:3], -1
	s_cbranch_vccnz .LBB0_657
	s_cmpk_gt_i32 s8, 0x3ff
	s_cbranch_scc0 .LBB0_680
	s_add_i32 s2, s8, 0xfffffc00
	s_lshr_b32 s9, s2, 3
	s_and_b32 s3, s8, 7
	s_mul_i32 s4, s9, 0x4920000
	s_mul_hi_u32 s2, s9, 0x4920000
	s_add_u32 s4, s58, s4
	s_addc_u32 s2, s59, s2
	s_lshl_b32 s5, s3, 7
	s_add_u32 s5, s4, s5
	s_addc_u32 s18, s2, 0
	s_lshl_b32 s6, s8, 5
	s_and_b32 s6, s6, 0x80
	v_mov_b32_e32 v36, v220
	s_add_u32 s6, s4, s6
	s_addc_u32 s7, s2, 0
	v_readfirstlane_b32 s4, v36
	s_ashr_i32 s2, s4, 6
	v_and_b32_e32 v184, 63, v36
	s_mul_i32 s20, s2, 0x24000
	s_mul_hi_i32 s19, s2, 0x24000
	s_add_u32 s20, s5, s20
	v_mul_u32_u24_e32 v0, 0x900, v184
	s_addc_u32 s21, s18, s19
	v_lshlrev_b32_e32 v0, 1, v0
	s_lshl_b32 s18, s2, 3
	v_lshl_add_u64 v[2:3], s[6:7], 0, v[0:1]
	s_ashr_i32 s19, s18, 31
	v_lshl_add_u64 v[34:35], s[18:19], 1, v[2:3]
	s_mov_b64 s[18:19], 0x1000
	v_lshl_add_u64 v[2:3], v[34:35], 0, s[18:19]
	s_lshl_b32 s18, s2, 4
	v_bfe_u32 v0, v36, 2, 4
	v_and_or_b32 v0, s18, 48, v0
	v_mul_u32_u24_e32 v0, 0x900, v0
	s_and_b32 s5, s4, 0x3fffffc0
	v_lshlrev_b32_e32 v0, 1, v0
	s_ashr_i32 s4, s4, 3
	v_lshl_add_u64 v[4:5], s[6:7], 0, v[0:1]
	s_and_b32 s6, s4, 0xffffffe0
	v_lshlrev_b32_e32 v185, 3, v36
	s_ashr_i32 s7, s6, 31
	v_and_b32_e32 v188, 24, v185
	v_lshl_add_u64 v[4:5], s[6:7], 1, v[4:5]
	v_lshlrev_b32_e32 v0, 1, v188
	s_lshl_b32 s4, s2, 10
	v_lshl_add_u64 v[38:39], v[4:5], 0, v[0:1]
	s_mov_b64 s[6:7], 0x1100
	s_cmp_lg_u32 0, -1
	v_lshl_add_u64 v[182:183], v[38:39], 0, s[6:7]
	s_cselect_b32 s6, 0, 0
	v_and_b32_e32 v186, 31, v36
	s_add_i32 s4, s6, s4
	s_mov_b32 s6, m0
	s_mov_b32 m0, s4
	s_nop 0
	global_load_lds_dwordx4 v[2:3], off
	s_mov_b32 m0, s6
	s_add_i32 s18, s4, 0x6000
	s_mov_b32 s6, m0
	s_mov_b32 m0, s18
	s_nop 0
	global_load_lds_dwordx4 v[182:183], off
	s_mov_b32 m0, s6
	v_mul_u32_u24_e32 v0, 0x900, v186
	v_bfe_u32 v187, v36, 5, 1
	s_mov_b64 s[6:7], 0x49000
	v_lshlrev_b32_e32 v0, 1, v0
	v_lshl_add_u64 v[2:3], v[34:35], 0, s[6:7]
	s_add_i32 s6, s4, 0x2000
	s_mov_b32 s7, m0
	s_mov_b32 m0, s6
	s_nop 0
	global_load_lds_dwordx4 v[2:3], off
	s_mov_b32 m0, s7
	v_lshl_or_b32 v0, v187, 4, v0
	global_load_dwordx4 v[142:145], v0, s[20:21] offset:3072
	global_load_dwordx4 v[138:141], v0, s[20:21] offset:3104
	global_load_dwordx4 v[118:121], v0, s[20:21] offset:3136
	global_load_dwordx4 v[114:117], v0, s[20:21] offset:3168
	v_mov_b32_e32 v2, v1
	v_mov_b32_e32 v3, v1
	v_mov_b32_e32 v4, v1
	v_mov_b32_e32 v5, v1
	v_mov_b32_e32 v6, v1
	v_mov_b32_e32 v7, v1
	v_mov_b32_e32 v8, v1
	v_mov_b32_e32 v9, v1
	v_mov_b32_e32 v10, v1
	v_mov_b32_e32 v11, v1
	v_mov_b32_e32 v12, v1
	v_mov_b32_e32 v13, v1
	v_mov_b32_e32 v14, v1
	v_mov_b32_e32 v15, v1
	v_lshlrev_b32_e32 v0, 4, v186
	v_lshl_add_u32 v16, v187, 10, 0
	v_add_u32_e32 v194, v16, v0
	v_mov_b32_e32 v0, v1
	v_mov_b64_e32 v[16:17], v[14:15]
	s_mov_b64 s[6:7], 0x91000
	v_mov_b64_e32 v[14:15], v[12:13]
	v_mov_b64_e32 v[12:13], v[10:11]
	v_mov_b64_e32 v[10:11], v[8:9]
	v_mov_b64_e32 v[8:9], v[6:7]
	v_mov_b64_e32 v[6:7], v[4:5]
	v_mov_b64_e32 v[4:5], v[2:3]
	v_mov_b64_e32 v[2:3], v[0:1]
	v_lshl_add_u64 v[18:19], v[34:35], 0, s[6:7]
	s_add_i32 s6, s4, 0x4000
	s_mov_b32 s7, m0
	s_mov_b32 m0, s6
	s_nop 0
	global_load_lds_dwordx4 v[18:19], off
	s_mov_b32 m0, s7
	s_waitcnt vmcnt(3) lgkmcnt(0)
	s_barrier
	ds_read_b128 v[40:43], v194
	ds_read_b128 v[44:47], v194 offset:512
	s_lshl_b32 s5, s5, 2
	s_mov_b64 s[6:7], 0xd9000
	s_add_i32 s19, s5, 0
	v_lshlrev_b32_e32 v0, 1, v36
	v_lshlrev_b32_e32 v36, 4, v36
	v_and_b32_e32 v0, 32, v0
	v_and_b32_e32 v36, 0xc0, v36
	s_waitcnt vmcnt(3) lgkmcnt(1)
	v_mfma_f32_32x32x16_bf16 v[18:33], v[40:43], v[142:145], v[2:17]
	v_lshl_or_b32 v189, v187, 8, v36
	v_add3_u32 v36, 0, v0, v188
	v_add_u32_e32 v193, v36, v189
	v_cmp_gt_u32_e64 s[40:41], 32, v184
	v_lshl_add_u32 v190, v186, 2, s19
	s_waitcnt lgkmcnt(0)
	v_mfma_f32_32x32x16_bf16 v[2:17], v[44:47], v[142:145], v[2:17]
	ds_read_b128 v[40:43], v194 offset:2048
	ds_read_b128 v[44:47], v194 offset:2560
	s_waitcnt vmcnt(2) lgkmcnt(1)
	v_mfma_f32_32x32x16_bf16 v[18:33], v[40:43], v[138:141], v[18:33]
	s_waitcnt lgkmcnt(0)
	v_mfma_f32_32x32x16_bf16 v[2:17], v[44:47], v[138:141], v[2:17]
	ds_read_b128 v[40:43], v194 offset:4096
	ds_read_b128 v[44:47], v194 offset:4608
	s_waitcnt vmcnt(1) lgkmcnt(1)
	v_mfma_f32_32x32x16_bf16 v[18:33], v[40:43], v[118:121], v[18:33]
	s_waitcnt lgkmcnt(0)
	v_mfma_f32_32x32x16_bf16 v[2:17], v[44:47], v[118:121], v[2:17]
	ds_read_b128 v[40:43], v194 offset:6144
	ds_read_b128 v[44:47], v194 offset:6656
	s_waitcnt vmcnt(0) lgkmcnt(1)
	v_mfma_f32_32x32x16_bf16 v[18:33], v[40:43], v[114:117], v[18:33]
	s_waitcnt lgkmcnt(0)
	v_mfma_f32_32x32x16_bf16 v[2:17], v[44:47], v[114:117], v[2:17]
	s_nop 15
	s_nop 7
	s_nop 0
	v_max3_f32 v37, v18, v19, v2
	v_max3_f32 v40, v20, v21, v3
	s_nop 0
	v_max3_f32 v37, v37, v4, v5
	v_max3_f32 v40, v40, v24, v25
	s_nop 0
	v_max3_f32 v37, v37, v22, v23
	v_max3_f32 v40, v40, v8, v9
	s_nop 0
	v_max3_f32 v37, v37, v6, v7
	v_max3_f32 v40, v40, v28, v29
	s_nop 0
	v_max3_f32 v37, v37, v26, v27
	v_max3_f32 v40, v40, v12, v13
	s_nop 0
	v_max3_f32 v37, v37, v10, v11
	v_max3_f32 v40, v40, v32, v33
	s_nop 0
	v_max3_f32 v37, v37, v30, v31
	v_max3_f32 v40, v40, v16, v17
	s_nop 0
	v_max3_f32 v37, v37, v14, v15
	s_nop 0
	v_max_f32_e32 v37, v37, v40
	s_nop 0
	v_mov_b32_e32 v40, v37
	s_nop 1
	v_permlane32_swap_b32_e32 v37, v40
	v_max_f32_e32 v37, v37, v40
	s_nop 0
	v_add_f32_e32 v191, v1, v37
	v_sub_f32_e32 v40, v2, v37
	v_sub_f32_e32 v18, v18, v37
	v_sub_f32_e32 v19, v19, v37
	v_sub_f32_e32 v41, v3, v37
	v_sub_f32_e32 v20, v20, v37
	s_nop 0
	v_xor_b32_e32 v2, 0x80000000, v191
	v_sub_f32_e32 v42, v4, v37
	v_sub_f32_e32 v21, v21, v37
	v_sub_f32_e32 v43, v5, v37
	v_sub_f32_e32 v22, v22, v37
	v_sub_f32_e32 v44, v6, v37
	v_sub_f32_e32 v23, v23, v37
	v_sub_f32_e32 v45, v7, v37
	v_sub_f32_e32 v24, v24, v37
	v_sub_f32_e32 v46, v8, v37
	v_sub_f32_e32 v25, v25, v37
	v_sub_f32_e32 v47, v9, v37
	v_sub_f32_e32 v26, v26, v37
	v_sub_f32_e32 v48, v10, v37
	v_sub_f32_e32 v27, v27, v37
	v_sub_f32_e32 v49, v11, v37
	v_sub_f32_e32 v28, v28, v37
	v_sub_f32_e32 v50, v12, v37
	v_sub_f32_e32 v29, v29, v37
	v_sub_f32_e32 v51, v13, v37
	v_sub_f32_e32 v30, v30, v37
	v_sub_f32_e32 v52, v14, v37
	v_sub_f32_e32 v31, v31, v37
	v_sub_f32_e32 v53, v15, v37
	v_sub_f32_e32 v32, v32, v37
	v_sub_f32_e32 v54, v16, v37
	v_sub_f32_e32 v33, v33, v37
	v_sub_f32_e32 v37, v17, v37
	v_mov_b32_e32 v3, v2
	v_mov_b32_e32 v4, v2
	v_mov_b32_e32 v5, v2
	v_mov_b32_e32 v6, v2
	v_mov_b32_e32 v7, v2
	v_mov_b32_e32 v8, v2
	v_mov_b32_e32 v9, v2
	v_mov_b32_e32 v10, v2
	v_mov_b32_e32 v11, v2
	v_mov_b32_e32 v12, v2
	v_mov_b32_e32 v13, v2
	v_mov_b32_e32 v14, v2
	v_mov_b32_e32 v15, v2
	v_mov_b32_e32 v16, v2
	v_mov_b32_e32 v17, v2
	s_waitcnt vmcnt(0) lgkmcnt(0)
	s_barrier
; #define WAIT_BAR(N) asm volatile("s_waitcnt vmcnt(" #N ") lgkmcnt(0)\n\ts_barrier":::"memory")
;   #define DMA_K(t,slot) glds16(ksrc+(long)(t)*KVBLK*PQ,(unsigned)__builtin_amdgcn_readfirstlane(kdst+(slot)))
;   #define DMA_V(t,slot) glds16(vsrc+(long)(t)*KVBLK*PQ,(unsigned)__builtin_amdgcn_readfirstlane(vdst+(slot)))
;   #define CMASK(P0,P1,t) do{}while(0)
;   #define START(P0,P1) do{ const float rm=rowmax(P0,P1); resc=false; \
;     { const float dl=rm; mhat=fadd_s(mhat,dl); \
;       _Pragma("unroll") for(int r=0;r<16;++r){P0[r]=fsub_s(P0[r],dl);P1[r]=fsub_s(P1[r],dl);} \
;       _Pragma("unroll") for(int r=0;r<16;++r)negm[r]=-mhat; asm volatile("":"+v"(negm)); } \
;     _Pragma("unroll") for(int r=0;r<16;++r)P0[r]=__builtin_amdgcn_exp2f(P0[r]); }while(0)
;   #define ROT() do{sl_prev=sl_cur;sl_cur=sl_next;sl_next=(sl_next==(NSLOT-1)*SLOTB)?0:sl_next+SLOTB;}while(0)
;   #define CMASK(P0,P1,t) do{}while(0)
;   #define CMASK(P0,P1,t) do{}while(0)
;   #define DMA_K(t,slot) glds16((const char*)Kh+(size_t)(t)*(KVBLK*PQ*2)+koff,(unsigned)__builtin_amdgcn_readfirstlane(kdst+(slot)))
;   #define DMA_V(t,slot) do{ glds16((const char*)Vh+(size_t)(t)*(KVBLK*PQ*2)+voff,(unsigned)__builtin_amdgcn_readfirstlane(vdst+2*(slot))); glds16((const char*)Vh+(size_t)(t)*(KVBLK*PQ*2)+128+voff,(unsigned)__builtin_amdgcn_readfirstlane(vdst+2*(slot)+8192)); }while(0)
;   #define CMASK(P0,P1,t) do{}while(0)
;   #define START(P0,P1) do{ const float rm=rowmax(P0,P1); resc=false; \
;     { const float dl=rm; mhat=fadd_s(mhat,dl); \
;       _Pragma("unroll") for(int r=0;r<16;++r){P0[r]=fsub_s(P0[r],dl);P1[r]=fsub_s(P1[r],dl);} \
;       _Pragma("unroll") for(int r=0;r<16;++r)negm[r]=-mhat; asm volatile("":"+v"(negm)); } \
;     _Pragma("unroll") for(int r=0;r<16;++r)P0[r]=__builtin_amdgcn_exp2f(P0[r]); }while(0)
;   #define CMASK(P0,P1,t) do{}while(0)
; template<int THRL> __device__ __forceinline__ void attn_unit(const bf16*Qblk,const bf16*__restrict__ Kh,const bf16*__restrict__ Vh,bf16*Oblk,const int po,const int NT,char*shm){
;     ...
;   DMA_K(2,2*SLOTB);
;   WAIT_BAR(3);
;   qkt(pA0,pA1,Kbase,qr,negm,r32,hi);asm volatile("s_nop 15\n\ts_nop 7":"+v"(pA0),"+v"(pA1));CMASK(pA0,pA1,0);
;   START(pA0,pA1);
;   _Pragma("unroll") for(int r=0;r<16;++r)pA1[r]=__builtin_amdgcn_exp2f(pA1[r]);
;   WAIT_BAR(0);
;   DMA_K(3,0);DMA_V(1,SLOTB);
;   ROT();
;   kload8(kf,kp0+sl_cur);
;   WAIT_BAR(2);
	v_exp_f32_e32 v55, v18
	v_exp_f32_e32 v56, v19
	v_lshl_add_u64 v[18:19], v[34:35], 0, s[6:7]
	s_mov_b32 s5, m0
	s_mov_b32 m0, s4
	s_nop 0
	global_load_lds_dwordx4 v[18:19], off
	s_mov_b32 m0, s5
	s_mov_b64 s[6:7], 0x49100
	v_lshl_add_u64 v[18:19], v[38:39], 0, s[6:7]
	s_add_i32 s5, s4, 0x8000
	s_mov_b32 s6, m0
	s_mov_b32 m0, s5
	s_nop 0
	global_load_lds_dwordx4 v[18:19], off
	s_mov_b32 m0, s6
	v_exp_f32_e32 v59, v22
	v_exp_f32_e32 v60, v23
	v_exp_f32_e32 v61, v24
	v_exp_f32_e32 v62, v25
	v_exp_f32_e32 v63, v26
	v_exp_f32_e32 v64, v27
	v_exp_f32_e32 v65, v28
	v_exp_f32_e32 v94, v29
	v_exp_f32_e32 v95, v30
	v_exp_f32_e32 v96, v31
	v_exp_f32_e32 v97, v32
	v_exp_f32_e32 v130, v33
	v_exp_f32_e32 v131, v40
	v_exp_f32_e32 v132, v41
	v_exp_f32_e32 v133, v42
	v_exp_f32_e32 v134, v43
	v_exp_f32_e32 v135, v44
	v_exp_f32_e32 v136, v45
	v_exp_f32_e32 v137, v46
	v_exp_f32_e32 v146, v47
	ds_read_b128 v[22:25], v194 offset:8192
	ds_read_b128 v[26:29], v194 offset:8704
	ds_read_b128 v[30:33], v194 offset:10240
	ds_read_b128 v[40:43], v194 offset:10752
	ds_read_b128 v[44:47], v194 offset:12288
	ds_read_b128 v[82:85], v194 offset:12800
	ds_read_b128 v[86:89], v194 offset:14336
	ds_read_b128 v[90:93], v194 offset:14848
	v_exp_f32_e32 v57, v20
	v_exp_f32_e32 v58, v21
	s_waitcnt vmcnt(2) lgkmcnt(0)
	s_barrier
	v_exp_f32_e32 v48, v48
	v_exp_f32_e32 v49, v49
	v_exp_f32_e32 v147, v50
	v_exp_f32_e32 v148, v51
	v_exp_f32_e32 v149, v52
	v_exp_f32_e32 v150, v53
	v_exp_f32_e32 v151, v54
	v_exp_f32_e32 v152, v37
	ds_read_b64_tr_b16 v[18:19], v193 offset:24576
	ds_read_b64_tr_b16 v[20:21], v193 offset:25088
	s_waitcnt lgkmcnt(9)
	v_mfma_f32_32x32x16_bf16 v[98:113], v[22:25], v[142:145], v[2:17]
	v_add_f32_e32 v34, v55, v56
	v_add_f32_e32 v34, v34, v57
	v_add_f32_e32 v34, v34, v58
	v_add_f32_e32 v34, v34, v59
	v_add_f32_e32 v50, v34, v60
	v_cvt_pk_bf16_f32 v126, v55, v56
	v_cvt_pk_bf16_f32 v127, v57, v58
	ds_read_b64_tr_b16 v[34:35], v193 offset:28672
	ds_read_b64_tr_b16 v[36:37], v193 offset:29184
	s_waitcnt lgkmcnt(10)
	v_mfma_f32_32x32x16_bf16 v[66:81], v[26:29], v[142:145], v[2:17]
	v_add_f32_e32 v22, v61, v50
	v_add_f32_e32 v22, v62, v22
	v_add_f32_e32 v22, v63, v22
	v_add_f32_e32 v22, v64, v22
	v_cvt_pk_bf16_f32 v128, v59, v60
	v_cvt_pk_bf16_f32 v129, v61, v62
	ds_read_b64_tr_b16 v[50:51], v193 offset:25600
	ds_read_b64_tr_b16 v[52:53], v193 offset:26112
	s_waitcnt lgkmcnt(11)
	v_mfma_f32_32x32x16_bf16 v[98:113], v[30:33], v[138:141], v[98:113]
	v_add_f32_e32 v22, v65, v22
	v_add_f32_e32 v22, v94, v22
	v_add_f32_e32 v22, v95, v22
	v_add_f32_e32 v22, v96, v22
	v_cvt_pk_bf16_f32 v122, v63, v64
	v_cvt_pk_bf16_f32 v123, v65, v94
	ds_read_b64_tr_b16 v[54:55], v193 offset:29696
	ds_read_b64_tr_b16 v[56:57], v193 offset:30208
	s_waitcnt lgkmcnt(12)
	v_mfma_f32_32x32x16_bf16 v[66:81], v[40:43], v[138:141], v[66:81]
	v_add_f32_e32 v22, v97, v22
	v_add_f32_e32 v22, v130, v22
	v_add_f32_e32 v22, v131, v22
	v_add_f32_e32 v22, v132, v22
	v_cvt_pk_bf16_f32 v124, v95, v96
	v_cvt_pk_bf16_f32 v125, v97, v130
	ds_read_b64_tr_b16 v[58:59], v193 offset:26624
	ds_read_b64_tr_b16 v[60:61], v193 offset:27136
	s_waitcnt lgkmcnt(13)
	v_mfma_f32_32x32x16_bf16 v[98:113], v[44:47], v[118:121], v[98:113]
	v_add_f32_e32 v22, v133, v22
	v_add_f32_e32 v22, v134, v22
	v_add_f32_e32 v22, v135, v22
	v_add_f32_e32 v22, v136, v22
	v_cvt_pk_bf16_f32 v130, v131, v132
	v_cvt_pk_bf16_f32 v131, v133, v134
	ds_read_b64_tr_b16 v[62:63], v193 offset:30720
	ds_read_b64_tr_b16 v[64:65], v193 offset:31232
	s_waitcnt lgkmcnt(14)
	v_mfma_f32_32x32x16_bf16 v[66:81], v[82:85], v[118:121], v[66:81]
	v_add_f32_e32 v22, v137, v22
	v_add_f32_e32 v22, v146, v22
	v_add_f32_e32 v22, v48, v22
	v_add_f32_e32 v22, v49, v22
	v_cvt_pk_bf16_f32 v132, v135, v136
	v_cvt_pk_bf16_f32 v133, v137, v146
	ds_read_b64_tr_b16 v[82:83], v193 offset:27648
	ds_read_b64_tr_b16 v[84:85], v193 offset:28160
	s_waitcnt lgkmcnt(14)
	v_mfma_f32_32x32x16_bf16 v[98:113], v[86:89], v[114:117], v[98:113]
	v_add_f32_e32 v22, v147, v22
	v_add_f32_e32 v22, v148, v22
	v_add_f32_e32 v22, v149, v22
	v_add_f32_e32 v22, v150, v22
	v_cvt_pk_bf16_f32 v134, v48, v49
	v_cvt_pk_bf16_f32 v135, v147, v148
	ds_read_b64_tr_b16 v[86:87], v193 offset:31744
	ds_read_b64_tr_b16 v[88:89], v193 offset:32256
	v_mfma_f32_32x32x16_bf16 v[66:81], v[90:93], v[114:117], v[66:81]
	v_add_f32_e32 v22, v151, v22
	v_add_f32_e32 v22, v152, v22
	v_add_f32_e32 v22, 0, v22
	v_cvt_pk_bf16_f32 v136, v149, v150
	v_cvt_pk_bf16_f32 v137, v151, v152
	s_mov_b64 s[6:7], 0x91100
	v_add_f32_e32 v195, 0, v22
	v_lshl_add_u64 v[22:23], v[38:39], 0, s[6:7]
	s_add_i32 s4, s4, 0xa000
	s_mov_b32 s5, m0
	s_mov_b32 m0, s4
	s_nop 0
	global_load_lds_dwordx4 v[22:23], off
	s_mov_b32 m0, s5
	v_max_f32_e32 v22, v99, v99
	v_max_f32_e32 v23, v98, v98
	v_max_f32_e32 v22, v23, v22
	v_max3_f32 v23, v100, v101, v67
	v_max3_f32 v22, v22, v66, v68
	v_max3_f32 v22, v22, v69, v102
	v_max3_f32 v23, v23, v104, v105
	v_max3_f32 v22, v22, v103, v70
	v_max3_f32 v23, v23, v72, v73
	v_max3_f32 v22, v22, v71, v106
	v_max3_f32 v23, v23, v108, v109
	v_max3_f32 v22, v22, v107, v74
	v_max3_f32 v23, v23, v76, v77
	v_max3_f32 v22, v22, v75, v110
	v_max3_f32 v23, v23, v112, v113
	v_max3_f32 v22, v22, v111, v78
	v_max3_f32 v23, v23, v80, v81
	v_max3_f32 v22, v22, v79, v23
	v_mov_b32_e32 v23, v22
	s_nop 1
	v_permlane32_swap_b32_e32 v22, v23
	v_max_f32_e32 v23, v23, v23
	v_max_f32_e32 v22, v22, v22
	v_max_f32_e32 v22, v22, v23
	v_cmp_lt_f32_e32 vcc, s15, v22
	s_cbranch_vccnz .LBB0_713
	s_mov_b64 s[4:5], 0

.LBB0_674:
	ds_read_b64_tr_b16 v[98:99], v193 offset:40960
	ds_read_b64_tr_b16 v[100:101], v193 offset:41472
	v_add_f32_e32 v66, v82, v83
	v_add_f32_e32 v66, v84, v66
	v_add_f32_e32 v66, v85, v66
	v_add_f32_e32 v66, v86, v66
	v_add_f32_e32 v106, v87, v66
	s_waitcnt lgkmcnt(9)
	v_mfma_f32_32x32x16_bf16 v[66:81], v[166:169], v[142:145], v[2:17]
	v_cvt_pk_bf16_f32 v126, v82, v83
	v_cvt_pk_bf16_f32 v127, v84, v85
	ds_read_b64_tr_b16 v[82:83], v193 offset:45056
	ds_read_b64_tr_b16 v[84:85], v193 offset:45568
	s_waitcnt lgkmcnt(10)
	v_mfma_f32_32x32x16_bf16 v[2:17], v[162:165], v[142:145], v[2:17]
	v_add_f32_e32 v106, v88, v106
	v_add_f32_e32 v106, v89, v106
	v_add_f32_e32 v106, v90, v106
	v_add_f32_e32 v106, v91, v106
	v_cvt_pk_bf16_f32 v128, v86, v87
	v_cvt_pk_bf16_f32 v129, v88, v89
	ds_read_b64_tr_b16 v[86:87], v193 offset:41984
	ds_read_b64_tr_b16 v[88:89], v193 offset:42496
	s_waitcnt lgkmcnt(11)
	v_mfma_f32_32x32x16_bf16 v[66:81], v[158:161], v[138:141], v[66:81]
	v_add_f32_e32 v106, v92, v106
	v_add_f32_e32 v106, v93, v106
	v_add_f32_e32 v106, v94, v106
	v_add_f32_e32 v106, v95, v106
	v_cvt_pk_bf16_f32 v122, v90, v91
	v_cvt_pk_bf16_f32 v123, v92, v93
	ds_read_b64_tr_b16 v[90:91], v193 offset:46080
	ds_read_b64_tr_b16 v[92:93], v193 offset:46592
	s_waitcnt lgkmcnt(12)
	v_mfma_f32_32x32x16_bf16 v[2:17], v[154:157], v[138:141], v[2:17]
	v_add_f32_e32 v106, v96, v106
	v_add_f32_e32 v106, v97, v106
	v_add_f32_e32 v106, v50, v106
	v_add_f32_e32 v106, v51, v106
	v_cvt_pk_bf16_f32 v124, v94, v95
	v_cvt_pk_bf16_f32 v125, v96, v97
	ds_read_b64_tr_b16 v[94:95], v193 offset:43008
	ds_read_b64_tr_b16 v[96:97], v193 offset:43520
	s_waitcnt lgkmcnt(13)
	v_mfma_f32_32x32x16_bf16 v[66:81], v[102:105], v[118:121], v[66:81]
	v_add_f32_e32 v102, v52, v106
	v_add_f32_e32 v102, v53, v102
	v_add_f32_e32 v102, v54, v102
	v_add_f32_e32 v106, v55, v102
	v_cvt_pk_bf16_f32 v130, v50, v51
	v_cvt_pk_bf16_f32 v131, v52, v53
	ds_read_b64_tr_b16 v[102:103], v193 offset:47104
	ds_read_b64_tr_b16 v[104:105], v193 offset:47616
	s_waitcnt lgkmcnt(14)
	v_mfma_f32_32x32x16_bf16 v[2:17], v[150:153], v[118:121], v[2:17]
	v_add_f32_e32 v50, v56, v106
	v_add_f32_e32 v50, v57, v50
	v_add_f32_e32 v50, v58, v50
	v_add_f32_e32 v50, v59, v50
	v_cvt_pk_bf16_f32 v132, v54, v55
	v_cvt_pk_bf16_f32 v133, v56, v57
	ds_read_b64_tr_b16 v[106:107], v193 offset:44032
	ds_read_b64_tr_b16 v[108:109], v193 offset:44544
	s_waitcnt lgkmcnt(14)
	v_mfma_f32_32x32x16_bf16 v[66:81], v[146:149], v[114:117], v[66:81]
	v_add_f32_e32 v50, v60, v50
	v_add_f32_e32 v50, v61, v50
	v_add_f32_e32 v50, v62, v50
	v_add_f32_e32 v50, v63, v50
	v_cvt_pk_bf16_f32 v134, v58, v59
	v_cvt_pk_bf16_f32 v135, v60, v61
	ds_read_b64_tr_b16 v[118:119], v193 offset:48128
	ds_read_b64_tr_b16 v[120:121], v193 offset:48640
	v_mfma_f32_32x32x16_bf16 v[2:17], v[110:113], v[114:117], v[2:17]
	v_add_f32_e32 v50, v64, v50
	v_add_f32_e32 v50, v65, v50
	v_add_f32_e32 v50, 0, v50
	v_cvt_pk_bf16_f32 v136, v62, v63
	v_cvt_pk_bf16_f32 v137, v64, v65
	v_max_f32_e32 v51, v67, v67
	v_max_f32_e32 v52, v66, v66
	v_max_f32_e32 v51, v52, v51
	s_nop 3
	v_max3_f32 v52, v68, v69, v3
	v_max3_f32 v51, v51, v2, v4
	v_max3_f32 v51, v51, v5, v70
	v_max3_f32 v52, v52, v72, v73
	v_max3_f32 v51, v51, v71, v6
	v_max3_f32 v52, v52, v8, v9
	v_max3_f32 v51, v51, v7, v74
	v_max3_f32 v52, v52, v76, v77
	v_max3_f32 v51, v51, v75, v10
	v_max3_f32 v52, v52, v12, v13
	v_max3_f32 v51, v51, v11, v78
	v_max3_f32 v52, v52, v80, v81
	v_max3_f32 v51, v51, v79, v14
	v_max3_f32 v52, v52, v16, v17
	v_add_f32_e32 v110, v170, v50
	v_max3_f32 v50, v51, v15, v52
	v_mov_b32_e32 v51, v50
	s_nop 1
	v_permlane32_swap_b32_e32 v50, v51
	v_max_f32_e32 v51, v51, v51
	v_max_f32_e32 v50, v50, v50
	v_max_f32_e32 v50, v50, v51
	v_cmp_lt_f32_e32 vcc, s15, v50
	s_cbranch_vccnz .LBB0_719
	s_mov_b64 s[4:5], 0

.LBB0_682:
	v_add_u32_e32 v187, s6, v211
	ds_read_b64_tr_b16 v[178:179], v187 offset:24576
	ds_read_b64_tr_b16 v[180:181], v187 offset:25088
	v_mfma_f32_32x32x16_bf16 v[98:113], v[82:85], v[158:161], v[34:49]
	v_add_f32_e32 v86, v66, v67
	v_add_f32_e32 v86, v68, v86
	v_add_f32_e32 v86, v69, v86
	v_add_f32_e32 v86, v70, v86
	v_add_f32_e32 v86, v71, v86
	v_cvt_pk_bf16_f32 v150, v66, v67
	v_cvt_pk_bf16_f32 v151, v68, v69
	ds_read_b64_tr_b16 v[174:175], v187 offset:28672
	ds_read_b64_tr_b16 v[176:177], v187 offset:29184
	v_add_f32_e32 v66, v72, v86
	v_mfma_f32_32x32x16_bf16 v[82:97], v[166:169], v[158:161], v[34:49]
	v_add_f32_e32 v66, v73, v66
	v_add_f32_e32 v66, v74, v66
	v_add_f32_e32 v130, v75, v66
	v_cvt_pk_bf16_f32 v152, v70, v71
	v_cvt_pk_bf16_f32 v153, v72, v73
	ds_read_b64_tr_b16 v[66:67], v187 offset:25600
	ds_read_b64_tr_b16 v[68:69], v187 offset:26112
	v_mfma_f32_32x32x16_bf16 v[98:113], v[170:173], v[154:157], v[98:113]
	v_add_f32_e32 v70, v76, v130
	v_add_f32_e32 v70, v77, v70
	v_add_f32_e32 v70, v78, v70
	v_add_f32_e32 v130, v79, v70
	v_cvt_pk_bf16_f32 v142, v74, v75
	v_cvt_pk_bf16_f32 v143, v76, v77
	ds_read_b64_tr_b16 v[70:71], v187 offset:29696
	ds_read_b64_tr_b16 v[72:73], v187 offset:30208
	v_mfma_f32_32x32x16_bf16 v[82:97], v[162:165], v[154:157], v[82:97]
	v_add_f32_e32 v74, v80, v130
	v_add_f32_e32 v74, v81, v74
	v_add_f32_e32 v74, v50, v74
	v_add_f32_e32 v130, v51, v74
	v_cvt_pk_bf16_f32 v144, v78, v79
	v_cvt_pk_bf16_f32 v145, v80, v81
	ds_read_b64_tr_b16 v[74:75], v187 offset:26624
	ds_read_b64_tr_b16 v[76:77], v187 offset:27136
	v_mfma_f32_32x32x16_bf16 v[98:113], v[126:129], v[146:149], v[98:113]
	v_add_f32_e32 v78, v52, v130
	v_add_f32_e32 v78, v53, v78
	v_add_f32_e32 v78, v54, v78
	v_add_f32_e32 v78, v55, v78
	v_cvt_pk_bf16_f32 v134, v50, v51
	v_cvt_pk_bf16_f32 v135, v52, v53
	ds_read_b64_tr_b16 v[50:51], v187 offset:30720
	ds_read_b64_tr_b16 v[52:53], v187 offset:31232
	v_mfma_f32_32x32x16_bf16 v[82:97], v[122:125], v[146:149], v[82:97]
	v_add_f32_e32 v78, v56, v78
	v_add_f32_e32 v78, v57, v78
	v_add_f32_e32 v78, v58, v78
	v_add_f32_e32 v78, v59, v78
	v_cvt_pk_bf16_f32 v136, v54, v55
	v_cvt_pk_bf16_f32 v137, v56, v57
	ds_read_b64_tr_b16 v[54:55], v187 offset:27648
	ds_read_b64_tr_b16 v[56:57], v187 offset:28160
	v_mfma_f32_32x32x16_bf16 v[98:113], v[118:121], v[138:141], v[98:113]
	v_add_f32_e32 v78, v60, v78
	v_add_f32_e32 v78, v61, v78
	v_add_f32_e32 v78, v62, v78
	v_add_f32_e32 v78, v63, v78
	v_cvt_pk_bf16_f32 v130, v58, v59
	v_cvt_pk_bf16_f32 v131, v60, v61
	ds_read_b64_tr_b16 v[58:59], v187 offset:31744
	ds_read_b64_tr_b16 v[60:61], v187 offset:32256
	v_mfma_f32_32x32x16_bf16 v[82:97], v[114:117], v[138:141], v[82:97]
	v_add_f32_e32 v78, v64, v78
	v_add_f32_e32 v78, v65, v78
	v_cvt_pk_bf16_f32 v132, v62, v63
	v_cvt_pk_bf16_f32 v133, v64, v65
	v_add_f32_e32 v186, v186, v78
	v_max3_f32 v62, v98, v99, v100
	v_max3_f32 v63, v101, v102, v103
	v_max3_f32 v62, v62, v104, v105
	v_max3_f32 v63, v63, v106, v107
	v_max3_f32 v62, v62, v108, v109
	v_max3_f32 v63, v63, v110, v111
	v_max3_f32 v62, v62, v112, v113
	v_max3_f32 v63, v63, v82, v83
	v_max3_f32 v62, v62, v84, v85
	v_max3_f32 v63, v63, v86, v87
	v_max3_f32 v62, v62, v88, v89
	v_max3_f32 v63, v63, v90, v91
	v_max3_f32 v62, v62, v92, v93
	v_max3_f32 v63, v63, v94, v95
	v_max3_f32 v62, v62, v96, v97
	v_max_f32_e32 v62, v62, v63
	v_mov_b32_e32 v63, v62
	s_nop 1
	v_permlane32_swap_b32_e32 v62, v63
	v_max_f32_e32 v62, v62, v63
	v_cmp_lt_f32_e32 vcc, s15, v62
	s_cbranch_vccnz .LBB0_690
	s_mov_b64 s[6:7], 0

.LBB0_685:
	s_add_i32 s6, s23, 0x2000
	s_cmpk_lg_i32 s23, 0x4000
	s_cselect_b32 s24, s6, 0
	v_add_u32_e32 v187, s26, v211
	ds_read_b64_tr_b16 v[118:119], v187 offset:24576
	ds_read_b64_tr_b16 v[120:121], v187 offset:25088
	v_mfma_f32_32x32x16_bf16 v[66:81], v[62:65], v[158:161], v[34:49]
	v_add_f32_e32 v50, v98, v99
	v_add_f32_e32 v50, v100, v50
	v_add_f32_e32 v50, v101, v50
	v_add_f32_e32 v50, v102, v50
	v_add_f32_e32 v50, v103, v50
	v_cvt_pk_bf16_f32 v150, v98, v99
	v_cvt_pk_bf16_f32 v151, v100, v101
	ds_read_b64_tr_b16 v[114:115], v187 offset:28672
	ds_read_b64_tr_b16 v[116:117], v187 offset:29184
	v_add_f32_e32 v50, v104, v50
	v_add_f32_e32 v50, v105, v50
	v_add_f32_e32 v50, v106, v50
	v_add_f32_e32 v130, v107, v50
	v_mfma_f32_32x32x16_bf16 v[50:65], v[174:177], v[158:161], v[34:49]
	v_cvt_pk_bf16_f32 v152, v102, v103
	v_cvt_pk_bf16_f32 v153, v104, v105
	ds_read_b64_tr_b16 v[98:99], v187 offset:25600
	ds_read_b64_tr_b16 v[100:101], v187 offset:26112
	v_mfma_f32_32x32x16_bf16 v[66:81], v[178:181], v[154:157], v[66:81]
	v_add_f32_e32 v102, v108, v130
	v_add_f32_e32 v102, v109, v102
	v_add_f32_e32 v102, v110, v102
	v_add_f32_e32 v130, v111, v102
	v_cvt_pk_bf16_f32 v142, v106, v107
	v_cvt_pk_bf16_f32 v143, v108, v109
	ds_read_b64_tr_b16 v[102:103], v187 offset:29696
	ds_read_b64_tr_b16 v[104:105], v187 offset:30208
	v_mfma_f32_32x32x16_bf16 v[50:65], v[170:173], v[154:157], v[50:65]
	v_add_f32_e32 v106, v112, v130
	v_add_f32_e32 v106, v113, v106
	v_add_f32_e32 v106, v82, v106
	v_add_f32_e32 v130, v83, v106
	v_cvt_pk_bf16_f32 v144, v110, v111
	v_cvt_pk_bf16_f32 v145, v112, v113
	ds_read_b64_tr_b16 v[106:107], v187 offset:26624
	ds_read_b64_tr_b16 v[108:109], v187 offset:27136
	v_mfma_f32_32x32x16_bf16 v[66:81], v[166:169], v[146:149], v[66:81]
	v_add_f32_e32 v110, v84, v130
	v_add_f32_e32 v110, v85, v110
	v_add_f32_e32 v110, v86, v110
	v_add_f32_e32 v130, v87, v110
	v_cvt_pk_bf16_f32 v134, v82, v83
	v_cvt_pk_bf16_f32 v135, v84, v85
	ds_read_b64_tr_b16 v[110:111], v187 offset:30720
	ds_read_b64_tr_b16 v[112:113], v187 offset:31232
	v_mfma_f32_32x32x16_bf16 v[50:65], v[162:165], v[146:149], v[50:65]
	v_add_f32_e32 v82, v88, v130
	v_add_f32_e32 v82, v89, v82
	v_add_f32_e32 v82, v90, v82
	v_add_f32_e32 v82, v91, v82
	v_cvt_pk_bf16_f32 v136, v86, v87
	v_cvt_pk_bf16_f32 v137, v88, v89
	ds_read_b64_tr_b16 v[86:87], v187 offset:27648
	ds_read_b64_tr_b16 v[88:89], v187 offset:28160
	v_mfma_f32_32x32x16_bf16 v[66:81], v[126:129], v[138:141], v[66:81]
	v_add_f32_e32 v82, v92, v82
	v_add_f32_e32 v82, v93, v82
	v_add_f32_e32 v82, v94, v82
	v_add_f32_e32 v82, v95, v82
	v_cvt_pk_bf16_f32 v130, v90, v91
	v_cvt_pk_bf16_f32 v131, v92, v93
	ds_read_b64_tr_b16 v[90:91], v187 offset:31744
	ds_read_b64_tr_b16 v[92:93], v187 offset:32256
	v_mfma_f32_32x32x16_bf16 v[50:65], v[122:125], v[138:141], v[50:65]
	v_add_f32_e32 v82, v96, v82
	v_add_f32_e32 v82, v97, v82
	v_cvt_pk_bf16_f32 v132, v94, v95
	v_cvt_pk_bf16_f32 v133, v96, v97
	v_add_f32_e32 v186, v186, v82
	v_max3_f32 v82, v66, v67, v68
	v_max3_f32 v83, v69, v70, v71
	v_max3_f32 v82, v82, v72, v73
	v_max3_f32 v83, v83, v74, v75
	v_max3_f32 v82, v82, v76, v77
	v_max3_f32 v83, v83, v78, v79
	v_max3_f32 v82, v82, v80, v81
	v_max3_f32 v83, v83, v50, v51
	v_max3_f32 v82, v82, v52, v53
	v_max3_f32 v83, v83, v54, v55
	v_max3_f32 v82, v82, v56, v57
	v_max3_f32 v83, v83, v58, v59
	v_max3_f32 v82, v82, v60, v61
	v_max3_f32 v83, v83, v62, v63
	v_max3_f32 v82, v82, v64, v65
	v_max_f32_e32 v82, v82, v83
	v_mov_b32_e32 v83, v82
	s_nop 1
	v_permlane32_swap_b32_e32 v82, v83
	v_max_f32_e32 v82, v82, v83
	v_cmp_lt_f32_e32 vcc, s15, v82
	s_cbranch_vccnz .LBB0_693
	s_mov_b64 s[6:7], 0

.LBB0_690:
	v_max_f32_e32 v34, v62, v62
	v_max_f32_e32 v62, 0, v34
	v_exp_f32_e64 v63, -v62
	v_add_f32_e32 v205, v205, v62
	v_xor_b32_e32 v34, 0x80000000, v205
	v_mov_b32_e32 v35, v34
	v_mov_b32_e32 v36, v34
	v_mov_b32_e32 v37, v34
	v_mov_b32_e32 v38, v34
	v_mov_b32_e32 v39, v34
	v_mov_b32_e32 v40, v34
	v_mov_b32_e32 v41, v34
	v_mov_b32_e32 v42, v34
	v_mov_b32_e32 v43, v34
	v_mov_b32_e32 v44, v34
	v_mov_b32_e32 v45, v34
	v_mov_b32_e32 v46, v34
	v_mov_b32_e32 v47, v34
	v_mov_b32_e32 v48, v34
	v_mov_b32_e32 v49, v34
	s_and_saveexec_b64 s[8:9], s[40:41]
	ds_write_b32 v204, v63 offset:49152
	s_or_b64 exec, exec, s[8:9]
	v_sub_f32_e32 v113, v113, v62
	v_sub_f32_e32 v112, v112, v62
	v_sub_f32_e32 v111, v111, v62
	v_sub_f32_e32 v110, v110, v62
	v_sub_f32_e32 v109, v109, v62
	v_sub_f32_e32 v108, v108, v62
	v_sub_f32_e32 v107, v107, v62
	v_sub_f32_e32 v106, v106, v62
	v_sub_f32_e32 v105, v105, v62
	v_sub_f32_e32 v104, v104, v62
	v_sub_f32_e32 v103, v103, v62
	v_sub_f32_e32 v102, v102, v62
	v_sub_f32_e32 v101, v101, v62
	v_sub_f32_e32 v100, v100, v62
	v_sub_f32_e32 v99, v99, v62
	v_sub_f32_e32 v98, v98, v62
	v_sub_f32_e32 v97, v97, v62
	v_sub_f32_e32 v96, v96, v62
	v_sub_f32_e32 v95, v95, v62
	v_sub_f32_e32 v94, v94, v62
	v_sub_f32_e32 v93, v93, v62
	v_sub_f32_e32 v92, v92, v62
	v_sub_f32_e32 v91, v91, v62
	v_sub_f32_e32 v90, v90, v62
	v_sub_f32_e32 v89, v89, v62
	v_sub_f32_e32 v88, v88, v62
	v_sub_f32_e32 v87, v87, v62
	v_sub_f32_e32 v86, v86, v62
	v_sub_f32_e32 v85, v85, v62
	v_sub_f32_e32 v84, v84, v62
	v_sub_f32_e32 v83, v83, v62
	v_sub_f32_e32 v82, v82, v62
	v_mul_f32_e32 v186, v186, v63
	s_mov_b64 s[6:7], -1
	s_branch .LBB0_683
.LBB0_693:
	v_max_f32_e32 v34, v82, v82
	v_max_f32_e32 v82, 0, v34
	v_exp_f32_e64 v83, -v82
	v_add_f32_e32 v205, v205, v82
	v_xor_b32_e32 v34, 0x80000000, v205
	v_mov_b32_e32 v35, v34
	v_mov_b32_e32 v36, v34
	v_mov_b32_e32 v37, v34
	v_mov_b32_e32 v38, v34
	v_mov_b32_e32 v39, v34
	v_mov_b32_e32 v40, v34
	v_mov_b32_e32 v41, v34
	v_mov_b32_e32 v42, v34
	v_mov_b32_e32 v43, v34
	v_mov_b32_e32 v44, v34
	v_mov_b32_e32 v45, v34
	v_mov_b32_e32 v46, v34
	v_mov_b32_e32 v47, v34
	v_mov_b32_e32 v48, v34
	v_mov_b32_e32 v49, v34
	s_and_saveexec_b64 s[8:9], s[40:41]
	ds_write_b32 v204, v83 offset:49152
	s_or_b64 exec, exec, s[8:9]
	v_sub_f32_e32 v81, v81, v82
	v_sub_f32_e32 v80, v80, v82
	v_sub_f32_e32 v79, v79, v82
	v_sub_f32_e32 v78, v78, v82
	v_sub_f32_e32 v77, v77, v82
	v_sub_f32_e32 v76, v76, v82
	v_sub_f32_e32 v75, v75, v82
	v_sub_f32_e32 v74, v74, v82
	v_sub_f32_e32 v73, v73, v82
	v_sub_f32_e32 v72, v72, v82
	v_sub_f32_e32 v71, v71, v82
	v_sub_f32_e32 v70, v70, v82
	v_sub_f32_e32 v69, v69, v82
	v_sub_f32_e32 v68, v68, v82
	v_sub_f32_e32 v67, v67, v82
	v_sub_f32_e32 v66, v66, v82
	v_sub_f32_e32 v65, v65, v82
	v_sub_f32_e32 v64, v64, v82
	v_sub_f32_e32 v63, v63, v82
	v_sub_f32_e32 v62, v62, v82
	v_sub_f32_e32 v61, v61, v82
	v_sub_f32_e32 v60, v60, v82
	v_sub_f32_e32 v59, v59, v82
	v_sub_f32_e32 v58, v58, v82
	v_sub_f32_e32 v57, v57, v82
	v_sub_f32_e32 v56, v56, v82
	v_sub_f32_e32 v55, v55, v82
	v_sub_f32_e32 v54, v54, v82
	v_sub_f32_e32 v53, v53, v82
	v_sub_f32_e32 v52, v52, v82
	v_sub_f32_e32 v51, v51, v82
	v_sub_f32_e32 v50, v50, v82
	v_mul_f32_e32 v186, v186, v83
	s_mov_b64 s[6:7], -1
	s_branch .LBB0_686

.LBB0_708:
	v_add_u32_e32 v171, s22, v211
	ds_read_b64_tr_b16 v[98:99], v171 offset:24576
	ds_read_b64_tr_b16 v[100:101], v171 offset:25088
	v_add_f32_e32 v66, v82, v83
	v_add_f32_e32 v66, v84, v66
	v_add_f32_e32 v66, v85, v66
	v_add_f32_e32 v66, v86, v66
	v_add_f32_e32 v106, v87, v66
	s_waitcnt lgkmcnt(9)
	v_mfma_f32_32x32x16_bf16 v[66:81], v[166:169], v[158:161], v[34:49]
	v_cvt_pk_bf16_f32 v150, v82, v83
	v_cvt_pk_bf16_f32 v151, v84, v85
	ds_read_b64_tr_b16 v[82:83], v171 offset:28672
	ds_read_b64_tr_b16 v[84:85], v171 offset:29184
	s_waitcnt lgkmcnt(10)
	v_mfma_f32_32x32x16_bf16 v[34:49], v[162:165], v[158:161], v[34:49]
	v_add_f32_e32 v106, v88, v106
	v_add_f32_e32 v106, v89, v106
	v_add_f32_e32 v106, v90, v106
	v_add_f32_e32 v106, v91, v106
	v_cvt_pk_bf16_f32 v152, v86, v87
	v_cvt_pk_bf16_f32 v153, v88, v89
	ds_read_b64_tr_b16 v[86:87], v171 offset:25600
	ds_read_b64_tr_b16 v[88:89], v171 offset:26112
	s_waitcnt lgkmcnt(11)
	v_mfma_f32_32x32x16_bf16 v[66:81], v[126:129], v[154:157], v[66:81]
	v_add_f32_e32 v106, v92, v106
	v_add_f32_e32 v106, v93, v106
	v_add_f32_e32 v106, v94, v106
	v_add_f32_e32 v106, v95, v106
	v_cvt_pk_bf16_f32 v142, v90, v91
	v_cvt_pk_bf16_f32 v143, v92, v93
	ds_read_b64_tr_b16 v[90:91], v171 offset:29696
	ds_read_b64_tr_b16 v[92:93], v171 offset:30208
	s_waitcnt lgkmcnt(12)
	v_mfma_f32_32x32x16_bf16 v[34:49], v[122:125], v[154:157], v[34:49]
	v_add_f32_e32 v106, v96, v106
	v_add_f32_e32 v106, v97, v106
	v_add_f32_e32 v106, v50, v106
	v_add_f32_e32 v106, v51, v106
	v_cvt_pk_bf16_f32 v144, v94, v95
	v_cvt_pk_bf16_f32 v145, v96, v97
	ds_read_b64_tr_b16 v[94:95], v171 offset:26624
	ds_read_b64_tr_b16 v[96:97], v171 offset:27136
	s_waitcnt lgkmcnt(13)
	v_mfma_f32_32x32x16_bf16 v[66:81], v[102:105], v[146:149], v[66:81]
	v_add_f32_e32 v102, v52, v106
	v_add_f32_e32 v102, v53, v102
	v_add_f32_e32 v102, v54, v102
	v_add_f32_e32 v106, v55, v102
	v_cvt_pk_bf16_f32 v134, v50, v51
	v_cvt_pk_bf16_f32 v135, v52, v53
	ds_read_b64_tr_b16 v[102:103], v171 offset:30720
	ds_read_b64_tr_b16 v[104:105], v171 offset:31232
	s_waitcnt lgkmcnt(14)
	v_mfma_f32_32x32x16_bf16 v[34:49], v[118:121], v[146:149], v[34:49]
	v_add_f32_e32 v50, v56, v106
	v_add_f32_e32 v50, v57, v50
	v_add_f32_e32 v50, v58, v50
	v_add_f32_e32 v50, v59, v50
	v_cvt_pk_bf16_f32 v136, v54, v55
	v_cvt_pk_bf16_f32 v137, v56, v57
	ds_read_b64_tr_b16 v[106:107], v171 offset:27648
	ds_read_b64_tr_b16 v[108:109], v171 offset:28160
	s_waitcnt lgkmcnt(14)
	v_mfma_f32_32x32x16_bf16 v[66:81], v[114:117], v[138:141], v[66:81]
	v_add_f32_e32 v50, v60, v50
	v_add_f32_e32 v50, v61, v50
	v_add_f32_e32 v50, v62, v50
	v_add_f32_e32 v50, v63, v50
	v_cvt_pk_bf16_f32 v130, v58, v59
	v_cvt_pk_bf16_f32 v131, v60, v61
	ds_read_b64_tr_b16 v[114:115], v171 offset:31744
	ds_read_b64_tr_b16 v[116:117], v171 offset:32256
	v_mfma_f32_32x32x16_bf16 v[34:49], v[110:113], v[138:141], v[34:49]
	v_add_f32_e32 v50, v64, v50
	v_add_f32_e32 v50, v65, v50
	v_add_f32_e32 v50, 0, v50
	v_cvt_pk_bf16_f32 v132, v62, v63
	v_cvt_pk_bf16_f32 v133, v64, v65
	v_max_f32_e32 v51, v67, v67
	v_max_f32_e32 v52, v66, v66
	v_max_f32_e32 v51, v52, v51
	s_nop 3
	v_max3_f32 v52, v68, v69, v35
	v_max3_f32 v51, v51, v34, v36
	v_max3_f32 v51, v51, v37, v70
	v_max3_f32 v52, v52, v72, v73
	v_max3_f32 v51, v51, v71, v38
	v_max3_f32 v52, v52, v40, v41
	v_max3_f32 v51, v51, v39, v74
	v_max3_f32 v52, v52, v76, v77
	v_max3_f32 v51, v51, v75, v42
	v_max3_f32 v52, v52, v44, v45
	v_max3_f32 v51, v51, v43, v78
	v_max3_f32 v52, v52, v80, v81
	v_max3_f32 v51, v51, v79, v46
	v_max3_f32 v52, v52, v48, v49
	v_add_f32_e32 v110, v170, v50
	v_max3_f32 v50, v51, v47, v52
	v_mov_b32_e32 v51, v50
	s_nop 1
	v_permlane32_swap_b32_e32 v50, v51
	v_max_f32_e32 v51, v51, v51
	v_max_f32_e32 v50, v50, v50
	v_max_f32_e32 v50, v50, v51
	v_cmp_lt_f32_e32 vcc, s15, v50
	s_cbranch_vccnz .LBB0_734
	s_mov_b64 s[6:7], 0

.LBB0_713:
	v_max_f32_e32 v2, v22, v22
	v_max_f32_e32 v22, 0, v2
	v_exp_f32_e64 v23, -v22
	v_add_f32_e32 v191, v191, v22
	v_xor_b32_e32 v2, 0x80000000, v191
	v_mov_b32_e32 v3, v2
	v_mov_b32_e32 v4, v2
	v_mov_b32_e32 v5, v2
	v_mov_b32_e32 v6, v2
	v_mov_b32_e32 v7, v2
	v_mov_b32_e32 v8, v2
	v_mov_b32_e32 v9, v2
	v_mov_b32_e32 v10, v2
	v_mov_b32_e32 v11, v2
	v_mov_b32_e32 v12, v2
	v_mov_b32_e32 v13, v2
	v_mov_b32_e32 v14, v2
	v_mov_b32_e32 v15, v2
	v_mov_b32_e32 v16, v2
	v_mov_b32_e32 v17, v2
	s_and_saveexec_b64 s[6:7], s[40:41]
	ds_write_b32 v190, v23 offset:49152
	s_or_b64 exec, exec, s[6:7]
	v_sub_f32_e32 v113, v113, v22
	v_sub_f32_e32 v112, v112, v22
	v_sub_f32_e32 v111, v111, v22
	v_sub_f32_e32 v110, v110, v22
	v_sub_f32_e32 v109, v109, v22
	v_sub_f32_e32 v108, v108, v22
	v_sub_f32_e32 v107, v107, v22
	v_sub_f32_e32 v106, v106, v22
	v_sub_f32_e32 v105, v105, v22
	v_sub_f32_e32 v104, v104, v22
	v_sub_f32_e32 v103, v103, v22
	v_sub_f32_e32 v102, v102, v22
	v_sub_f32_e32 v101, v101, v22
	v_sub_f32_e32 v100, v100, v22
	v_sub_f32_e32 v99, v99, v22
	v_sub_f32_e32 v98, v98, v22
	v_sub_f32_e32 v81, v81, v22
	v_sub_f32_e32 v80, v80, v22
	v_sub_f32_e32 v79, v79, v22
	v_sub_f32_e32 v78, v78, v22
	v_sub_f32_e32 v77, v77, v22
	v_sub_f32_e32 v76, v76, v22
	v_sub_f32_e32 v75, v75, v22
	v_sub_f32_e32 v74, v74, v22
	v_sub_f32_e32 v73, v73, v22
	v_sub_f32_e32 v72, v72, v22
	v_sub_f32_e32 v71, v71, v22
	v_sub_f32_e32 v70, v70, v22
	v_sub_f32_e32 v69, v69, v22
	v_sub_f32_e32 v68, v68, v22
	v_sub_f32_e32 v67, v67, v22
	v_sub_f32_e32 v66, v66, v22
	v_mul_f32_e32 v195, v195, v23
	s_mov_b64 s[4:5], -1
	s_branch .LBB0_669

.LBB0_719:
	v_max_f32_e32 v50, v50, v50
	v_max_f32_e32 v111, 0, v50
	v_add_f32_e32 v50, v191, v111
	v_xor_b32_e32 v50, 0x80000000, v50
	v_mov_b32_e32 v51, v50
	v_mov_b32_e32 v52, v50
	v_mov_b32_e32 v53, v50
	v_mov_b32_e32 v54, v50
	v_mov_b32_e32 v55, v50
	v_mov_b32_e32 v56, v50
	v_mov_b32_e32 v57, v50
	v_mov_b32_e32 v58, v50
	v_mov_b32_e32 v59, v50
	v_mov_b32_e32 v60, v50
	v_mov_b32_e32 v61, v50
	v_mov_b32_e32 v62, v50
	v_mov_b32_e32 v63, v50
	v_mov_b32_e32 v64, v50
	v_mov_b32_e32 v65, v50
	s_nop 0
	v_exp_f32_e64 v50, -v111
	s_and_saveexec_b64 s[6:7], s[40:41]
	ds_write_b32 v190, v50 offset:49152
	s_or_b64 exec, exec, s[6:7]
	v_sub_f32_e32 v81, v81, v111
	v_sub_f32_e32 v80, v80, v111
	v_sub_f32_e32 v79, v79, v111
	v_sub_f32_e32 v78, v78, v111
	v_sub_f32_e32 v77, v77, v111
	v_sub_f32_e32 v76, v76, v111
	v_sub_f32_e32 v75, v75, v111
	v_sub_f32_e32 v74, v74, v111
	v_sub_f32_e32 v73, v73, v111
	v_sub_f32_e32 v72, v72, v111
	v_sub_f32_e32 v71, v71, v111
	v_sub_f32_e32 v70, v70, v111
	v_sub_f32_e32 v69, v69, v111
	v_sub_f32_e32 v68, v68, v111
	v_sub_f32_e32 v67, v67, v111
	v_sub_f32_e32 v66, v66, v111
	v_sub_f32_e32 v17, v17, v111
	v_sub_f32_e32 v16, v16, v111
	v_sub_f32_e32 v15, v15, v111
	v_sub_f32_e32 v14, v14, v111
	v_sub_f32_e32 v13, v13, v111
	v_sub_f32_e32 v12, v12, v111
	v_sub_f32_e32 v11, v11, v111
	v_sub_f32_e32 v10, v10, v111
	v_sub_f32_e32 v9, v9, v111
	v_sub_f32_e32 v8, v8, v111
	v_sub_f32_e32 v7, v7, v111
	v_sub_f32_e32 v6, v6, v111
	v_sub_f32_e32 v5, v5, v111
	v_sub_f32_e32 v4, v4, v111
	v_sub_f32_e32 v3, v3, v111
	v_sub_f32_e32 v2, v2, v111
	v_mul_f32_e32 v110, v110, v50
	s_mov_b64 s[4:5], -1
	s_branch .LBB0_675

.LBB0_734:
	v_max_f32_e32 v50, v50, v50
	v_max_f32_e32 v111, 0, v50
	v_add_f32_e32 v50, v205, v111
	v_xor_b32_e32 v50, 0x80000000, v50
	v_mov_b32_e32 v51, v50
	v_mov_b32_e32 v52, v50
	v_mov_b32_e32 v53, v50
	v_mov_b32_e32 v54, v50
	v_mov_b32_e32 v55, v50
	v_mov_b32_e32 v56, v50
	v_mov_b32_e32 v57, v50
	v_mov_b32_e32 v58, v50
	v_mov_b32_e32 v59, v50
	v_mov_b32_e32 v60, v50
	v_mov_b32_e32 v61, v50
	v_mov_b32_e32 v62, v50
	v_mov_b32_e32 v63, v50
	v_mov_b32_e32 v64, v50
	v_mov_b32_e32 v65, v50
	s_nop 0
	v_exp_f32_e64 v50, -v111
	s_and_saveexec_b64 s[8:9], s[40:41]
	ds_write_b32 v204, v50 offset:49152
	s_or_b64 exec, exec, s[8:9]
	v_sub_f32_e32 v81, v81, v111
	v_sub_f32_e32 v80, v80, v111
	v_sub_f32_e32 v79, v79, v111
	v_sub_f32_e32 v78, v78, v111
	v_sub_f32_e32 v77, v77, v111
	v_sub_f32_e32 v76, v76, v111
	v_sub_f32_e32 v75, v75, v111
	v_sub_f32_e32 v74, v74, v111
	v_sub_f32_e32 v73, v73, v111
	v_sub_f32_e32 v72, v72, v111
	v_sub_f32_e32 v71, v71, v111
	v_sub_f32_e32 v70, v70, v111
	v_sub_f32_e32 v69, v69, v111
	v_sub_f32_e32 v68, v68, v111
	v_sub_f32_e32 v67, v67, v111
	v_sub_f32_e32 v66, v66, v111
	v_sub_f32_e32 v49, v49, v111
	v_sub_f32_e32 v48, v48, v111
	v_sub_f32_e32 v47, v47, v111
	v_sub_f32_e32 v46, v46, v111
	v_sub_f32_e32 v45, v45, v111
	v_sub_f32_e32 v44, v44, v111
	v_sub_f32_e32 v43, v43, v111
	v_sub_f32_e32 v42, v42, v111
	v_sub_f32_e32 v41, v41, v111
	v_sub_f32_e32 v40, v40, v111
	v_sub_f32_e32 v39, v39, v111
	v_sub_f32_e32 v38, v38, v111
	v_sub_f32_e32 v37, v37, v111
	v_sub_f32_e32 v36, v36, v111
	v_sub_f32_e32 v35, v35, v111
	v_sub_f32_e32 v34, v34, v111
	v_mul_f32_e32 v110, v110, v50
	s_mov_b64 s[6:7], -1
	s_branch .LBB0_709
